# also the first slab's input LayerNorm hand-written (8 rows per wave, all workgroups) and an even 8-rows-per-wave final LayerNorm for the last slab; loop back edge through mid-kernel trampolines
# baseline (speedup 1.0000x reference)
.LBB0_176:
	s_sub_i32 s4, s86, s10
	v_ashrrev_i32_e32 v1, 6, v2
	v_lshl_add_u32 v94, s4, 3, v1
	v_cmp_gt_i32_e32 vcc, s31, v94
	s_and_saveexec_b64 s[4:5], vcc
	s_cbranch_execz .LBB0_187
	s_cmp_eq_u32 s92, 0
	s_movk_i32 s6, 0xa0
	s_cselect_b32 s6, s6, 0xa8
	s_brev_b32 s7, 16
	s_cselect_b32 s11, s7, 0x14e0000
	s_add_u32 s6, s8, s6
	s_addc_u32 s7, s9, 0
	s_load_dwordx2 s[6:7], s[6:7], 0x0
	v_ashrrev_i32_e32 v1, 31, v0
	s_load_dwordx2 s[20:21], s[8:9], 0xa8
	v_lshlrev_b64 v[0:1], 17, v[0:1]
	s_load_dwordx4 s[40:43], s[8:9], 0x10
	s_waitcnt lgkmcnt(0)
	s_add_u32 s6, s6, s11
	s_addc_u32 s7, s7, 0
	v_lshl_add_u64 v[0:1], s[20:21], 0, v[0:1]
	s_mov_b64 s[20:21], 0x1480000
	s_sub_i32 s8, s56, s10
	v_lshl_add_u64 v[0:1], v[0:1], 0, s[20:21]
	s_lshl_b32 s20, s8, 3
	s_lshl_b32 s8, s10, 6
	v_readlane_b32 s9, v254, 27
	s_sub_i32 s21, s9, s8
	s_lshl_b32 s8, s10, 5
	v_readlane_b32 s10, v254, 25
	v_and_b32_e32 v68, 63, v2
	v_lshlrev_b32_e32 v70, 3, v94
	s_waitcnt vmcnt(0)
	v_lshlrev_b32_e32 v72, 2, v94
	s_sub_i32 s34, s10, s8
	s_mov_b64 s[8:9], 0
	v_readlane_b32 s11, v254, 26
	s_cmpk_lg_u32 s56, 0x100
	s_cbranch_scc1 .Lln_generic
	v_readfirstlane_b32 s38, v0
	v_readfirstlane_b32 s39, v1
	v_mbcnt_lo_u32_b32 v0, -1, 0
	v_mbcnt_hi_u32_b32 v0, -1, v0
	v_lshlrev_b32_e32 v1, 4, v0
	v_lshlrev_b32_e32 v5, 3, v0
	v_mov_b32_e32 v2, 0x3a800000
	v_mov_b32_e32 v4, 0x3727c5ac
	s_lshr_b32 s10, s29, 6
	s_cmp_lt_i32 s92, 0
	s_cselect_b32 s11, 0, 64
	s_sub_u32 s11, s86, s11
	s_lshl_b32 s11, s11, 3
	s_add_i32 s10, s10, s11
	s_lshl_b32 s11, s10, 12
	s_add_u32 s4, s0, s11
	s_addc_u32 s5, s1, 0
	s_lshl_b32 s11, s10, 11
	s_add_u32 s8, s6, s11
	s_addc_u32 s9, s7, 0
	s_lshl_b32 s11, s10, 3
	s_add_u32 s38, s38, s11
	s_addc_u32 s39, s39, 0
	s_cmp_lt_i32 s92, 0
	s_cbranch_scc0 .Lln_late
	global_load_dwordx4 v[40:43], v1, s[4:5]
	global_load_dwordx4 v[44:47], v1, s[4:5] offset:1024
	global_load_dwordx4 v[48:51], v1, s[4:5] offset:2048
	global_load_dwordx4 v[52:55], v1, s[4:5] offset:3072
	global_load_dwordx4 v[8:11], v1, s[40:41]
	global_load_dwordx4 v[12:15], v1, s[40:41] offset:1024
	global_load_dwordx4 v[16:19], v1, s[40:41] offset:2048
	global_load_dwordx4 v[20:23], v1, s[40:41] offset:3072
	global_load_dwordx4 v[24:27], v1, s[42:43]
	global_load_dwordx4 v[28:31], v1, s[42:43] offset:1024
	global_load_dwordx4 v[32:35], v1, s[42:43] offset:2048
	global_load_dwordx4 v[36:39], v1, s[42:43] offset:3072
	v_add_u32_e32 v170, 0x800000, v1
	global_load_dwordx4 v[56:59], v170, s[4:5]
	global_load_dwordx4 v[60:63], v170, s[4:5] offset:1024
	global_load_dwordx4 v[64:67], v170, s[4:5] offset:2048
	global_load_dwordx4 v[68:71], v170, s[4:5] offset:3072
	v_add_u32_e32 v170, 0x1000000, v1
	global_load_dwordx4 v[72:75], v170, s[4:5]
	global_load_dwordx4 v[76:79], v170, s[4:5] offset:1024
	global_load_dwordx4 v[80:83], v170, s[4:5] offset:2048
	global_load_dwordx4 v[84:87], v170, s[4:5] offset:3072
	v_add_u32_e32 v170, 0x1800000, v1
	global_load_dwordx4 v[88:91], v170, s[4:5]
	global_load_dwordx4 v[92:95], v170, s[4:5] offset:1024
	global_load_dwordx4 v[96:99], v170, s[4:5] offset:2048
	global_load_dwordx4 v[100:103], v170, s[4:5] offset:3072
	v_add_u32_e32 v170, 0x2000000, v1
	global_load_dwordx4 v[104:107], v170, s[4:5]
	global_load_dwordx4 v[108:111], v170, s[4:5] offset:1024
	global_load_dwordx4 v[112:115], v170, s[4:5] offset:2048
	global_load_dwordx4 v[116:119], v170, s[4:5] offset:3072
	v_add_u32_e32 v170, 0x2800000, v1
	global_load_dwordx4 v[120:123], v170, s[4:5]
	global_load_dwordx4 v[124:127], v170, s[4:5] offset:1024
	global_load_dwordx4 v[128:131], v170, s[4:5] offset:2048
	global_load_dwordx4 v[132:135], v170, s[4:5] offset:3072
	v_add_u32_e32 v170, 0x3000000, v1
	global_load_dwordx4 v[136:139], v170, s[4:5]
	global_load_dwordx4 v[140:143], v170, s[4:5] offset:1024
	global_load_dwordx4 v[144:147], v170, s[4:5] offset:2048
	global_load_dwordx4 v[148:151], v170, s[4:5] offset:3072
	v_add_u32_e32 v170, 0x3800000, v1
	global_load_dwordx4 v[152:155], v170, s[4:5]
	global_load_dwordx4 v[156:159], v170, s[4:5] offset:1024
	global_load_dwordx4 v[160:163], v170, s[4:5] offset:2048
	global_load_dwordx4 v[164:167], v170, s[4:5] offset:3072
	s_waitcnt vmcnt(36)
	v_add_f32_e32 v180, v40, v41
	v_add_f32_e32 v181, v44, v45
	v_add_f32_e32 v182, v48, v49
	v_add_f32_e32 v183, v52, v53
	v_add_f32_e32 v180, v180, v42
	v_add_f32_e32 v181, v181, v46
	v_add_f32_e32 v182, v182, v50
	v_add_f32_e32 v183, v183, v54
	v_add_f32_e32 v180, v180, v43
	v_add_f32_e32 v181, v181, v47
	v_add_f32_e32 v182, v182, v51
	v_add_f32_e32 v183, v183, v55
	v_add_f32_e32 v180, v180, v181
	v_add_f32_e32 v182, v182, v183
	v_add_f32_e32 v180, v180, v182
	s_nop 1
	v_add_f32_dpp v180, v180, v180 quad_perm:[1,0,3,2] row_mask:0xf bank_mask:0xf
	s_nop 1
	v_add_f32_dpp v180, v180, v180 quad_perm:[2,3,0,1] row_mask:0xf bank_mask:0xf
	s_nop 1
	v_add_f32_dpp v180, v180, v180 row_half_mirror row_mask:0xf bank_mask:0xf
	s_nop 1
	v_add_f32_dpp v180, v180, v180 row_mirror row_mask:0xf bank_mask:0xf
	s_nop 1
	v_add_f32_dpp v180, v180, v180 row_bcast:15 row_mask:0xa bank_mask:0xf
	s_nop 1
	v_add_f32_dpp v180, v180, v180 row_bcast:31 row_mask:0xc bank_mask:0xf
	s_nop 0
	v_readlane_b32 s20, v180, 63
	s_nop 1
	v_mul_f32_e32 v184, s20, v2
	v_sub_f32_e32 v40, v40, v184
	v_sub_f32_e32 v41, v41, v184
	v_sub_f32_e32 v42, v42, v184
	v_sub_f32_e32 v43, v43, v184
	v_sub_f32_e32 v44, v44, v184
	v_sub_f32_e32 v45, v45, v184
	v_sub_f32_e32 v46, v46, v184
	v_sub_f32_e32 v47, v47, v184
	v_sub_f32_e32 v48, v48, v184
	v_sub_f32_e32 v49, v49, v184
	v_sub_f32_e32 v50, v50, v184
	v_sub_f32_e32 v51, v51, v184
	v_sub_f32_e32 v52, v52, v184
	v_sub_f32_e32 v53, v53, v184
	v_sub_f32_e32 v54, v54, v184
	v_sub_f32_e32 v55, v55, v184
	v_mul_f32_e32 v180, v40, v40
	v_mul_f32_e32 v181, v44, v44
	v_mul_f32_e32 v182, v48, v48
	v_mul_f32_e32 v183, v52, v52
	v_fmac_f32_e32 v180, v41, v41
	v_fmac_f32_e32 v181, v45, v45
	v_fmac_f32_e32 v182, v49, v49
	v_fmac_f32_e32 v183, v53, v53
	v_fmac_f32_e32 v180, v42, v42
	v_fmac_f32_e32 v181, v46, v46
	v_fmac_f32_e32 v182, v50, v50
	v_fmac_f32_e32 v183, v54, v54
	v_fmac_f32_e32 v180, v43, v43
	v_fmac_f32_e32 v181, v47, v47
	v_fmac_f32_e32 v182, v51, v51
	v_fmac_f32_e32 v183, v55, v55
	v_add_f32_e32 v180, v180, v181
	v_add_f32_e32 v182, v182, v183
	v_add_f32_e32 v180, v180, v182
	s_nop 1
	v_add_f32_dpp v180, v180, v180 quad_perm:[1,0,3,2] row_mask:0xf bank_mask:0xf
	s_nop 1
	v_add_f32_dpp v180, v180, v180 quad_perm:[2,3,0,1] row_mask:0xf bank_mask:0xf
	s_nop 1
	v_add_f32_dpp v180, v180, v180 row_half_mirror row_mask:0xf bank_mask:0xf
	s_nop 1
	v_add_f32_dpp v180, v180, v180 row_mirror row_mask:0xf bank_mask:0xf
	s_nop 1
	v_add_f32_dpp v180, v180, v180 row_bcast:15 row_mask:0xa bank_mask:0xf
	s_nop 1
	v_add_f32_dpp v180, v180, v180 row_bcast:31 row_mask:0xc bank_mask:0xf
	s_nop 0
	v_readlane_b32 s20, v180, 63
	s_nop 1
	v_mov_b32_e32 v185, s20
	v_fma_f32 v185, v185, v2, v4
	v_rsq_f32_e32 v185, v185
	s_nop 0
	v_mul_f32_e32 v40, v40, v185
	v_mul_f32_e32 v41, v41, v185
	v_mul_f32_e32 v42, v42, v185
	v_mul_f32_e32 v43, v43, v185
	v_mul_f32_e32 v44, v44, v185
	v_mul_f32_e32 v45, v45, v185
	v_mul_f32_e32 v46, v46, v185
	v_mul_f32_e32 v47, v47, v185
	v_mul_f32_e32 v48, v48, v185
	v_mul_f32_e32 v49, v49, v185
	v_mul_f32_e32 v50, v50, v185
	v_mul_f32_e32 v51, v51, v185
	v_mul_f32_e32 v52, v52, v185
	v_mul_f32_e32 v53, v53, v185
	v_mul_f32_e32 v54, v54, v185
	v_mul_f32_e32 v55, v55, v185
	s_waitcnt vmcnt(28)
	v_fma_f32 v40, v40, v8, v24
	v_fma_f32 v41, v41, v9, v25
	v_fma_f32 v42, v42, v10, v26
	v_fma_f32 v43, v43, v11, v27
	v_fma_f32 v44, v44, v12, v28
	v_fma_f32 v45, v45, v13, v29
	v_fma_f32 v46, v46, v14, v30
	v_fma_f32 v47, v47, v15, v31
	v_fma_f32 v48, v48, v16, v32
	v_fma_f32 v49, v49, v17, v33
	v_fma_f32 v50, v50, v18, v34
	v_fma_f32 v51, v51, v19, v35
	v_fma_f32 v52, v52, v20, v36
	v_fma_f32 v53, v53, v21, v37
	v_fma_f32 v54, v54, v22, v38
	v_fma_f32 v55, v55, v23, v39
	v_cvt_pk_bf16_f32 v40, v40, v41
	v_cvt_pk_bf16_f32 v41, v42, v43
	v_cvt_pk_bf16_f32 v44, v44, v45
	v_cvt_pk_bf16_f32 v45, v46, v47
	v_cvt_pk_bf16_f32 v48, v48, v49
	v_cvt_pk_bf16_f32 v49, v50, v51
	v_cvt_pk_bf16_f32 v52, v52, v53
	v_cvt_pk_bf16_f32 v53, v54, v55
	global_store_dwordx2 v5, v[40:41], s[8:9]
	global_store_dwordx2 v5, v[44:45], s[8:9] offset:512
	global_store_dwordx2 v5, v[48:49], s[8:9] offset:1024
	global_store_dwordx2 v5, v[52:53], s[8:9] offset:1536
	v_mov_b32_e32 v172, 0x0
	s_mov_b64 exec, 1
	global_store_dwordx2 v172, v[184:185], s[38:39]
	s_mov_b64 exec, -1
	s_waitcnt vmcnt(29)
	v_add_f32_e32 v180, v56, v57
	v_add_f32_e32 v181, v60, v61
	v_add_f32_e32 v182, v64, v65
	v_add_f32_e32 v183, v68, v69
	v_add_f32_e32 v180, v180, v58
	v_add_f32_e32 v181, v181, v62
	v_add_f32_e32 v182, v182, v66
	v_add_f32_e32 v183, v183, v70
	v_add_f32_e32 v180, v180, v59
	v_add_f32_e32 v181, v181, v63
	v_add_f32_e32 v182, v182, v67
	v_add_f32_e32 v183, v183, v71
	v_add_f32_e32 v180, v180, v181
	v_add_f32_e32 v182, v182, v183
	v_add_f32_e32 v180, v180, v182
	s_nop 1
	v_add_f32_dpp v180, v180, v180 quad_perm:[1,0,3,2] row_mask:0xf bank_mask:0xf
	s_nop 1
	v_add_f32_dpp v180, v180, v180 quad_perm:[2,3,0,1] row_mask:0xf bank_mask:0xf
	s_nop 1
	v_add_f32_dpp v180, v180, v180 row_half_mirror row_mask:0xf bank_mask:0xf
	s_nop 1
	v_add_f32_dpp v180, v180, v180 row_mirror row_mask:0xf bank_mask:0xf
	s_nop 1
	v_add_f32_dpp v180, v180, v180 row_bcast:15 row_mask:0xa bank_mask:0xf
	s_nop 1
	v_add_f32_dpp v180, v180, v180 row_bcast:31 row_mask:0xc bank_mask:0xf
	s_nop 0
	v_readlane_b32 s20, v180, 63
	s_nop 1
	v_mul_f32_e32 v184, s20, v2
	v_sub_f32_e32 v56, v56, v184
	v_sub_f32_e32 v57, v57, v184
	v_sub_f32_e32 v58, v58, v184
	v_sub_f32_e32 v59, v59, v184
	v_sub_f32_e32 v60, v60, v184
	v_sub_f32_e32 v61, v61, v184
	v_sub_f32_e32 v62, v62, v184
	v_sub_f32_e32 v63, v63, v184
	v_sub_f32_e32 v64, v64, v184
	v_sub_f32_e32 v65, v65, v184
	v_sub_f32_e32 v66, v66, v184
	v_sub_f32_e32 v67, v67, v184
	v_sub_f32_e32 v68, v68, v184
	v_sub_f32_e32 v69, v69, v184
	v_sub_f32_e32 v70, v70, v184
	v_sub_f32_e32 v71, v71, v184
	v_mul_f32_e32 v180, v56, v56
	v_mul_f32_e32 v181, v60, v60
	v_mul_f32_e32 v182, v64, v64
	v_mul_f32_e32 v183, v68, v68
	v_fmac_f32_e32 v180, v57, v57
	v_fmac_f32_e32 v181, v61, v61
	v_fmac_f32_e32 v182, v65, v65
	v_fmac_f32_e32 v183, v69, v69
	v_fmac_f32_e32 v180, v58, v58
	v_fmac_f32_e32 v181, v62, v62
	v_fmac_f32_e32 v182, v66, v66
	v_fmac_f32_e32 v183, v70, v70
	v_fmac_f32_e32 v180, v59, v59
	v_fmac_f32_e32 v181, v63, v63
	v_fmac_f32_e32 v182, v67, v67
	v_fmac_f32_e32 v183, v71, v71
	v_add_f32_e32 v180, v180, v181
	v_add_f32_e32 v182, v182, v183
	v_add_f32_e32 v180, v180, v182
	s_nop 1
	v_add_f32_dpp v180, v180, v180 quad_perm:[1,0,3,2] row_mask:0xf bank_mask:0xf
	s_nop 1
	v_add_f32_dpp v180, v180, v180 quad_perm:[2,3,0,1] row_mask:0xf bank_mask:0xf
	s_nop 1
	v_add_f32_dpp v180, v180, v180 row_half_mirror row_mask:0xf bank_mask:0xf
	s_nop 1
	v_add_f32_dpp v180, v180, v180 row_mirror row_mask:0xf bank_mask:0xf
	s_nop 1
	v_add_f32_dpp v180, v180, v180 row_bcast:15 row_mask:0xa bank_mask:0xf
	s_nop 1
	v_add_f32_dpp v180, v180, v180 row_bcast:31 row_mask:0xc bank_mask:0xf
	s_nop 0
	v_readlane_b32 s20, v180, 63
	s_nop 1
	v_mov_b32_e32 v185, s20
	v_fma_f32 v185, v185, v2, v4
	v_rsq_f32_e32 v185, v185
	s_nop 0
	v_mul_f32_e32 v56, v56, v185
	v_mul_f32_e32 v57, v57, v185
	v_mul_f32_e32 v58, v58, v185
	v_mul_f32_e32 v59, v59, v185
	v_mul_f32_e32 v60, v60, v185
	v_mul_f32_e32 v61, v61, v185
	v_mul_f32_e32 v62, v62, v185
	v_mul_f32_e32 v63, v63, v185
	v_mul_f32_e32 v64, v64, v185
	v_mul_f32_e32 v65, v65, v185
	v_mul_f32_e32 v66, v66, v185
	v_mul_f32_e32 v67, v67, v185
	v_mul_f32_e32 v68, v68, v185
	v_mul_f32_e32 v69, v69, v185
	v_mul_f32_e32 v70, v70, v185
	v_mul_f32_e32 v71, v71, v185
	v_fma_f32 v56, v56, v8, v24
	v_fma_f32 v57, v57, v9, v25
	v_fma_f32 v58, v58, v10, v26
	v_fma_f32 v59, v59, v11, v27
	v_fma_f32 v60, v60, v12, v28
	v_fma_f32 v61, v61, v13, v29
	v_fma_f32 v62, v62, v14, v30
	v_fma_f32 v63, v63, v15, v31
	v_fma_f32 v64, v64, v16, v32
	v_fma_f32 v65, v65, v17, v33
	v_fma_f32 v66, v66, v18, v34
	v_fma_f32 v67, v67, v19, v35
	v_fma_f32 v68, v68, v20, v36
	v_fma_f32 v69, v69, v21, v37
	v_fma_f32 v70, v70, v22, v38
	v_fma_f32 v71, v71, v23, v39
	v_cvt_pk_bf16_f32 v56, v56, v57
	v_cvt_pk_bf16_f32 v57, v58, v59
	v_cvt_pk_bf16_f32 v60, v60, v61
	v_cvt_pk_bf16_f32 v61, v62, v63
	v_cvt_pk_bf16_f32 v64, v64, v65
	v_cvt_pk_bf16_f32 v65, v66, v67
	v_cvt_pk_bf16_f32 v68, v68, v69
	v_cvt_pk_bf16_f32 v69, v70, v71
	v_add_u32_e32 v171, 0x400000, v5
	global_store_dwordx2 v171, v[56:57], s[8:9]
	global_store_dwordx2 v171, v[60:61], s[8:9] offset:512
	global_store_dwordx2 v171, v[64:65], s[8:9] offset:1024
	global_store_dwordx2 v171, v[68:69], s[8:9] offset:1536
	v_mov_b32_e32 v172, 0x4000
	s_mov_b64 exec, 1
	global_store_dwordx2 v172, v[184:185], s[38:39]
	s_mov_b64 exec, -1
	s_waitcnt vmcnt(30)
	v_add_f32_e32 v180, v72, v73
	v_add_f32_e32 v181, v76, v77
	v_add_f32_e32 v182, v80, v81
	v_add_f32_e32 v183, v84, v85
	v_add_f32_e32 v180, v180, v74
	v_add_f32_e32 v181, v181, v78
	v_add_f32_e32 v182, v182, v82
	v_add_f32_e32 v183, v183, v86
	v_add_f32_e32 v180, v180, v75
	v_add_f32_e32 v181, v181, v79
	v_add_f32_e32 v182, v182, v83
	v_add_f32_e32 v183, v183, v87
	v_add_f32_e32 v180, v180, v181
	v_add_f32_e32 v182, v182, v183
	v_add_f32_e32 v180, v180, v182
	s_nop 1
	v_add_f32_dpp v180, v180, v180 quad_perm:[1,0,3,2] row_mask:0xf bank_mask:0xf
	s_nop 1
	v_add_f32_dpp v180, v180, v180 quad_perm:[2,3,0,1] row_mask:0xf bank_mask:0xf
	s_nop 1
	v_add_f32_dpp v180, v180, v180 row_half_mirror row_mask:0xf bank_mask:0xf
	s_nop 1
	v_add_f32_dpp v180, v180, v180 row_mirror row_mask:0xf bank_mask:0xf
	s_nop 1
	v_add_f32_dpp v180, v180, v180 row_bcast:15 row_mask:0xa bank_mask:0xf
	s_nop 1
	v_add_f32_dpp v180, v180, v180 row_bcast:31 row_mask:0xc bank_mask:0xf
	s_nop 0
	v_readlane_b32 s20, v180, 63
	s_nop 1
	v_mul_f32_e32 v184, s20, v2
	v_sub_f32_e32 v72, v72, v184
	v_sub_f32_e32 v73, v73, v184
	v_sub_f32_e32 v74, v74, v184
	v_sub_f32_e32 v75, v75, v184
	v_sub_f32_e32 v76, v76, v184
	v_sub_f32_e32 v77, v77, v184
	v_sub_f32_e32 v78, v78, v184
	v_sub_f32_e32 v79, v79, v184
	v_sub_f32_e32 v80, v80, v184
	v_sub_f32_e32 v81, v81, v184
	v_sub_f32_e32 v82, v82, v184
	v_sub_f32_e32 v83, v83, v184
	v_sub_f32_e32 v84, v84, v184
	v_sub_f32_e32 v85, v85, v184
	v_sub_f32_e32 v86, v86, v184
	v_sub_f32_e32 v87, v87, v184
	v_mul_f32_e32 v180, v72, v72
	v_mul_f32_e32 v181, v76, v76
	v_mul_f32_e32 v182, v80, v80
	v_mul_f32_e32 v183, v84, v84
	v_fmac_f32_e32 v180, v73, v73
	v_fmac_f32_e32 v181, v77, v77
	v_fmac_f32_e32 v182, v81, v81
	v_fmac_f32_e32 v183, v85, v85
	v_fmac_f32_e32 v180, v74, v74
	v_fmac_f32_e32 v181, v78, v78
	v_fmac_f32_e32 v182, v82, v82
	v_fmac_f32_e32 v183, v86, v86
	v_fmac_f32_e32 v180, v75, v75
	v_fmac_f32_e32 v181, v79, v79
	v_fmac_f32_e32 v182, v83, v83
	v_fmac_f32_e32 v183, v87, v87
	v_add_f32_e32 v180, v180, v181
	v_add_f32_e32 v182, v182, v183
	v_add_f32_e32 v180, v180, v182
	s_nop 1
	v_add_f32_dpp v180, v180, v180 quad_perm:[1,0,3,2] row_mask:0xf bank_mask:0xf
	s_nop 1
	v_add_f32_dpp v180, v180, v180 quad_perm:[2,3,0,1] row_mask:0xf bank_mask:0xf
	s_nop 1
	v_add_f32_dpp v180, v180, v180 row_half_mirror row_mask:0xf bank_mask:0xf
	s_nop 1
	v_add_f32_dpp v180, v180, v180 row_mirror row_mask:0xf bank_mask:0xf
	s_nop 1
	v_add_f32_dpp v180, v180, v180 row_bcast:15 row_mask:0xa bank_mask:0xf
	s_nop 1
	v_add_f32_dpp v180, v180, v180 row_bcast:31 row_mask:0xc bank_mask:0xf
	s_nop 0
	v_readlane_b32 s20, v180, 63
	s_nop 1
	v_mov_b32_e32 v185, s20
	v_fma_f32 v185, v185, v2, v4
	v_rsq_f32_e32 v185, v185
	s_nop 0
	v_mul_f32_e32 v72, v72, v185
	v_mul_f32_e32 v73, v73, v185
	v_mul_f32_e32 v74, v74, v185
	v_mul_f32_e32 v75, v75, v185
	v_mul_f32_e32 v76, v76, v185
	v_mul_f32_e32 v77, v77, v185
	v_mul_f32_e32 v78, v78, v185
	v_mul_f32_e32 v79, v79, v185
	v_mul_f32_e32 v80, v80, v185
	v_mul_f32_e32 v81, v81, v185
	v_mul_f32_e32 v82, v82, v185
	v_mul_f32_e32 v83, v83, v185
	v_mul_f32_e32 v84, v84, v185
	v_mul_f32_e32 v85, v85, v185
	v_mul_f32_e32 v86, v86, v185
	v_mul_f32_e32 v87, v87, v185
	v_fma_f32 v72, v72, v8, v24
	v_fma_f32 v73, v73, v9, v25
	v_fma_f32 v74, v74, v10, v26
	v_fma_f32 v75, v75, v11, v27
	v_fma_f32 v76, v76, v12, v28
	v_fma_f32 v77, v77, v13, v29
	v_fma_f32 v78, v78, v14, v30
	v_fma_f32 v79, v79, v15, v31
	v_fma_f32 v80, v80, v16, v32
	v_fma_f32 v81, v81, v17, v33
	v_fma_f32 v82, v82, v18, v34
	v_fma_f32 v83, v83, v19, v35
	v_fma_f32 v84, v84, v20, v36
	v_fma_f32 v85, v85, v21, v37
	v_fma_f32 v86, v86, v22, v38
	v_fma_f32 v87, v87, v23, v39
	v_cvt_pk_bf16_f32 v72, v72, v73
	v_cvt_pk_bf16_f32 v73, v74, v75
	v_cvt_pk_bf16_f32 v76, v76, v77
	v_cvt_pk_bf16_f32 v77, v78, v79
	v_cvt_pk_bf16_f32 v80, v80, v81
	v_cvt_pk_bf16_f32 v81, v82, v83
	v_cvt_pk_bf16_f32 v84, v84, v85
	v_cvt_pk_bf16_f32 v85, v86, v87
	v_add_u32_e32 v171, 0x800000, v5
	global_store_dwordx2 v171, v[72:73], s[8:9]
	global_store_dwordx2 v171, v[76:77], s[8:9] offset:512
	global_store_dwordx2 v171, v[80:81], s[8:9] offset:1024
	global_store_dwordx2 v171, v[84:85], s[8:9] offset:1536
	v_mov_b32_e32 v172, 0x8000
	s_mov_b64 exec, 1
	global_store_dwordx2 v172, v[184:185], s[38:39]
	s_mov_b64 exec, -1
	s_waitcnt vmcnt(31)
	v_add_f32_e32 v180, v88, v89
	v_add_f32_e32 v181, v92, v93
	v_add_f32_e32 v182, v96, v97
	v_add_f32_e32 v183, v100, v101
	v_add_f32_e32 v180, v180, v90
	v_add_f32_e32 v181, v181, v94
	v_add_f32_e32 v182, v182, v98
	v_add_f32_e32 v183, v183, v102
	v_add_f32_e32 v180, v180, v91
	v_add_f32_e32 v181, v181, v95
	v_add_f32_e32 v182, v182, v99
	v_add_f32_e32 v183, v183, v103
	v_add_f32_e32 v180, v180, v181
	v_add_f32_e32 v182, v182, v183
	v_add_f32_e32 v180, v180, v182
	s_nop 1
	v_add_f32_dpp v180, v180, v180 quad_perm:[1,0,3,2] row_mask:0xf bank_mask:0xf
	s_nop 1
	v_add_f32_dpp v180, v180, v180 quad_perm:[2,3,0,1] row_mask:0xf bank_mask:0xf
	s_nop 1
	v_add_f32_dpp v180, v180, v180 row_half_mirror row_mask:0xf bank_mask:0xf
	s_nop 1
	v_add_f32_dpp v180, v180, v180 row_mirror row_mask:0xf bank_mask:0xf
	s_nop 1
	v_add_f32_dpp v180, v180, v180 row_bcast:15 row_mask:0xa bank_mask:0xf
	s_nop 1
	v_add_f32_dpp v180, v180, v180 row_bcast:31 row_mask:0xc bank_mask:0xf
	s_nop 0
	v_readlane_b32 s20, v180, 63
	s_nop 1
	v_mul_f32_e32 v184, s20, v2
	v_sub_f32_e32 v88, v88, v184
	v_sub_f32_e32 v89, v89, v184
	v_sub_f32_e32 v90, v90, v184
	v_sub_f32_e32 v91, v91, v184
	v_sub_f32_e32 v92, v92, v184
	v_sub_f32_e32 v93, v93, v184
	v_sub_f32_e32 v94, v94, v184
	v_sub_f32_e32 v95, v95, v184
	v_sub_f32_e32 v96, v96, v184
	v_sub_f32_e32 v97, v97, v184
	v_sub_f32_e32 v98, v98, v184
	v_sub_f32_e32 v99, v99, v184
	v_sub_f32_e32 v100, v100, v184
	v_sub_f32_e32 v101, v101, v184
	v_sub_f32_e32 v102, v102, v184
	v_sub_f32_e32 v103, v103, v184
	v_mul_f32_e32 v180, v88, v88
	v_mul_f32_e32 v181, v92, v92
	v_mul_f32_e32 v182, v96, v96
	v_mul_f32_e32 v183, v100, v100
	v_fmac_f32_e32 v180, v89, v89
	v_fmac_f32_e32 v181, v93, v93
	v_fmac_f32_e32 v182, v97, v97
	v_fmac_f32_e32 v183, v101, v101
	v_fmac_f32_e32 v180, v90, v90
	v_fmac_f32_e32 v181, v94, v94
	v_fmac_f32_e32 v182, v98, v98
	v_fmac_f32_e32 v183, v102, v102
	v_fmac_f32_e32 v180, v91, v91
	v_fmac_f32_e32 v181, v95, v95
	v_fmac_f32_e32 v182, v99, v99
	v_fmac_f32_e32 v183, v103, v103
	v_add_f32_e32 v180, v180, v181
	v_add_f32_e32 v182, v182, v183
	v_add_f32_e32 v180, v180, v182
	s_nop 1
	v_add_f32_dpp v180, v180, v180 quad_perm:[1,0,3,2] row_mask:0xf bank_mask:0xf
	s_nop 1
	v_add_f32_dpp v180, v180, v180 quad_perm:[2,3,0,1] row_mask:0xf bank_mask:0xf
	s_nop 1
	v_add_f32_dpp v180, v180, v180 row_half_mirror row_mask:0xf bank_mask:0xf
	s_nop 1
	v_add_f32_dpp v180, v180, v180 row_mirror row_mask:0xf bank_mask:0xf
	s_nop 1
	v_add_f32_dpp v180, v180, v180 row_bcast:15 row_mask:0xa bank_mask:0xf
	s_nop 1
	v_add_f32_dpp v180, v180, v180 row_bcast:31 row_mask:0xc bank_mask:0xf
	s_nop 0
	v_readlane_b32 s20, v180, 63
	s_nop 1
	v_mov_b32_e32 v185, s20
	v_fma_f32 v185, v185, v2, v4
	v_rsq_f32_e32 v185, v185
	s_nop 0
	v_mul_f32_e32 v88, v88, v185
	v_mul_f32_e32 v89, v89, v185
	v_mul_f32_e32 v90, v90, v185
	v_mul_f32_e32 v91, v91, v185
	v_mul_f32_e32 v92, v92, v185
	v_mul_f32_e32 v93, v93, v185
	v_mul_f32_e32 v94, v94, v185
	v_mul_f32_e32 v95, v95, v185
	v_mul_f32_e32 v96, v96, v185
	v_mul_f32_e32 v97, v97, v185
	v_mul_f32_e32 v98, v98, v185
	v_mul_f32_e32 v99, v99, v185
	v_mul_f32_e32 v100, v100, v185
	v_mul_f32_e32 v101, v101, v185
	v_mul_f32_e32 v102, v102, v185
	v_mul_f32_e32 v103, v103, v185
	v_fma_f32 v88, v88, v8, v24
	v_fma_f32 v89, v89, v9, v25
	v_fma_f32 v90, v90, v10, v26
	v_fma_f32 v91, v91, v11, v27
	v_fma_f32 v92, v92, v12, v28
	v_fma_f32 v93, v93, v13, v29
	v_fma_f32 v94, v94, v14, v30
	v_fma_f32 v95, v95, v15, v31
	v_fma_f32 v96, v96, v16, v32
	v_fma_f32 v97, v97, v17, v33
	v_fma_f32 v98, v98, v18, v34
	v_fma_f32 v99, v99, v19, v35
	v_fma_f32 v100, v100, v20, v36
	v_fma_f32 v101, v101, v21, v37
	v_fma_f32 v102, v102, v22, v38
	v_fma_f32 v103, v103, v23, v39
	v_cvt_pk_bf16_f32 v88, v88, v89
	v_cvt_pk_bf16_f32 v89, v90, v91
	v_cvt_pk_bf16_f32 v92, v92, v93
	v_cvt_pk_bf16_f32 v93, v94, v95
	v_cvt_pk_bf16_f32 v96, v96, v97
	v_cvt_pk_bf16_f32 v97, v98, v99
	v_cvt_pk_bf16_f32 v100, v100, v101
	v_cvt_pk_bf16_f32 v101, v102, v103
	v_add_u32_e32 v171, 0xc00000, v5
	global_store_dwordx2 v171, v[88:89], s[8:9]
	global_store_dwordx2 v171, v[92:93], s[8:9] offset:512
	global_store_dwordx2 v171, v[96:97], s[8:9] offset:1024
	global_store_dwordx2 v171, v[100:101], s[8:9] offset:1536
	v_mov_b32_e32 v172, 0xc000
	s_mov_b64 exec, 1
	global_store_dwordx2 v172, v[184:185], s[38:39]
	s_mov_b64 exec, -1
	s_waitcnt vmcnt(32)
	v_add_f32_e32 v180, v104, v105
	v_add_f32_e32 v181, v108, v109
	v_add_f32_e32 v182, v112, v113
	v_add_f32_e32 v183, v116, v117
	v_add_f32_e32 v180, v180, v106
	v_add_f32_e32 v181, v181, v110
	v_add_f32_e32 v182, v182, v114
	v_add_f32_e32 v183, v183, v118
	v_add_f32_e32 v180, v180, v107
	v_add_f32_e32 v181, v181, v111
	v_add_f32_e32 v182, v182, v115
	v_add_f32_e32 v183, v183, v119
	v_add_f32_e32 v180, v180, v181
	v_add_f32_e32 v182, v182, v183
	v_add_f32_e32 v180, v180, v182
	s_nop 1
	v_add_f32_dpp v180, v180, v180 quad_perm:[1,0,3,2] row_mask:0xf bank_mask:0xf
	s_nop 1
	v_add_f32_dpp v180, v180, v180 quad_perm:[2,3,0,1] row_mask:0xf bank_mask:0xf
	s_nop 1
	v_add_f32_dpp v180, v180, v180 row_half_mirror row_mask:0xf bank_mask:0xf
	s_nop 1
	v_add_f32_dpp v180, v180, v180 row_mirror row_mask:0xf bank_mask:0xf
	s_nop 1
	v_add_f32_dpp v180, v180, v180 row_bcast:15 row_mask:0xa bank_mask:0xf
	s_nop 1
	v_add_f32_dpp v180, v180, v180 row_bcast:31 row_mask:0xc bank_mask:0xf
	s_nop 0
	v_readlane_b32 s20, v180, 63
	s_nop 1
	v_mul_f32_e32 v184, s20, v2
	v_sub_f32_e32 v104, v104, v184
	v_sub_f32_e32 v105, v105, v184
	v_sub_f32_e32 v106, v106, v184
	v_sub_f32_e32 v107, v107, v184
	v_sub_f32_e32 v108, v108, v184
	v_sub_f32_e32 v109, v109, v184
	v_sub_f32_e32 v110, v110, v184
	v_sub_f32_e32 v111, v111, v184
	v_sub_f32_e32 v112, v112, v184
	v_sub_f32_e32 v113, v113, v184
	v_sub_f32_e32 v114, v114, v184
	v_sub_f32_e32 v115, v115, v184
	v_sub_f32_e32 v116, v116, v184
	v_sub_f32_e32 v117, v117, v184
	v_sub_f32_e32 v118, v118, v184
	v_sub_f32_e32 v119, v119, v184
	v_mul_f32_e32 v180, v104, v104
	v_mul_f32_e32 v181, v108, v108
	v_mul_f32_e32 v182, v112, v112
	v_mul_f32_e32 v183, v116, v116
	v_fmac_f32_e32 v180, v105, v105
	v_fmac_f32_e32 v181, v109, v109
	v_fmac_f32_e32 v182, v113, v113
	v_fmac_f32_e32 v183, v117, v117
	v_fmac_f32_e32 v180, v106, v106
	v_fmac_f32_e32 v181, v110, v110
	v_fmac_f32_e32 v182, v114, v114
	v_fmac_f32_e32 v183, v118, v118
	v_fmac_f32_e32 v180, v107, v107
	v_fmac_f32_e32 v181, v111, v111
	v_fmac_f32_e32 v182, v115, v115
	v_fmac_f32_e32 v183, v119, v119
	v_add_f32_e32 v180, v180, v181
	v_add_f32_e32 v182, v182, v183
	v_add_f32_e32 v180, v180, v182
	s_nop 1
	v_add_f32_dpp v180, v180, v180 quad_perm:[1,0,3,2] row_mask:0xf bank_mask:0xf
	s_nop 1
	v_add_f32_dpp v180, v180, v180 quad_perm:[2,3,0,1] row_mask:0xf bank_mask:0xf
	s_nop 1
	v_add_f32_dpp v180, v180, v180 row_half_mirror row_mask:0xf bank_mask:0xf
	s_nop 1
	v_add_f32_dpp v180, v180, v180 row_mirror row_mask:0xf bank_mask:0xf
	s_nop 1
	v_add_f32_dpp v180, v180, v180 row_bcast:15 row_mask:0xa bank_mask:0xf
	s_nop 1
	v_add_f32_dpp v180, v180, v180 row_bcast:31 row_mask:0xc bank_mask:0xf
	s_nop 0
	v_readlane_b32 s20, v180, 63
	s_nop 1
	v_mov_b32_e32 v185, s20
	v_fma_f32 v185, v185, v2, v4
	v_rsq_f32_e32 v185, v185
	s_nop 0
	v_mul_f32_e32 v104, v104, v185
	v_mul_f32_e32 v105, v105, v185
	v_mul_f32_e32 v106, v106, v185
	v_mul_f32_e32 v107, v107, v185
	v_mul_f32_e32 v108, v108, v185
	v_mul_f32_e32 v109, v109, v185
	v_mul_f32_e32 v110, v110, v185
	v_mul_f32_e32 v111, v111, v185
	v_mul_f32_e32 v112, v112, v185
	v_mul_f32_e32 v113, v113, v185
	v_mul_f32_e32 v114, v114, v185
	v_mul_f32_e32 v115, v115, v185
	v_mul_f32_e32 v116, v116, v185
	v_mul_f32_e32 v117, v117, v185
	v_mul_f32_e32 v118, v118, v185
	v_mul_f32_e32 v119, v119, v185
	v_fma_f32 v104, v104, v8, v24
	v_fma_f32 v105, v105, v9, v25
	v_fma_f32 v106, v106, v10, v26
	v_fma_f32 v107, v107, v11, v27
	v_fma_f32 v108, v108, v12, v28
	v_fma_f32 v109, v109, v13, v29
	v_fma_f32 v110, v110, v14, v30
	v_fma_f32 v111, v111, v15, v31
	v_fma_f32 v112, v112, v16, v32
	v_fma_f32 v113, v113, v17, v33
	v_fma_f32 v114, v114, v18, v34
	v_fma_f32 v115, v115, v19, v35
	v_fma_f32 v116, v116, v20, v36
	v_fma_f32 v117, v117, v21, v37
	v_fma_f32 v118, v118, v22, v38
	v_fma_f32 v119, v119, v23, v39
	v_cvt_pk_bf16_f32 v104, v104, v105
	v_cvt_pk_bf16_f32 v105, v106, v107
	v_cvt_pk_bf16_f32 v108, v108, v109
	v_cvt_pk_bf16_f32 v109, v110, v111
	v_cvt_pk_bf16_f32 v112, v112, v113
	v_cvt_pk_bf16_f32 v113, v114, v115
	v_cvt_pk_bf16_f32 v116, v116, v117
	v_cvt_pk_bf16_f32 v117, v118, v119
	v_add_u32_e32 v171, 0x1000000, v5
	global_store_dwordx2 v171, v[104:105], s[8:9]
	global_store_dwordx2 v171, v[108:109], s[8:9] offset:512
	global_store_dwordx2 v171, v[112:113], s[8:9] offset:1024
	global_store_dwordx2 v171, v[116:117], s[8:9] offset:1536
	v_mov_b32_e32 v172, 0x10000
	s_mov_b64 exec, 1
	global_store_dwordx2 v172, v[184:185], s[38:39]
	s_mov_b64 exec, -1
	s_waitcnt vmcnt(33)
	v_add_f32_e32 v180, v120, v121
	v_add_f32_e32 v181, v124, v125
	v_add_f32_e32 v182, v128, v129
	v_add_f32_e32 v183, v132, v133
	v_add_f32_e32 v180, v180, v122
	v_add_f32_e32 v181, v181, v126
	v_add_f32_e32 v182, v182, v130
	v_add_f32_e32 v183, v183, v134
	v_add_f32_e32 v180, v180, v123
	v_add_f32_e32 v181, v181, v127
	v_add_f32_e32 v182, v182, v131
	v_add_f32_e32 v183, v183, v135
	v_add_f32_e32 v180, v180, v181
	v_add_f32_e32 v182, v182, v183
	v_add_f32_e32 v180, v180, v182
	s_nop 1
	v_add_f32_dpp v180, v180, v180 quad_perm:[1,0,3,2] row_mask:0xf bank_mask:0xf
	s_nop 1
	v_add_f32_dpp v180, v180, v180 quad_perm:[2,3,0,1] row_mask:0xf bank_mask:0xf
	s_nop 1
	v_add_f32_dpp v180, v180, v180 row_half_mirror row_mask:0xf bank_mask:0xf
	s_nop 1
	v_add_f32_dpp v180, v180, v180 row_mirror row_mask:0xf bank_mask:0xf
	s_nop 1
	v_add_f32_dpp v180, v180, v180 row_bcast:15 row_mask:0xa bank_mask:0xf
	s_nop 1
	v_add_f32_dpp v180, v180, v180 row_bcast:31 row_mask:0xc bank_mask:0xf
	s_nop 0
	v_readlane_b32 s20, v180, 63
	s_nop 1
	v_mul_f32_e32 v184, s20, v2
	v_sub_f32_e32 v120, v120, v184
	v_sub_f32_e32 v121, v121, v184
	v_sub_f32_e32 v122, v122, v184
	v_sub_f32_e32 v123, v123, v184
	v_sub_f32_e32 v124, v124, v184
	v_sub_f32_e32 v125, v125, v184
	v_sub_f32_e32 v126, v126, v184
	v_sub_f32_e32 v127, v127, v184
	v_sub_f32_e32 v128, v128, v184
	v_sub_f32_e32 v129, v129, v184
	v_sub_f32_e32 v130, v130, v184
	v_sub_f32_e32 v131, v131, v184
	v_sub_f32_e32 v132, v132, v184
	v_sub_f32_e32 v133, v133, v184
	v_sub_f32_e32 v134, v134, v184
	v_sub_f32_e32 v135, v135, v184
	v_mul_f32_e32 v180, v120, v120
	v_mul_f32_e32 v181, v124, v124
	v_mul_f32_e32 v182, v128, v128
	v_mul_f32_e32 v183, v132, v132
	v_fmac_f32_e32 v180, v121, v121
	v_fmac_f32_e32 v181, v125, v125
	v_fmac_f32_e32 v182, v129, v129
	v_fmac_f32_e32 v183, v133, v133
	v_fmac_f32_e32 v180, v122, v122
	v_fmac_f32_e32 v181, v126, v126
	v_fmac_f32_e32 v182, v130, v130
	v_fmac_f32_e32 v183, v134, v134
	v_fmac_f32_e32 v180, v123, v123
	v_fmac_f32_e32 v181, v127, v127
	v_fmac_f32_e32 v182, v131, v131
	v_fmac_f32_e32 v183, v135, v135
	v_add_f32_e32 v180, v180, v181
	v_add_f32_e32 v182, v182, v183
	v_add_f32_e32 v180, v180, v182
	s_nop 1
	v_add_f32_dpp v180, v180, v180 quad_perm:[1,0,3,2] row_mask:0xf bank_mask:0xf
	s_nop 1
	v_add_f32_dpp v180, v180, v180 quad_perm:[2,3,0,1] row_mask:0xf bank_mask:0xf
	s_nop 1
	v_add_f32_dpp v180, v180, v180 row_half_mirror row_mask:0xf bank_mask:0xf
	s_nop 1
	v_add_f32_dpp v180, v180, v180 row_mirror row_mask:0xf bank_mask:0xf
	s_nop 1
	v_add_f32_dpp v180, v180, v180 row_bcast:15 row_mask:0xa bank_mask:0xf
	s_nop 1
	v_add_f32_dpp v180, v180, v180 row_bcast:31 row_mask:0xc bank_mask:0xf
	s_nop 0
	v_readlane_b32 s20, v180, 63
	s_nop 1
	v_mov_b32_e32 v185, s20
	v_fma_f32 v185, v185, v2, v4
	v_rsq_f32_e32 v185, v185
	s_nop 0
	v_mul_f32_e32 v120, v120, v185
	v_mul_f32_e32 v121, v121, v185
	v_mul_f32_e32 v122, v122, v185
	v_mul_f32_e32 v123, v123, v185
	v_mul_f32_e32 v124, v124, v185
	v_mul_f32_e32 v125, v125, v185
	v_mul_f32_e32 v126, v126, v185
	v_mul_f32_e32 v127, v127, v185
	v_mul_f32_e32 v128, v128, v185
	v_mul_f32_e32 v129, v129, v185
	v_mul_f32_e32 v130, v130, v185
	v_mul_f32_e32 v131, v131, v185
	v_mul_f32_e32 v132, v132, v185
	v_mul_f32_e32 v133, v133, v185
	v_mul_f32_e32 v134, v134, v185
	v_mul_f32_e32 v135, v135, v185
	v_fma_f32 v120, v120, v8, v24
	v_fma_f32 v121, v121, v9, v25
	v_fma_f32 v122, v122, v10, v26
	v_fma_f32 v123, v123, v11, v27
	v_fma_f32 v124, v124, v12, v28
	v_fma_f32 v125, v125, v13, v29
	v_fma_f32 v126, v126, v14, v30
	v_fma_f32 v127, v127, v15, v31
	v_fma_f32 v128, v128, v16, v32
	v_fma_f32 v129, v129, v17, v33
	v_fma_f32 v130, v130, v18, v34
	v_fma_f32 v131, v131, v19, v35
	v_fma_f32 v132, v132, v20, v36
	v_fma_f32 v133, v133, v21, v37
	v_fma_f32 v134, v134, v22, v38
	v_fma_f32 v135, v135, v23, v39
	v_cvt_pk_bf16_f32 v120, v120, v121
	v_cvt_pk_bf16_f32 v121, v122, v123
	v_cvt_pk_bf16_f32 v124, v124, v125
	v_cvt_pk_bf16_f32 v125, v126, v127
	v_cvt_pk_bf16_f32 v128, v128, v129
	v_cvt_pk_bf16_f32 v129, v130, v131
	v_cvt_pk_bf16_f32 v132, v132, v133
	v_cvt_pk_bf16_f32 v133, v134, v135
	v_add_u32_e32 v171, 0x1400000, v5
	global_store_dwordx2 v171, v[120:121], s[8:9]
	global_store_dwordx2 v171, v[124:125], s[8:9] offset:512
	global_store_dwordx2 v171, v[128:129], s[8:9] offset:1024
	global_store_dwordx2 v171, v[132:133], s[8:9] offset:1536
	v_mov_b32_e32 v172, 0x14000
	s_mov_b64 exec, 1
	global_store_dwordx2 v172, v[184:185], s[38:39]
	s_mov_b64 exec, -1
	s_waitcnt vmcnt(34)
	v_add_f32_e32 v180, v136, v137
	v_add_f32_e32 v181, v140, v141
	v_add_f32_e32 v182, v144, v145
	v_add_f32_e32 v183, v148, v149
	v_add_f32_e32 v180, v180, v138
	v_add_f32_e32 v181, v181, v142
	v_add_f32_e32 v182, v182, v146
	v_add_f32_e32 v183, v183, v150
	v_add_f32_e32 v180, v180, v139
	v_add_f32_e32 v181, v181, v143
	v_add_f32_e32 v182, v182, v147
	v_add_f32_e32 v183, v183, v151
	v_add_f32_e32 v180, v180, v181
	v_add_f32_e32 v182, v182, v183
	v_add_f32_e32 v180, v180, v182
	s_nop 1
	v_add_f32_dpp v180, v180, v180 quad_perm:[1,0,3,2] row_mask:0xf bank_mask:0xf
	s_nop 1
	v_add_f32_dpp v180, v180, v180 quad_perm:[2,3,0,1] row_mask:0xf bank_mask:0xf
	s_nop 1
	v_add_f32_dpp v180, v180, v180 row_half_mirror row_mask:0xf bank_mask:0xf
	s_nop 1
	v_add_f32_dpp v180, v180, v180 row_mirror row_mask:0xf bank_mask:0xf
	s_nop 1
	v_add_f32_dpp v180, v180, v180 row_bcast:15 row_mask:0xa bank_mask:0xf
	s_nop 1
	v_add_f32_dpp v180, v180, v180 row_bcast:31 row_mask:0xc bank_mask:0xf
	s_nop 0
	v_readlane_b32 s20, v180, 63
	s_nop 1
	v_mul_f32_e32 v184, s20, v2
	v_sub_f32_e32 v136, v136, v184
	v_sub_f32_e32 v137, v137, v184
	v_sub_f32_e32 v138, v138, v184
	v_sub_f32_e32 v139, v139, v184
	v_sub_f32_e32 v140, v140, v184
	v_sub_f32_e32 v141, v141, v184
	v_sub_f32_e32 v142, v142, v184
	v_sub_f32_e32 v143, v143, v184
	v_sub_f32_e32 v144, v144, v184
	v_sub_f32_e32 v145, v145, v184
	v_sub_f32_e32 v146, v146, v184
	v_sub_f32_e32 v147, v147, v184
	v_sub_f32_e32 v148, v148, v184
	v_sub_f32_e32 v149, v149, v184
	v_sub_f32_e32 v150, v150, v184
	v_sub_f32_e32 v151, v151, v184
	v_mul_f32_e32 v180, v136, v136
	v_mul_f32_e32 v181, v140, v140
	v_mul_f32_e32 v182, v144, v144
	v_mul_f32_e32 v183, v148, v148
	v_fmac_f32_e32 v180, v137, v137
	v_fmac_f32_e32 v181, v141, v141
	v_fmac_f32_e32 v182, v145, v145
	v_fmac_f32_e32 v183, v149, v149
	v_fmac_f32_e32 v180, v138, v138
	v_fmac_f32_e32 v181, v142, v142
	v_fmac_f32_e32 v182, v146, v146
	v_fmac_f32_e32 v183, v150, v150
	v_fmac_f32_e32 v180, v139, v139
	v_fmac_f32_e32 v181, v143, v143
	v_fmac_f32_e32 v182, v147, v147
	v_fmac_f32_e32 v183, v151, v151
	v_add_f32_e32 v180, v180, v181
	v_add_f32_e32 v182, v182, v183
	v_add_f32_e32 v180, v180, v182
	s_nop 1
	v_add_f32_dpp v180, v180, v180 quad_perm:[1,0,3,2] row_mask:0xf bank_mask:0xf
	s_nop 1
	v_add_f32_dpp v180, v180, v180 quad_perm:[2,3,0,1] row_mask:0xf bank_mask:0xf
	s_nop 1
	v_add_f32_dpp v180, v180, v180 row_half_mirror row_mask:0xf bank_mask:0xf
	s_nop 1
	v_add_f32_dpp v180, v180, v180 row_mirror row_mask:0xf bank_mask:0xf
	s_nop 1
	v_add_f32_dpp v180, v180, v180 row_bcast:15 row_mask:0xa bank_mask:0xf
	s_nop 1
	v_add_f32_dpp v180, v180, v180 row_bcast:31 row_mask:0xc bank_mask:0xf
	s_nop 0
	v_readlane_b32 s20, v180, 63
	s_nop 1
	v_mov_b32_e32 v185, s20
	v_fma_f32 v185, v185, v2, v4
	v_rsq_f32_e32 v185, v185
	s_nop 0
	v_mul_f32_e32 v136, v136, v185
	v_mul_f32_e32 v137, v137, v185
	v_mul_f32_e32 v138, v138, v185
	v_mul_f32_e32 v139, v139, v185
	v_mul_f32_e32 v140, v140, v185
	v_mul_f32_e32 v141, v141, v185
	v_mul_f32_e32 v142, v142, v185
	v_mul_f32_e32 v143, v143, v185
	v_mul_f32_e32 v144, v144, v185
	v_mul_f32_e32 v145, v145, v185
	v_mul_f32_e32 v146, v146, v185
	v_mul_f32_e32 v147, v147, v185
	v_mul_f32_e32 v148, v148, v185
	v_mul_f32_e32 v149, v149, v185
	v_mul_f32_e32 v150, v150, v185
	v_mul_f32_e32 v151, v151, v185
	v_fma_f32 v136, v136, v8, v24
	v_fma_f32 v137, v137, v9, v25
	v_fma_f32 v138, v138, v10, v26
	v_fma_f32 v139, v139, v11, v27
	v_fma_f32 v140, v140, v12, v28
	v_fma_f32 v141, v141, v13, v29
	v_fma_f32 v142, v142, v14, v30
	v_fma_f32 v143, v143, v15, v31
	v_fma_f32 v144, v144, v16, v32
	v_fma_f32 v145, v145, v17, v33
	v_fma_f32 v146, v146, v18, v34
	v_fma_f32 v147, v147, v19, v35
	v_fma_f32 v148, v148, v20, v36
	v_fma_f32 v149, v149, v21, v37
	v_fma_f32 v150, v150, v22, v38
	v_fma_f32 v151, v151, v23, v39
	v_cvt_pk_bf16_f32 v136, v136, v137
	v_cvt_pk_bf16_f32 v137, v138, v139
	v_cvt_pk_bf16_f32 v140, v140, v141
	v_cvt_pk_bf16_f32 v141, v142, v143
	v_cvt_pk_bf16_f32 v144, v144, v145
	v_cvt_pk_bf16_f32 v145, v146, v147
	v_cvt_pk_bf16_f32 v148, v148, v149
	v_cvt_pk_bf16_f32 v149, v150, v151
	v_add_u32_e32 v171, 0x1800000, v5
	global_store_dwordx2 v171, v[136:137], s[8:9]
	global_store_dwordx2 v171, v[140:141], s[8:9] offset:512
	global_store_dwordx2 v171, v[144:145], s[8:9] offset:1024
	global_store_dwordx2 v171, v[148:149], s[8:9] offset:1536
	v_mov_b32_e32 v172, 0x18000
	s_mov_b64 exec, 1
	global_store_dwordx2 v172, v[184:185], s[38:39]
	s_mov_b64 exec, -1
	s_waitcnt vmcnt(35)
	v_add_f32_e32 v180, v152, v153
	v_add_f32_e32 v181, v156, v157
	v_add_f32_e32 v182, v160, v161
	v_add_f32_e32 v183, v164, v165
	v_add_f32_e32 v180, v180, v154
	v_add_f32_e32 v181, v181, v158
	v_add_f32_e32 v182, v182, v162
	v_add_f32_e32 v183, v183, v166
	v_add_f32_e32 v180, v180, v155
	v_add_f32_e32 v181, v181, v159
	v_add_f32_e32 v182, v182, v163
	v_add_f32_e32 v183, v183, v167
	v_add_f32_e32 v180, v180, v181
	v_add_f32_e32 v182, v182, v183
	v_add_f32_e32 v180, v180, v182
	s_nop 1
	v_add_f32_dpp v180, v180, v180 quad_perm:[1,0,3,2] row_mask:0xf bank_mask:0xf
	s_nop 1
	v_add_f32_dpp v180, v180, v180 quad_perm:[2,3,0,1] row_mask:0xf bank_mask:0xf
	s_nop 1
	v_add_f32_dpp v180, v180, v180 row_half_mirror row_mask:0xf bank_mask:0xf
	s_nop 1
	v_add_f32_dpp v180, v180, v180 row_mirror row_mask:0xf bank_mask:0xf
	s_nop 1
	v_add_f32_dpp v180, v180, v180 row_bcast:15 row_mask:0xa bank_mask:0xf
	s_nop 1
	v_add_f32_dpp v180, v180, v180 row_bcast:31 row_mask:0xc bank_mask:0xf
	s_nop 0
	v_readlane_b32 s20, v180, 63
	s_nop 1
	v_mul_f32_e32 v184, s20, v2
	v_sub_f32_e32 v152, v152, v184
	v_sub_f32_e32 v153, v153, v184
	v_sub_f32_e32 v154, v154, v184
	v_sub_f32_e32 v155, v155, v184
	v_sub_f32_e32 v156, v156, v184
	v_sub_f32_e32 v157, v157, v184
	v_sub_f32_e32 v158, v158, v184
	v_sub_f32_e32 v159, v159, v184
	v_sub_f32_e32 v160, v160, v184
	v_sub_f32_e32 v161, v161, v184
	v_sub_f32_e32 v162, v162, v184
	v_sub_f32_e32 v163, v163, v184
	v_sub_f32_e32 v164, v164, v184
	v_sub_f32_e32 v165, v165, v184
	v_sub_f32_e32 v166, v166, v184
	v_sub_f32_e32 v167, v167, v184
	v_mul_f32_e32 v180, v152, v152
	v_mul_f32_e32 v181, v156, v156
	v_mul_f32_e32 v182, v160, v160
	v_mul_f32_e32 v183, v164, v164
	v_fmac_f32_e32 v180, v153, v153
	v_fmac_f32_e32 v181, v157, v157
	v_fmac_f32_e32 v182, v161, v161
	v_fmac_f32_e32 v183, v165, v165
	v_fmac_f32_e32 v180, v154, v154
	v_fmac_f32_e32 v181, v158, v158
	v_fmac_f32_e32 v182, v162, v162
	v_fmac_f32_e32 v183, v166, v166
	v_fmac_f32_e32 v180, v155, v155
	v_fmac_f32_e32 v181, v159, v159
	v_fmac_f32_e32 v182, v163, v163
	v_fmac_f32_e32 v183, v167, v167
	v_add_f32_e32 v180, v180, v181
	v_add_f32_e32 v182, v182, v183
	v_add_f32_e32 v180, v180, v182
	s_nop 1
	v_add_f32_dpp v180, v180, v180 quad_perm:[1,0,3,2] row_mask:0xf bank_mask:0xf
	s_nop 1
	v_add_f32_dpp v180, v180, v180 quad_perm:[2,3,0,1] row_mask:0xf bank_mask:0xf
	s_nop 1
	v_add_f32_dpp v180, v180, v180 row_half_mirror row_mask:0xf bank_mask:0xf
	s_nop 1
	v_add_f32_dpp v180, v180, v180 row_mirror row_mask:0xf bank_mask:0xf
	s_nop 1
	v_add_f32_dpp v180, v180, v180 row_bcast:15 row_mask:0xa bank_mask:0xf
	s_nop 1
	v_add_f32_dpp v180, v180, v180 row_bcast:31 row_mask:0xc bank_mask:0xf
	s_nop 0
	v_readlane_b32 s20, v180, 63
	s_nop 1
	v_mov_b32_e32 v185, s20
	v_fma_f32 v185, v185, v2, v4
	v_rsq_f32_e32 v185, v185
	s_nop 0
	v_mul_f32_e32 v152, v152, v185
	v_mul_f32_e32 v153, v153, v185
	v_mul_f32_e32 v154, v154, v185
	v_mul_f32_e32 v155, v155, v185
	v_mul_f32_e32 v156, v156, v185
	v_mul_f32_e32 v157, v157, v185
	v_mul_f32_e32 v158, v158, v185
	v_mul_f32_e32 v159, v159, v185
	v_mul_f32_e32 v160, v160, v185
	v_mul_f32_e32 v161, v161, v185
	v_mul_f32_e32 v162, v162, v185
	v_mul_f32_e32 v163, v163, v185
	v_mul_f32_e32 v164, v164, v185
	v_mul_f32_e32 v165, v165, v185
	v_mul_f32_e32 v166, v166, v185
	v_mul_f32_e32 v167, v167, v185
	v_fma_f32 v152, v152, v8, v24
	v_fma_f32 v153, v153, v9, v25
	v_fma_f32 v154, v154, v10, v26
	v_fma_f32 v155, v155, v11, v27
	v_fma_f32 v156, v156, v12, v28
	v_fma_f32 v157, v157, v13, v29
	v_fma_f32 v158, v158, v14, v30
	v_fma_f32 v159, v159, v15, v31
	v_fma_f32 v160, v160, v16, v32
	v_fma_f32 v161, v161, v17, v33
	v_fma_f32 v162, v162, v18, v34
	v_fma_f32 v163, v163, v19, v35
	v_fma_f32 v164, v164, v20, v36
	v_fma_f32 v165, v165, v21, v37
	v_fma_f32 v166, v166, v22, v38
	v_fma_f32 v167, v167, v23, v39
	v_cvt_pk_bf16_f32 v152, v152, v153
	v_cvt_pk_bf16_f32 v153, v154, v155
	v_cvt_pk_bf16_f32 v156, v156, v157
	v_cvt_pk_bf16_f32 v157, v158, v159
	v_cvt_pk_bf16_f32 v160, v160, v161
	v_cvt_pk_bf16_f32 v161, v162, v163
	v_cvt_pk_bf16_f32 v164, v164, v165
	v_cvt_pk_bf16_f32 v165, v166, v167
	v_add_u32_e32 v171, 0x1c00000, v5
	global_store_dwordx2 v171, v[152:153], s[8:9]
	global_store_dwordx2 v171, v[156:157], s[8:9] offset:512
	global_store_dwordx2 v171, v[160:161], s[8:9] offset:1024
	global_store_dwordx2 v171, v[164:165], s[8:9] offset:1536
	v_mov_b32_e32 v172, 0x1c000
	s_mov_b64 exec, 1
	global_store_dwordx2 v172, v[184:185], s[38:39]
	s_mov_b64 exec, -1
	s_branch .LBB0_188
.Lln_late:
	s_cmpk_lt_u32 s10, 0x400
	s_cbranch_scc0 .Lln_r10
	global_load_dwordx4 v[40:43], v1, s[4:5]
	global_load_dwordx4 v[44:47], v1, s[4:5] offset:1024
	global_load_dwordx4 v[48:51], v1, s[4:5] offset:2048
	global_load_dwordx4 v[52:55], v1, s[4:5] offset:3072
	global_load_dwordx4 v[8:11], v1, s[40:41]
	global_load_dwordx4 v[12:15], v1, s[40:41] offset:1024
	global_load_dwordx4 v[16:19], v1, s[40:41] offset:2048
	global_load_dwordx4 v[20:23], v1, s[40:41] offset:3072
	global_load_dwordx4 v[24:27], v1, s[42:43]
	global_load_dwordx4 v[28:31], v1, s[42:43] offset:1024
	global_load_dwordx4 v[32:35], v1, s[42:43] offset:2048
	global_load_dwordx4 v[36:39], v1, s[42:43] offset:3072
	v_add_u32_e32 v170, 0x600000, v1
	global_load_dwordx4 v[56:59], v170, s[4:5]
	global_load_dwordx4 v[60:63], v170, s[4:5] offset:1024
	global_load_dwordx4 v[64:67], v170, s[4:5] offset:2048
	global_load_dwordx4 v[68:71], v170, s[4:5] offset:3072
	v_add_u32_e32 v170, 0xc00000, v1
	global_load_dwordx4 v[72:75], v170, s[4:5]
	global_load_dwordx4 v[76:79], v170, s[4:5] offset:1024
	global_load_dwordx4 v[80:83], v170, s[4:5] offset:2048
	global_load_dwordx4 v[84:87], v170, s[4:5] offset:3072
	v_add_u32_e32 v170, 0x1200000, v1
	global_load_dwordx4 v[88:91], v170, s[4:5]
	global_load_dwordx4 v[92:95], v170, s[4:5] offset:1024
	global_load_dwordx4 v[96:99], v170, s[4:5] offset:2048
	global_load_dwordx4 v[100:103], v170, s[4:5] offset:3072
	v_add_u32_e32 v170, 0x1800000, v1
	global_load_dwordx4 v[104:107], v170, s[4:5]
	global_load_dwordx4 v[108:111], v170, s[4:5] offset:1024
	global_load_dwordx4 v[112:115], v170, s[4:5] offset:2048
	global_load_dwordx4 v[116:119], v170, s[4:5] offset:3072
	v_add_u32_e32 v170, 0x1e00000, v1
	global_load_dwordx4 v[120:123], v170, s[4:5]
	global_load_dwordx4 v[124:127], v170, s[4:5] offset:1024
	global_load_dwordx4 v[128:131], v170, s[4:5] offset:2048
	global_load_dwordx4 v[132:135], v170, s[4:5] offset:3072
	v_add_u32_e32 v170, 0x2400000, v1
	global_load_dwordx4 v[136:139], v170, s[4:5]
	global_load_dwordx4 v[140:143], v170, s[4:5] offset:1024
	global_load_dwordx4 v[144:147], v170, s[4:5] offset:2048
	global_load_dwordx4 v[148:151], v170, s[4:5] offset:3072
	v_add_u32_e32 v170, 0x2a00000, v1
	global_load_dwordx4 v[152:155], v170, s[4:5]
	global_load_dwordx4 v[156:159], v170, s[4:5] offset:1024
	global_load_dwordx4 v[160:163], v170, s[4:5] offset:2048
	global_load_dwordx4 v[164:167], v170, s[4:5] offset:3072
	s_waitcnt vmcnt(36)
	v_add_f32_e32 v180, v40, v41
	v_add_f32_e32 v181, v44, v45
	v_add_f32_e32 v182, v48, v49
	v_add_f32_e32 v183, v52, v53
	v_add_f32_e32 v180, v180, v42
	v_add_f32_e32 v181, v181, v46
	v_add_f32_e32 v182, v182, v50
	v_add_f32_e32 v183, v183, v54
	v_add_f32_e32 v180, v180, v43
	v_add_f32_e32 v181, v181, v47
	v_add_f32_e32 v182, v182, v51
	v_add_f32_e32 v183, v183, v55
	v_add_f32_e32 v180, v180, v181
	v_add_f32_e32 v182, v182, v183
	v_add_f32_e32 v180, v180, v182
	s_nop 1
	v_add_f32_dpp v180, v180, v180 quad_perm:[1,0,3,2] row_mask:0xf bank_mask:0xf
	s_nop 1
	v_add_f32_dpp v180, v180, v180 quad_perm:[2,3,0,1] row_mask:0xf bank_mask:0xf
	s_nop 1
	v_add_f32_dpp v180, v180, v180 row_half_mirror row_mask:0xf bank_mask:0xf
	s_nop 1
	v_add_f32_dpp v180, v180, v180 row_mirror row_mask:0xf bank_mask:0xf
	s_nop 1
	v_add_f32_dpp v180, v180, v180 row_bcast:15 row_mask:0xa bank_mask:0xf
	s_nop 1
	v_add_f32_dpp v180, v180, v180 row_bcast:31 row_mask:0xc bank_mask:0xf
	s_nop 0
	v_readlane_b32 s20, v180, 63
	s_nop 1
	v_mul_f32_e32 v184, s20, v2
	v_sub_f32_e32 v40, v40, v184
	v_sub_f32_e32 v41, v41, v184
	v_sub_f32_e32 v42, v42, v184
	v_sub_f32_e32 v43, v43, v184
	v_sub_f32_e32 v44, v44, v184
	v_sub_f32_e32 v45, v45, v184
	v_sub_f32_e32 v46, v46, v184
	v_sub_f32_e32 v47, v47, v184
	v_sub_f32_e32 v48, v48, v184
	v_sub_f32_e32 v49, v49, v184
	v_sub_f32_e32 v50, v50, v184
	v_sub_f32_e32 v51, v51, v184
	v_sub_f32_e32 v52, v52, v184
	v_sub_f32_e32 v53, v53, v184
	v_sub_f32_e32 v54, v54, v184
	v_sub_f32_e32 v55, v55, v184
	v_mul_f32_e32 v180, v40, v40
	v_mul_f32_e32 v181, v44, v44
	v_mul_f32_e32 v182, v48, v48
	v_mul_f32_e32 v183, v52, v52
	v_fmac_f32_e32 v180, v41, v41
	v_fmac_f32_e32 v181, v45, v45
	v_fmac_f32_e32 v182, v49, v49
	v_fmac_f32_e32 v183, v53, v53
	v_fmac_f32_e32 v180, v42, v42
	v_fmac_f32_e32 v181, v46, v46
	v_fmac_f32_e32 v182, v50, v50
	v_fmac_f32_e32 v183, v54, v54
	v_fmac_f32_e32 v180, v43, v43
	v_fmac_f32_e32 v181, v47, v47
	v_fmac_f32_e32 v182, v51, v51
	v_fmac_f32_e32 v183, v55, v55
	v_add_f32_e32 v180, v180, v181
	v_add_f32_e32 v182, v182, v183
	v_add_f32_e32 v180, v180, v182
	s_nop 1
	v_add_f32_dpp v180, v180, v180 quad_perm:[1,0,3,2] row_mask:0xf bank_mask:0xf
	s_nop 1
	v_add_f32_dpp v180, v180, v180 quad_perm:[2,3,0,1] row_mask:0xf bank_mask:0xf
	s_nop 1
	v_add_f32_dpp v180, v180, v180 row_half_mirror row_mask:0xf bank_mask:0xf
	s_nop 1
	v_add_f32_dpp v180, v180, v180 row_mirror row_mask:0xf bank_mask:0xf
	s_nop 1
	v_add_f32_dpp v180, v180, v180 row_bcast:15 row_mask:0xa bank_mask:0xf
	s_nop 1
	v_add_f32_dpp v180, v180, v180 row_bcast:31 row_mask:0xc bank_mask:0xf
	s_nop 0
	v_readlane_b32 s20, v180, 63
	s_nop 1
	v_mov_b32_e32 v185, s20
	v_fma_f32 v185, v185, v2, v4
	v_rsq_f32_e32 v185, v185
	s_nop 0
	v_mul_f32_e32 v40, v40, v185
	v_mul_f32_e32 v41, v41, v185
	v_mul_f32_e32 v42, v42, v185
	v_mul_f32_e32 v43, v43, v185
	v_mul_f32_e32 v44, v44, v185
	v_mul_f32_e32 v45, v45, v185
	v_mul_f32_e32 v46, v46, v185
	v_mul_f32_e32 v47, v47, v185
	v_mul_f32_e32 v48, v48, v185
	v_mul_f32_e32 v49, v49, v185
	v_mul_f32_e32 v50, v50, v185
	v_mul_f32_e32 v51, v51, v185
	v_mul_f32_e32 v52, v52, v185
	v_mul_f32_e32 v53, v53, v185
	v_mul_f32_e32 v54, v54, v185
	v_mul_f32_e32 v55, v55, v185
	s_waitcnt vmcnt(28)
	v_fma_f32 v40, v40, v8, v24
	v_fma_f32 v41, v41, v9, v25
	v_fma_f32 v42, v42, v10, v26
	v_fma_f32 v43, v43, v11, v27
	v_fma_f32 v44, v44, v12, v28
	v_fma_f32 v45, v45, v13, v29
	v_fma_f32 v46, v46, v14, v30
	v_fma_f32 v47, v47, v15, v31
	v_fma_f32 v48, v48, v16, v32
	v_fma_f32 v49, v49, v17, v33
	v_fma_f32 v50, v50, v18, v34
	v_fma_f32 v51, v51, v19, v35
	v_fma_f32 v52, v52, v20, v36
	v_fma_f32 v53, v53, v21, v37
	v_fma_f32 v54, v54, v22, v38
	v_fma_f32 v55, v55, v23, v39
	v_cvt_pk_bf16_f32 v40, v40, v41
	v_cvt_pk_bf16_f32 v41, v42, v43
	v_cvt_pk_bf16_f32 v44, v44, v45
	v_cvt_pk_bf16_f32 v45, v46, v47
	v_cvt_pk_bf16_f32 v48, v48, v49
	v_cvt_pk_bf16_f32 v49, v50, v51
	v_cvt_pk_bf16_f32 v52, v52, v53
	v_cvt_pk_bf16_f32 v53, v54, v55
	global_store_dwordx2 v5, v[40:41], s[8:9]
	global_store_dwordx2 v5, v[44:45], s[8:9] offset:512
	global_store_dwordx2 v5, v[48:49], s[8:9] offset:1024
	global_store_dwordx2 v5, v[52:53], s[8:9] offset:1536
	v_mov_b32_e32 v172, 0x0
	s_mov_b64 exec, 1
	global_store_dwordx2 v172, v[184:185], s[38:39]
	s_mov_b64 exec, -1
	s_nop 1
	v_add_u32_e32 v170, 0x3000000, v1
	global_load_dwordx4 v[40:43], v170, s[4:5]
	global_load_dwordx4 v[44:47], v170, s[4:5] offset:1024
	global_load_dwordx4 v[48:51], v170, s[4:5] offset:2048
	global_load_dwordx4 v[52:55], v170, s[4:5] offset:3072
	s_waitcnt vmcnt(33)
	v_add_f32_e32 v180, v56, v57
	v_add_f32_e32 v181, v60, v61
	v_add_f32_e32 v182, v64, v65
	v_add_f32_e32 v183, v68, v69
	v_add_f32_e32 v180, v180, v58
	v_add_f32_e32 v181, v181, v62
	v_add_f32_e32 v182, v182, v66
	v_add_f32_e32 v183, v183, v70
	v_add_f32_e32 v180, v180, v59
	v_add_f32_e32 v181, v181, v63
	v_add_f32_e32 v182, v182, v67
	v_add_f32_e32 v183, v183, v71
	v_add_f32_e32 v180, v180, v181
	v_add_f32_e32 v182, v182, v183
	v_add_f32_e32 v180, v180, v182
	s_nop 1
	v_add_f32_dpp v180, v180, v180 quad_perm:[1,0,3,2] row_mask:0xf bank_mask:0xf
	s_nop 1
	v_add_f32_dpp v180, v180, v180 quad_perm:[2,3,0,1] row_mask:0xf bank_mask:0xf
	s_nop 1
	v_add_f32_dpp v180, v180, v180 row_half_mirror row_mask:0xf bank_mask:0xf
	s_nop 1
	v_add_f32_dpp v180, v180, v180 row_mirror row_mask:0xf bank_mask:0xf
	s_nop 1
	v_add_f32_dpp v180, v180, v180 row_bcast:15 row_mask:0xa bank_mask:0xf
	s_nop 1
	v_add_f32_dpp v180, v180, v180 row_bcast:31 row_mask:0xc bank_mask:0xf
	s_nop 0
	v_readlane_b32 s20, v180, 63
	s_nop 1
	v_mul_f32_e32 v184, s20, v2
	v_sub_f32_e32 v56, v56, v184
	v_sub_f32_e32 v57, v57, v184
	v_sub_f32_e32 v58, v58, v184
	v_sub_f32_e32 v59, v59, v184
	v_sub_f32_e32 v60, v60, v184
	v_sub_f32_e32 v61, v61, v184
	v_sub_f32_e32 v62, v62, v184
	v_sub_f32_e32 v63, v63, v184
	v_sub_f32_e32 v64, v64, v184
	v_sub_f32_e32 v65, v65, v184
	v_sub_f32_e32 v66, v66, v184
	v_sub_f32_e32 v67, v67, v184
	v_sub_f32_e32 v68, v68, v184
	v_sub_f32_e32 v69, v69, v184
	v_sub_f32_e32 v70, v70, v184
	v_sub_f32_e32 v71, v71, v184
	v_mul_f32_e32 v180, v56, v56
	v_mul_f32_e32 v181, v60, v60
	v_mul_f32_e32 v182, v64, v64
	v_mul_f32_e32 v183, v68, v68
	v_fmac_f32_e32 v180, v57, v57
	v_fmac_f32_e32 v181, v61, v61
	v_fmac_f32_e32 v182, v65, v65
	v_fmac_f32_e32 v183, v69, v69
	v_fmac_f32_e32 v180, v58, v58
	v_fmac_f32_e32 v181, v62, v62
	v_fmac_f32_e32 v182, v66, v66
	v_fmac_f32_e32 v183, v70, v70
	v_fmac_f32_e32 v180, v59, v59
	v_fmac_f32_e32 v181, v63, v63
	v_fmac_f32_e32 v182, v67, v67
	v_fmac_f32_e32 v183, v71, v71
	v_add_f32_e32 v180, v180, v181
	v_add_f32_e32 v182, v182, v183
	v_add_f32_e32 v180, v180, v182
	s_nop 1
	v_add_f32_dpp v180, v180, v180 quad_perm:[1,0,3,2] row_mask:0xf bank_mask:0xf
	s_nop 1
	v_add_f32_dpp v180, v180, v180 quad_perm:[2,3,0,1] row_mask:0xf bank_mask:0xf
	s_nop 1
	v_add_f32_dpp v180, v180, v180 row_half_mirror row_mask:0xf bank_mask:0xf
	s_nop 1
	v_add_f32_dpp v180, v180, v180 row_mirror row_mask:0xf bank_mask:0xf
	s_nop 1
	v_add_f32_dpp v180, v180, v180 row_bcast:15 row_mask:0xa bank_mask:0xf
	s_nop 1
	v_add_f32_dpp v180, v180, v180 row_bcast:31 row_mask:0xc bank_mask:0xf
	s_nop 0
	v_readlane_b32 s20, v180, 63
	s_nop 1
	v_mov_b32_e32 v185, s20
	v_fma_f32 v185, v185, v2, v4
	v_rsq_f32_e32 v185, v185
	s_nop 0
	v_mul_f32_e32 v56, v56, v185
	v_mul_f32_e32 v57, v57, v185
	v_mul_f32_e32 v58, v58, v185
	v_mul_f32_e32 v59, v59, v185
	v_mul_f32_e32 v60, v60, v185
	v_mul_f32_e32 v61, v61, v185
	v_mul_f32_e32 v62, v62, v185
	v_mul_f32_e32 v63, v63, v185
	v_mul_f32_e32 v64, v64, v185
	v_mul_f32_e32 v65, v65, v185
	v_mul_f32_e32 v66, v66, v185
	v_mul_f32_e32 v67, v67, v185
	v_mul_f32_e32 v68, v68, v185
	v_mul_f32_e32 v69, v69, v185
	v_mul_f32_e32 v70, v70, v185
	v_mul_f32_e32 v71, v71, v185
	v_fma_f32 v56, v56, v8, v24
	v_fma_f32 v57, v57, v9, v25
	v_fma_f32 v58, v58, v10, v26
	v_fma_f32 v59, v59, v11, v27
	v_fma_f32 v60, v60, v12, v28
	v_fma_f32 v61, v61, v13, v29
	v_fma_f32 v62, v62, v14, v30
	v_fma_f32 v63, v63, v15, v31
	v_fma_f32 v64, v64, v16, v32
	v_fma_f32 v65, v65, v17, v33
	v_fma_f32 v66, v66, v18, v34
	v_fma_f32 v67, v67, v19, v35
	v_fma_f32 v68, v68, v20, v36
	v_fma_f32 v69, v69, v21, v37
	v_fma_f32 v70, v70, v22, v38
	v_fma_f32 v71, v71, v23, v39
	v_cvt_pk_bf16_f32 v56, v56, v57
	v_cvt_pk_bf16_f32 v57, v58, v59
	v_cvt_pk_bf16_f32 v60, v60, v61
	v_cvt_pk_bf16_f32 v61, v62, v63
	v_cvt_pk_bf16_f32 v64, v64, v65
	v_cvt_pk_bf16_f32 v65, v66, v67
	v_cvt_pk_bf16_f32 v68, v68, v69
	v_cvt_pk_bf16_f32 v69, v70, v71
	v_add_u32_e32 v171, 0x300000, v5
	global_store_dwordx2 v171, v[56:57], s[8:9]
	global_store_dwordx2 v171, v[60:61], s[8:9] offset:512
	global_store_dwordx2 v171, v[64:65], s[8:9] offset:1024
	global_store_dwordx2 v171, v[68:69], s[8:9] offset:1536
	v_mov_b32_e32 v172, 0x3000
	s_mov_b64 exec, 1
	global_store_dwordx2 v172, v[184:185], s[38:39]
	s_mov_b64 exec, -1
	s_nop 1
	v_add_u32_e32 v170, 0x3600000, v1
	global_load_dwordx4 v[56:59], v170, s[4:5]
	global_load_dwordx4 v[60:63], v170, s[4:5] offset:1024
	global_load_dwordx4 v[64:67], v170, s[4:5] offset:2048
	global_load_dwordx4 v[68:71], v170, s[4:5] offset:3072
	s_waitcnt vmcnt(38)
	v_add_f32_e32 v180, v72, v73
	v_add_f32_e32 v181, v76, v77
	v_add_f32_e32 v182, v80, v81
	v_add_f32_e32 v183, v84, v85
	v_add_f32_e32 v180, v180, v74
	v_add_f32_e32 v181, v181, v78
	v_add_f32_e32 v182, v182, v82
	v_add_f32_e32 v183, v183, v86
	v_add_f32_e32 v180, v180, v75
	v_add_f32_e32 v181, v181, v79
	v_add_f32_e32 v182, v182, v83
	v_add_f32_e32 v183, v183, v87
	v_add_f32_e32 v180, v180, v181
	v_add_f32_e32 v182, v182, v183
	v_add_f32_e32 v180, v180, v182
	s_nop 1
	v_add_f32_dpp v180, v180, v180 quad_perm:[1,0,3,2] row_mask:0xf bank_mask:0xf
	s_nop 1
	v_add_f32_dpp v180, v180, v180 quad_perm:[2,3,0,1] row_mask:0xf bank_mask:0xf
	s_nop 1
	v_add_f32_dpp v180, v180, v180 row_half_mirror row_mask:0xf bank_mask:0xf
	s_nop 1
	v_add_f32_dpp v180, v180, v180 row_mirror row_mask:0xf bank_mask:0xf
	s_nop 1
	v_add_f32_dpp v180, v180, v180 row_bcast:15 row_mask:0xa bank_mask:0xf
	s_nop 1
	v_add_f32_dpp v180, v180, v180 row_bcast:31 row_mask:0xc bank_mask:0xf
	s_nop 0
	v_readlane_b32 s20, v180, 63
	s_nop 1
	v_mul_f32_e32 v184, s20, v2
	v_sub_f32_e32 v72, v72, v184
	v_sub_f32_e32 v73, v73, v184
	v_sub_f32_e32 v74, v74, v184
	v_sub_f32_e32 v75, v75, v184
	v_sub_f32_e32 v76, v76, v184
	v_sub_f32_e32 v77, v77, v184
	v_sub_f32_e32 v78, v78, v184
	v_sub_f32_e32 v79, v79, v184
	v_sub_f32_e32 v80, v80, v184
	v_sub_f32_e32 v81, v81, v184
	v_sub_f32_e32 v82, v82, v184
	v_sub_f32_e32 v83, v83, v184
	v_sub_f32_e32 v84, v84, v184
	v_sub_f32_e32 v85, v85, v184
	v_sub_f32_e32 v86, v86, v184
	v_sub_f32_e32 v87, v87, v184
	v_mul_f32_e32 v180, v72, v72
	v_mul_f32_e32 v181, v76, v76
	v_mul_f32_e32 v182, v80, v80
	v_mul_f32_e32 v183, v84, v84
	v_fmac_f32_e32 v180, v73, v73
	v_fmac_f32_e32 v181, v77, v77
	v_fmac_f32_e32 v182, v81, v81
	v_fmac_f32_e32 v183, v85, v85
	v_fmac_f32_e32 v180, v74, v74
	v_fmac_f32_e32 v181, v78, v78
	v_fmac_f32_e32 v182, v82, v82
	v_fmac_f32_e32 v183, v86, v86
	v_fmac_f32_e32 v180, v75, v75
	v_fmac_f32_e32 v181, v79, v79
	v_fmac_f32_e32 v182, v83, v83
	v_fmac_f32_e32 v183, v87, v87
	v_add_f32_e32 v180, v180, v181
	v_add_f32_e32 v182, v182, v183
	v_add_f32_e32 v180, v180, v182
	s_nop 1
	v_add_f32_dpp v180, v180, v180 quad_perm:[1,0,3,2] row_mask:0xf bank_mask:0xf
	s_nop 1
	v_add_f32_dpp v180, v180, v180 quad_perm:[2,3,0,1] row_mask:0xf bank_mask:0xf
	s_nop 1
	v_add_f32_dpp v180, v180, v180 row_half_mirror row_mask:0xf bank_mask:0xf
	s_nop 1
	v_add_f32_dpp v180, v180, v180 row_mirror row_mask:0xf bank_mask:0xf
	s_nop 1
	v_add_f32_dpp v180, v180, v180 row_bcast:15 row_mask:0xa bank_mask:0xf
	s_nop 1
	v_add_f32_dpp v180, v180, v180 row_bcast:31 row_mask:0xc bank_mask:0xf
	s_nop 0
	v_readlane_b32 s20, v180, 63
	s_nop 1
	v_mov_b32_e32 v185, s20
	v_fma_f32 v185, v185, v2, v4
	v_rsq_f32_e32 v185, v185
	s_nop 0
	v_mul_f32_e32 v72, v72, v185
	v_mul_f32_e32 v73, v73, v185
	v_mul_f32_e32 v74, v74, v185
	v_mul_f32_e32 v75, v75, v185
	v_mul_f32_e32 v76, v76, v185
	v_mul_f32_e32 v77, v77, v185
	v_mul_f32_e32 v78, v78, v185
	v_mul_f32_e32 v79, v79, v185
	v_mul_f32_e32 v80, v80, v185
	v_mul_f32_e32 v81, v81, v185
	v_mul_f32_e32 v82, v82, v185
	v_mul_f32_e32 v83, v83, v185
	v_mul_f32_e32 v84, v84, v185
	v_mul_f32_e32 v85, v85, v185
	v_mul_f32_e32 v86, v86, v185
	v_mul_f32_e32 v87, v87, v185
	v_fma_f32 v72, v72, v8, v24
	v_fma_f32 v73, v73, v9, v25
	v_fma_f32 v74, v74, v10, v26
	v_fma_f32 v75, v75, v11, v27
	v_fma_f32 v76, v76, v12, v28
	v_fma_f32 v77, v77, v13, v29
	v_fma_f32 v78, v78, v14, v30
	v_fma_f32 v79, v79, v15, v31
	v_fma_f32 v80, v80, v16, v32
	v_fma_f32 v81, v81, v17, v33
	v_fma_f32 v82, v82, v18, v34
	v_fma_f32 v83, v83, v19, v35
	v_fma_f32 v84, v84, v20, v36
	v_fma_f32 v85, v85, v21, v37
	v_fma_f32 v86, v86, v22, v38
	v_fma_f32 v87, v87, v23, v39
	v_cvt_pk_bf16_f32 v72, v72, v73
	v_cvt_pk_bf16_f32 v73, v74, v75
	v_cvt_pk_bf16_f32 v76, v76, v77
	v_cvt_pk_bf16_f32 v77, v78, v79
	v_cvt_pk_bf16_f32 v80, v80, v81
	v_cvt_pk_bf16_f32 v81, v82, v83
	v_cvt_pk_bf16_f32 v84, v84, v85
	v_cvt_pk_bf16_f32 v85, v86, v87
	v_add_u32_e32 v171, 0x600000, v5
	global_store_dwordx2 v171, v[72:73], s[8:9]
	global_store_dwordx2 v171, v[76:77], s[8:9] offset:512
	global_store_dwordx2 v171, v[80:81], s[8:9] offset:1024
	global_store_dwordx2 v171, v[84:85], s[8:9] offset:1536
	v_mov_b32_e32 v172, 0x6000
	s_mov_b64 exec, 1
	global_store_dwordx2 v172, v[184:185], s[38:39]
	s_mov_b64 exec, -1
	s_nop 1
	v_add_u32_e32 v170, 0x3c00000, v1
	global_load_dwordx4 v[72:75], v170, s[4:5]
	global_load_dwordx4 v[76:79], v170, s[4:5] offset:1024
	global_load_dwordx4 v[80:83], v170, s[4:5] offset:2048
	global_load_dwordx4 v[84:87], v170, s[4:5] offset:3072
	s_waitcnt vmcnt(43)
	v_add_f32_e32 v180, v88, v89
	v_add_f32_e32 v181, v92, v93
	v_add_f32_e32 v182, v96, v97
	v_add_f32_e32 v183, v100, v101
	v_add_f32_e32 v180, v180, v90
	v_add_f32_e32 v181, v181, v94
	v_add_f32_e32 v182, v182, v98
	v_add_f32_e32 v183, v183, v102
	v_add_f32_e32 v180, v180, v91
	v_add_f32_e32 v181, v181, v95
	v_add_f32_e32 v182, v182, v99
	v_add_f32_e32 v183, v183, v103
	v_add_f32_e32 v180, v180, v181
	v_add_f32_e32 v182, v182, v183
	v_add_f32_e32 v180, v180, v182
	s_nop 1
	v_add_f32_dpp v180, v180, v180 quad_perm:[1,0,3,2] row_mask:0xf bank_mask:0xf
	s_nop 1
	v_add_f32_dpp v180, v180, v180 quad_perm:[2,3,0,1] row_mask:0xf bank_mask:0xf
	s_nop 1
	v_add_f32_dpp v180, v180, v180 row_half_mirror row_mask:0xf bank_mask:0xf
	s_nop 1
	v_add_f32_dpp v180, v180, v180 row_mirror row_mask:0xf bank_mask:0xf
	s_nop 1
	v_add_f32_dpp v180, v180, v180 row_bcast:15 row_mask:0xa bank_mask:0xf
	s_nop 1
	v_add_f32_dpp v180, v180, v180 row_bcast:31 row_mask:0xc bank_mask:0xf
	s_nop 0
	v_readlane_b32 s20, v180, 63
	s_nop 1
	v_mul_f32_e32 v184, s20, v2
	v_sub_f32_e32 v88, v88, v184
	v_sub_f32_e32 v89, v89, v184
	v_sub_f32_e32 v90, v90, v184
	v_sub_f32_e32 v91, v91, v184
	v_sub_f32_e32 v92, v92, v184
	v_sub_f32_e32 v93, v93, v184
	v_sub_f32_e32 v94, v94, v184
	v_sub_f32_e32 v95, v95, v184
	v_sub_f32_e32 v96, v96, v184
	v_sub_f32_e32 v97, v97, v184
	v_sub_f32_e32 v98, v98, v184
	v_sub_f32_e32 v99, v99, v184
	v_sub_f32_e32 v100, v100, v184
	v_sub_f32_e32 v101, v101, v184
	v_sub_f32_e32 v102, v102, v184
	v_sub_f32_e32 v103, v103, v184
	v_mul_f32_e32 v180, v88, v88
	v_mul_f32_e32 v181, v92, v92
	v_mul_f32_e32 v182, v96, v96
	v_mul_f32_e32 v183, v100, v100
	v_fmac_f32_e32 v180, v89, v89
	v_fmac_f32_e32 v181, v93, v93
	v_fmac_f32_e32 v182, v97, v97
	v_fmac_f32_e32 v183, v101, v101
	v_fmac_f32_e32 v180, v90, v90
	v_fmac_f32_e32 v181, v94, v94
	v_fmac_f32_e32 v182, v98, v98
	v_fmac_f32_e32 v183, v102, v102
	v_fmac_f32_e32 v180, v91, v91
	v_fmac_f32_e32 v181, v95, v95
	v_fmac_f32_e32 v182, v99, v99
	v_fmac_f32_e32 v183, v103, v103
	v_add_f32_e32 v180, v180, v181
	v_add_f32_e32 v182, v182, v183
	v_add_f32_e32 v180, v180, v182
	s_nop 1
	v_add_f32_dpp v180, v180, v180 quad_perm:[1,0,3,2] row_mask:0xf bank_mask:0xf
	s_nop 1
	v_add_f32_dpp v180, v180, v180 quad_perm:[2,3,0,1] row_mask:0xf bank_mask:0xf
	s_nop 1
	v_add_f32_dpp v180, v180, v180 row_half_mirror row_mask:0xf bank_mask:0xf
	s_nop 1
	v_add_f32_dpp v180, v180, v180 row_mirror row_mask:0xf bank_mask:0xf
	s_nop 1
	v_add_f32_dpp v180, v180, v180 row_bcast:15 row_mask:0xa bank_mask:0xf
	s_nop 1
	v_add_f32_dpp v180, v180, v180 row_bcast:31 row_mask:0xc bank_mask:0xf
	s_nop 0
	v_readlane_b32 s20, v180, 63
	s_nop 1
	v_mov_b32_e32 v185, s20
	v_fma_f32 v185, v185, v2, v4
	v_rsq_f32_e32 v185, v185
	s_nop 0
	v_mul_f32_e32 v88, v88, v185
	v_mul_f32_e32 v89, v89, v185
	v_mul_f32_e32 v90, v90, v185
	v_mul_f32_e32 v91, v91, v185
	v_mul_f32_e32 v92, v92, v185
	v_mul_f32_e32 v93, v93, v185
	v_mul_f32_e32 v94, v94, v185
	v_mul_f32_e32 v95, v95, v185
	v_mul_f32_e32 v96, v96, v185
	v_mul_f32_e32 v97, v97, v185
	v_mul_f32_e32 v98, v98, v185
	v_mul_f32_e32 v99, v99, v185
	v_mul_f32_e32 v100, v100, v185
	v_mul_f32_e32 v101, v101, v185
	v_mul_f32_e32 v102, v102, v185
	v_mul_f32_e32 v103, v103, v185
	v_fma_f32 v88, v88, v8, v24
	v_fma_f32 v89, v89, v9, v25
	v_fma_f32 v90, v90, v10, v26
	v_fma_f32 v91, v91, v11, v27
	v_fma_f32 v92, v92, v12, v28
	v_fma_f32 v93, v93, v13, v29
	v_fma_f32 v94, v94, v14, v30
	v_fma_f32 v95, v95, v15, v31
	v_fma_f32 v96, v96, v16, v32
	v_fma_f32 v97, v97, v17, v33
	v_fma_f32 v98, v98, v18, v34
	v_fma_f32 v99, v99, v19, v35
	v_fma_f32 v100, v100, v20, v36
	v_fma_f32 v101, v101, v21, v37
	v_fma_f32 v102, v102, v22, v38
	v_fma_f32 v103, v103, v23, v39
	v_cvt_pk_bf16_f32 v88, v88, v89
	v_cvt_pk_bf16_f32 v89, v90, v91
	v_cvt_pk_bf16_f32 v92, v92, v93
	v_cvt_pk_bf16_f32 v93, v94, v95
	v_cvt_pk_bf16_f32 v96, v96, v97
	v_cvt_pk_bf16_f32 v97, v98, v99
	v_cvt_pk_bf16_f32 v100, v100, v101
	v_cvt_pk_bf16_f32 v101, v102, v103
	v_add_u32_e32 v171, 0x900000, v5
	global_store_dwordx2 v171, v[88:89], s[8:9]
	global_store_dwordx2 v171, v[92:93], s[8:9] offset:512
	global_store_dwordx2 v171, v[96:97], s[8:9] offset:1024
	global_store_dwordx2 v171, v[100:101], s[8:9] offset:1536
	v_mov_b32_e32 v172, 0x9000
	s_mov_b64 exec, 1
	global_store_dwordx2 v172, v[184:185], s[38:39]
	s_mov_b64 exec, -1
	s_waitcnt vmcnt(44)
	v_add_f32_e32 v180, v104, v105
	v_add_f32_e32 v181, v108, v109
	v_add_f32_e32 v182, v112, v113
	v_add_f32_e32 v183, v116, v117
	v_add_f32_e32 v180, v180, v106
	v_add_f32_e32 v181, v181, v110
	v_add_f32_e32 v182, v182, v114
	v_add_f32_e32 v183, v183, v118
	v_add_f32_e32 v180, v180, v107
	v_add_f32_e32 v181, v181, v111
	v_add_f32_e32 v182, v182, v115
	v_add_f32_e32 v183, v183, v119
	v_add_f32_e32 v180, v180, v181
	v_add_f32_e32 v182, v182, v183
	v_add_f32_e32 v180, v180, v182
	s_nop 1
	v_add_f32_dpp v180, v180, v180 quad_perm:[1,0,3,2] row_mask:0xf bank_mask:0xf
	s_nop 1
	v_add_f32_dpp v180, v180, v180 quad_perm:[2,3,0,1] row_mask:0xf bank_mask:0xf
	s_nop 1
	v_add_f32_dpp v180, v180, v180 row_half_mirror row_mask:0xf bank_mask:0xf
	s_nop 1
	v_add_f32_dpp v180, v180, v180 row_mirror row_mask:0xf bank_mask:0xf
	s_nop 1
	v_add_f32_dpp v180, v180, v180 row_bcast:15 row_mask:0xa bank_mask:0xf
	s_nop 1
	v_add_f32_dpp v180, v180, v180 row_bcast:31 row_mask:0xc bank_mask:0xf
	s_nop 0
	v_readlane_b32 s20, v180, 63
	s_nop 1
	v_mul_f32_e32 v184, s20, v2
	v_sub_f32_e32 v104, v104, v184
	v_sub_f32_e32 v105, v105, v184
	v_sub_f32_e32 v106, v106, v184
	v_sub_f32_e32 v107, v107, v184
	v_sub_f32_e32 v108, v108, v184
	v_sub_f32_e32 v109, v109, v184
	v_sub_f32_e32 v110, v110, v184
	v_sub_f32_e32 v111, v111, v184
	v_sub_f32_e32 v112, v112, v184
	v_sub_f32_e32 v113, v113, v184
	v_sub_f32_e32 v114, v114, v184
	v_sub_f32_e32 v115, v115, v184
	v_sub_f32_e32 v116, v116, v184
	v_sub_f32_e32 v117, v117, v184
	v_sub_f32_e32 v118, v118, v184
	v_sub_f32_e32 v119, v119, v184
	v_mul_f32_e32 v180, v104, v104
	v_mul_f32_e32 v181, v108, v108
	v_mul_f32_e32 v182, v112, v112
	v_mul_f32_e32 v183, v116, v116
	v_fmac_f32_e32 v180, v105, v105
	v_fmac_f32_e32 v181, v109, v109
	v_fmac_f32_e32 v182, v113, v113
	v_fmac_f32_e32 v183, v117, v117
	v_fmac_f32_e32 v180, v106, v106
	v_fmac_f32_e32 v181, v110, v110
	v_fmac_f32_e32 v182, v114, v114
	v_fmac_f32_e32 v183, v118, v118
	v_fmac_f32_e32 v180, v107, v107
	v_fmac_f32_e32 v181, v111, v111
	v_fmac_f32_e32 v182, v115, v115
	v_fmac_f32_e32 v183, v119, v119
	v_add_f32_e32 v180, v180, v181
	v_add_f32_e32 v182, v182, v183
	v_add_f32_e32 v180, v180, v182
	s_nop 1
	v_add_f32_dpp v180, v180, v180 quad_perm:[1,0,3,2] row_mask:0xf bank_mask:0xf
	s_nop 1
	v_add_f32_dpp v180, v180, v180 quad_perm:[2,3,0,1] row_mask:0xf bank_mask:0xf
	s_nop 1
	v_add_f32_dpp v180, v180, v180 row_half_mirror row_mask:0xf bank_mask:0xf
	s_nop 1
	v_add_f32_dpp v180, v180, v180 row_mirror row_mask:0xf bank_mask:0xf
	s_nop 1
	v_add_f32_dpp v180, v180, v180 row_bcast:15 row_mask:0xa bank_mask:0xf
	s_nop 1
	v_add_f32_dpp v180, v180, v180 row_bcast:31 row_mask:0xc bank_mask:0xf
	s_nop 0
	v_readlane_b32 s20, v180, 63
	s_nop 1
	v_mov_b32_e32 v185, s20
	v_fma_f32 v185, v185, v2, v4
	v_rsq_f32_e32 v185, v185
	s_nop 0
	v_mul_f32_e32 v104, v104, v185
	v_mul_f32_e32 v105, v105, v185
	v_mul_f32_e32 v106, v106, v185
	v_mul_f32_e32 v107, v107, v185
	v_mul_f32_e32 v108, v108, v185
	v_mul_f32_e32 v109, v109, v185
	v_mul_f32_e32 v110, v110, v185
	v_mul_f32_e32 v111, v111, v185
	v_mul_f32_e32 v112, v112, v185
	v_mul_f32_e32 v113, v113, v185
	v_mul_f32_e32 v114, v114, v185
	v_mul_f32_e32 v115, v115, v185
	v_mul_f32_e32 v116, v116, v185
	v_mul_f32_e32 v117, v117, v185
	v_mul_f32_e32 v118, v118, v185
	v_mul_f32_e32 v119, v119, v185
	v_fma_f32 v104, v104, v8, v24
	v_fma_f32 v105, v105, v9, v25
	v_fma_f32 v106, v106, v10, v26
	v_fma_f32 v107, v107, v11, v27
	v_fma_f32 v108, v108, v12, v28
	v_fma_f32 v109, v109, v13, v29
	v_fma_f32 v110, v110, v14, v30
	v_fma_f32 v111, v111, v15, v31
	v_fma_f32 v112, v112, v16, v32
	v_fma_f32 v113, v113, v17, v33
	v_fma_f32 v114, v114, v18, v34
	v_fma_f32 v115, v115, v19, v35
	v_fma_f32 v116, v116, v20, v36
	v_fma_f32 v117, v117, v21, v37
	v_fma_f32 v118, v118, v22, v38
	v_fma_f32 v119, v119, v23, v39
	v_cvt_pk_bf16_f32 v104, v104, v105
	v_cvt_pk_bf16_f32 v105, v106, v107
	v_cvt_pk_bf16_f32 v108, v108, v109
	v_cvt_pk_bf16_f32 v109, v110, v111
	v_cvt_pk_bf16_f32 v112, v112, v113
	v_cvt_pk_bf16_f32 v113, v114, v115
	v_cvt_pk_bf16_f32 v116, v116, v117
	v_cvt_pk_bf16_f32 v117, v118, v119
	v_add_u32_e32 v171, 0xc00000, v5
	global_store_dwordx2 v171, v[104:105], s[8:9]
	global_store_dwordx2 v171, v[108:109], s[8:9] offset:512
	global_store_dwordx2 v171, v[112:113], s[8:9] offset:1024
	global_store_dwordx2 v171, v[116:117], s[8:9] offset:1536
	v_mov_b32_e32 v172, 0xc000
	s_mov_b64 exec, 1
	global_store_dwordx2 v172, v[184:185], s[38:39]
	s_mov_b64 exec, -1
	s_waitcnt vmcnt(45)
	v_add_f32_e32 v180, v120, v121
	v_add_f32_e32 v181, v124, v125
	v_add_f32_e32 v182, v128, v129
	v_add_f32_e32 v183, v132, v133
	v_add_f32_e32 v180, v180, v122
	v_add_f32_e32 v181, v181, v126
	v_add_f32_e32 v182, v182, v130
	v_add_f32_e32 v183, v183, v134
	v_add_f32_e32 v180, v180, v123
	v_add_f32_e32 v181, v181, v127
	v_add_f32_e32 v182, v182, v131
	v_add_f32_e32 v183, v183, v135
	v_add_f32_e32 v180, v180, v181
	v_add_f32_e32 v182, v182, v183
	v_add_f32_e32 v180, v180, v182
	s_nop 1
	v_add_f32_dpp v180, v180, v180 quad_perm:[1,0,3,2] row_mask:0xf bank_mask:0xf
	s_nop 1
	v_add_f32_dpp v180, v180, v180 quad_perm:[2,3,0,1] row_mask:0xf bank_mask:0xf
	s_nop 1
	v_add_f32_dpp v180, v180, v180 row_half_mirror row_mask:0xf bank_mask:0xf
	s_nop 1
	v_add_f32_dpp v180, v180, v180 row_mirror row_mask:0xf bank_mask:0xf
	s_nop 1
	v_add_f32_dpp v180, v180, v180 row_bcast:15 row_mask:0xa bank_mask:0xf
	s_nop 1
	v_add_f32_dpp v180, v180, v180 row_bcast:31 row_mask:0xc bank_mask:0xf
	s_nop 0
	v_readlane_b32 s20, v180, 63
	s_nop 1
	v_mul_f32_e32 v184, s20, v2
	v_sub_f32_e32 v120, v120, v184
	v_sub_f32_e32 v121, v121, v184
	v_sub_f32_e32 v122, v122, v184
	v_sub_f32_e32 v123, v123, v184
	v_sub_f32_e32 v124, v124, v184
	v_sub_f32_e32 v125, v125, v184
	v_sub_f32_e32 v126, v126, v184
	v_sub_f32_e32 v127, v127, v184
	v_sub_f32_e32 v128, v128, v184
	v_sub_f32_e32 v129, v129, v184
	v_sub_f32_e32 v130, v130, v184
	v_sub_f32_e32 v131, v131, v184
	v_sub_f32_e32 v132, v132, v184
	v_sub_f32_e32 v133, v133, v184
	v_sub_f32_e32 v134, v134, v184
	v_sub_f32_e32 v135, v135, v184
	v_mul_f32_e32 v180, v120, v120
	v_mul_f32_e32 v181, v124, v124
	v_mul_f32_e32 v182, v128, v128
	v_mul_f32_e32 v183, v132, v132
	v_fmac_f32_e32 v180, v121, v121
	v_fmac_f32_e32 v181, v125, v125
	v_fmac_f32_e32 v182, v129, v129
	v_fmac_f32_e32 v183, v133, v133
	v_fmac_f32_e32 v180, v122, v122
	v_fmac_f32_e32 v181, v126, v126
	v_fmac_f32_e32 v182, v130, v130
	v_fmac_f32_e32 v183, v134, v134
	v_fmac_f32_e32 v180, v123, v123
	v_fmac_f32_e32 v181, v127, v127
	v_fmac_f32_e32 v182, v131, v131
	v_fmac_f32_e32 v183, v135, v135
	v_add_f32_e32 v180, v180, v181
	v_add_f32_e32 v182, v182, v183
	v_add_f32_e32 v180, v180, v182
	s_nop 1
	v_add_f32_dpp v180, v180, v180 quad_perm:[1,0,3,2] row_mask:0xf bank_mask:0xf
	s_nop 1
	v_add_f32_dpp v180, v180, v180 quad_perm:[2,3,0,1] row_mask:0xf bank_mask:0xf
	s_nop 1
	v_add_f32_dpp v180, v180, v180 row_half_mirror row_mask:0xf bank_mask:0xf
	s_nop 1
	v_add_f32_dpp v180, v180, v180 row_mirror row_mask:0xf bank_mask:0xf
	s_nop 1
	v_add_f32_dpp v180, v180, v180 row_bcast:15 row_mask:0xa bank_mask:0xf
	s_nop 1
	v_add_f32_dpp v180, v180, v180 row_bcast:31 row_mask:0xc bank_mask:0xf
	s_nop 0
	v_readlane_b32 s20, v180, 63
	s_nop 1
	v_mov_b32_e32 v185, s20
	v_fma_f32 v185, v185, v2, v4
	v_rsq_f32_e32 v185, v185
	s_nop 0
	v_mul_f32_e32 v120, v120, v185
	v_mul_f32_e32 v121, v121, v185
	v_mul_f32_e32 v122, v122, v185
	v_mul_f32_e32 v123, v123, v185
	v_mul_f32_e32 v124, v124, v185
	v_mul_f32_e32 v125, v125, v185
	v_mul_f32_e32 v126, v126, v185
	v_mul_f32_e32 v127, v127, v185
	v_mul_f32_e32 v128, v128, v185
	v_mul_f32_e32 v129, v129, v185
	v_mul_f32_e32 v130, v130, v185
	v_mul_f32_e32 v131, v131, v185
	v_mul_f32_e32 v132, v132, v185
	v_mul_f32_e32 v133, v133, v185
	v_mul_f32_e32 v134, v134, v185
	v_mul_f32_e32 v135, v135, v185
	v_fma_f32 v120, v120, v8, v24
	v_fma_f32 v121, v121, v9, v25
	v_fma_f32 v122, v122, v10, v26
	v_fma_f32 v123, v123, v11, v27
	v_fma_f32 v124, v124, v12, v28
	v_fma_f32 v125, v125, v13, v29
	v_fma_f32 v126, v126, v14, v30
	v_fma_f32 v127, v127, v15, v31
	v_fma_f32 v128, v128, v16, v32
	v_fma_f32 v129, v129, v17, v33
	v_fma_f32 v130, v130, v18, v34
	v_fma_f32 v131, v131, v19, v35
	v_fma_f32 v132, v132, v20, v36
	v_fma_f32 v133, v133, v21, v37
	v_fma_f32 v134, v134, v22, v38
	v_fma_f32 v135, v135, v23, v39
	v_cvt_pk_bf16_f32 v120, v120, v121
	v_cvt_pk_bf16_f32 v121, v122, v123
	v_cvt_pk_bf16_f32 v124, v124, v125
	v_cvt_pk_bf16_f32 v125, v126, v127
	v_cvt_pk_bf16_f32 v128, v128, v129
	v_cvt_pk_bf16_f32 v129, v130, v131
	v_cvt_pk_bf16_f32 v132, v132, v133
	v_cvt_pk_bf16_f32 v133, v134, v135
	v_add_u32_e32 v171, 0xf00000, v5
	global_store_dwordx2 v171, v[120:121], s[8:9]
	global_store_dwordx2 v171, v[124:125], s[8:9] offset:512
	global_store_dwordx2 v171, v[128:129], s[8:9] offset:1024
	global_store_dwordx2 v171, v[132:133], s[8:9] offset:1536
	v_mov_b32_e32 v172, 0xf000
	s_mov_b64 exec, 1
	global_store_dwordx2 v172, v[184:185], s[38:39]
	s_mov_b64 exec, -1
	s_waitcnt vmcnt(46)
	v_add_f32_e32 v180, v136, v137
	v_add_f32_e32 v181, v140, v141
	v_add_f32_e32 v182, v144, v145
	v_add_f32_e32 v183, v148, v149
	v_add_f32_e32 v180, v180, v138
	v_add_f32_e32 v181, v181, v142
	v_add_f32_e32 v182, v182, v146
	v_add_f32_e32 v183, v183, v150
	v_add_f32_e32 v180, v180, v139
	v_add_f32_e32 v181, v181, v143
	v_add_f32_e32 v182, v182, v147
	v_add_f32_e32 v183, v183, v151
	v_add_f32_e32 v180, v180, v181
	v_add_f32_e32 v182, v182, v183
	v_add_f32_e32 v180, v180, v182
	s_nop 1
	v_add_f32_dpp v180, v180, v180 quad_perm:[1,0,3,2] row_mask:0xf bank_mask:0xf
	s_nop 1
	v_add_f32_dpp v180, v180, v180 quad_perm:[2,3,0,1] row_mask:0xf bank_mask:0xf
	s_nop 1
	v_add_f32_dpp v180, v180, v180 row_half_mirror row_mask:0xf bank_mask:0xf
	s_nop 1
	v_add_f32_dpp v180, v180, v180 row_mirror row_mask:0xf bank_mask:0xf
	s_nop 1
	v_add_f32_dpp v180, v180, v180 row_bcast:15 row_mask:0xa bank_mask:0xf
	s_nop 1
	v_add_f32_dpp v180, v180, v180 row_bcast:31 row_mask:0xc bank_mask:0xf
	s_nop 0
	v_readlane_b32 s20, v180, 63
	s_nop 1
	v_mul_f32_e32 v184, s20, v2
	v_sub_f32_e32 v136, v136, v184
	v_sub_f32_e32 v137, v137, v184
	v_sub_f32_e32 v138, v138, v184
	v_sub_f32_e32 v139, v139, v184
	v_sub_f32_e32 v140, v140, v184
	v_sub_f32_e32 v141, v141, v184
	v_sub_f32_e32 v142, v142, v184
	v_sub_f32_e32 v143, v143, v184
	v_sub_f32_e32 v144, v144, v184
	v_sub_f32_e32 v145, v145, v184
	v_sub_f32_e32 v146, v146, v184
	v_sub_f32_e32 v147, v147, v184
	v_sub_f32_e32 v148, v148, v184
	v_sub_f32_e32 v149, v149, v184
	v_sub_f32_e32 v150, v150, v184
	v_sub_f32_e32 v151, v151, v184
	v_mul_f32_e32 v180, v136, v136
	v_mul_f32_e32 v181, v140, v140
	v_mul_f32_e32 v182, v144, v144
	v_mul_f32_e32 v183, v148, v148
	v_fmac_f32_e32 v180, v137, v137
	v_fmac_f32_e32 v181, v141, v141
	v_fmac_f32_e32 v182, v145, v145
	v_fmac_f32_e32 v183, v149, v149
	v_fmac_f32_e32 v180, v138, v138
	v_fmac_f32_e32 v181, v142, v142
	v_fmac_f32_e32 v182, v146, v146
	v_fmac_f32_e32 v183, v150, v150
	v_fmac_f32_e32 v180, v139, v139
	v_fmac_f32_e32 v181, v143, v143
	v_fmac_f32_e32 v182, v147, v147
	v_fmac_f32_e32 v183, v151, v151
	v_add_f32_e32 v180, v180, v181
	v_add_f32_e32 v182, v182, v183
	v_add_f32_e32 v180, v180, v182
	s_nop 1
	v_add_f32_dpp v180, v180, v180 quad_perm:[1,0,3,2] row_mask:0xf bank_mask:0xf
	s_nop 1
	v_add_f32_dpp v180, v180, v180 quad_perm:[2,3,0,1] row_mask:0xf bank_mask:0xf
	s_nop 1
	v_add_f32_dpp v180, v180, v180 row_half_mirror row_mask:0xf bank_mask:0xf
	s_nop 1
	v_add_f32_dpp v180, v180, v180 row_mirror row_mask:0xf bank_mask:0xf
	s_nop 1
	v_add_f32_dpp v180, v180, v180 row_bcast:15 row_mask:0xa bank_mask:0xf
	s_nop 1
	v_add_f32_dpp v180, v180, v180 row_bcast:31 row_mask:0xc bank_mask:0xf
	s_nop 0
	v_readlane_b32 s20, v180, 63
	s_nop 1
	v_mov_b32_e32 v185, s20
	v_fma_f32 v185, v185, v2, v4
	v_rsq_f32_e32 v185, v185
	s_nop 0
	v_mul_f32_e32 v136, v136, v185
	v_mul_f32_e32 v137, v137, v185
	v_mul_f32_e32 v138, v138, v185
	v_mul_f32_e32 v139, v139, v185
	v_mul_f32_e32 v140, v140, v185
	v_mul_f32_e32 v141, v141, v185
	v_mul_f32_e32 v142, v142, v185
	v_mul_f32_e32 v143, v143, v185
	v_mul_f32_e32 v144, v144, v185
	v_mul_f32_e32 v145, v145, v185
	v_mul_f32_e32 v146, v146, v185
	v_mul_f32_e32 v147, v147, v185
	v_mul_f32_e32 v148, v148, v185
	v_mul_f32_e32 v149, v149, v185
	v_mul_f32_e32 v150, v150, v185
	v_mul_f32_e32 v151, v151, v185
	v_fma_f32 v136, v136, v8, v24
	v_fma_f32 v137, v137, v9, v25
	v_fma_f32 v138, v138, v10, v26
	v_fma_f32 v139, v139, v11, v27
	v_fma_f32 v140, v140, v12, v28
	v_fma_f32 v141, v141, v13, v29
	v_fma_f32 v142, v142, v14, v30
	v_fma_f32 v143, v143, v15, v31
	v_fma_f32 v144, v144, v16, v32
	v_fma_f32 v145, v145, v17, v33
	v_fma_f32 v146, v146, v18, v34
	v_fma_f32 v147, v147, v19, v35
	v_fma_f32 v148, v148, v20, v36
	v_fma_f32 v149, v149, v21, v37
	v_fma_f32 v150, v150, v22, v38
	v_fma_f32 v151, v151, v23, v39
	v_cvt_pk_bf16_f32 v136, v136, v137
	v_cvt_pk_bf16_f32 v137, v138, v139
	v_cvt_pk_bf16_f32 v140, v140, v141
	v_cvt_pk_bf16_f32 v141, v142, v143
	v_cvt_pk_bf16_f32 v144, v144, v145
	v_cvt_pk_bf16_f32 v145, v146, v147
	v_cvt_pk_bf16_f32 v148, v148, v149
	v_cvt_pk_bf16_f32 v149, v150, v151
	v_add_u32_e32 v171, 0x1200000, v5
	global_store_dwordx2 v171, v[136:137], s[8:9]
	global_store_dwordx2 v171, v[140:141], s[8:9] offset:512
	global_store_dwordx2 v171, v[144:145], s[8:9] offset:1024
	global_store_dwordx2 v171, v[148:149], s[8:9] offset:1536
	v_mov_b32_e32 v172, 0x12000
	s_mov_b64 exec, 1
	global_store_dwordx2 v172, v[184:185], s[38:39]
	s_mov_b64 exec, -1
	s_waitcnt vmcnt(47)
	v_add_f32_e32 v180, v152, v153
	v_add_f32_e32 v181, v156, v157
	v_add_f32_e32 v182, v160, v161
	v_add_f32_e32 v183, v164, v165
	v_add_f32_e32 v180, v180, v154
	v_add_f32_e32 v181, v181, v158
	v_add_f32_e32 v182, v182, v162
	v_add_f32_e32 v183, v183, v166
	v_add_f32_e32 v180, v180, v155
	v_add_f32_e32 v181, v181, v159
	v_add_f32_e32 v182, v182, v163
	v_add_f32_e32 v183, v183, v167
	v_add_f32_e32 v180, v180, v181
	v_add_f32_e32 v182, v182, v183
	v_add_f32_e32 v180, v180, v182
	s_nop 1
	v_add_f32_dpp v180, v180, v180 quad_perm:[1,0,3,2] row_mask:0xf bank_mask:0xf
	s_nop 1
	v_add_f32_dpp v180, v180, v180 quad_perm:[2,3,0,1] row_mask:0xf bank_mask:0xf
	s_nop 1
	v_add_f32_dpp v180, v180, v180 row_half_mirror row_mask:0xf bank_mask:0xf
	s_nop 1
	v_add_f32_dpp v180, v180, v180 row_mirror row_mask:0xf bank_mask:0xf
	s_nop 1
	v_add_f32_dpp v180, v180, v180 row_bcast:15 row_mask:0xa bank_mask:0xf
	s_nop 1
	v_add_f32_dpp v180, v180, v180 row_bcast:31 row_mask:0xc bank_mask:0xf
	s_nop 0
	v_readlane_b32 s20, v180, 63
	s_nop 1
	v_mul_f32_e32 v184, s20, v2
	v_sub_f32_e32 v152, v152, v184
	v_sub_f32_e32 v153, v153, v184
	v_sub_f32_e32 v154, v154, v184
	v_sub_f32_e32 v155, v155, v184
	v_sub_f32_e32 v156, v156, v184
	v_sub_f32_e32 v157, v157, v184
	v_sub_f32_e32 v158, v158, v184
	v_sub_f32_e32 v159, v159, v184
	v_sub_f32_e32 v160, v160, v184
	v_sub_f32_e32 v161, v161, v184
	v_sub_f32_e32 v162, v162, v184
	v_sub_f32_e32 v163, v163, v184
	v_sub_f32_e32 v164, v164, v184
	v_sub_f32_e32 v165, v165, v184
	v_sub_f32_e32 v166, v166, v184
	v_sub_f32_e32 v167, v167, v184
	v_mul_f32_e32 v180, v152, v152
	v_mul_f32_e32 v181, v156, v156
	v_mul_f32_e32 v182, v160, v160
	v_mul_f32_e32 v183, v164, v164
	v_fmac_f32_e32 v180, v153, v153
	v_fmac_f32_e32 v181, v157, v157
	v_fmac_f32_e32 v182, v161, v161
	v_fmac_f32_e32 v183, v165, v165
	v_fmac_f32_e32 v180, v154, v154
	v_fmac_f32_e32 v181, v158, v158
	v_fmac_f32_e32 v182, v162, v162
	v_fmac_f32_e32 v183, v166, v166
	v_fmac_f32_e32 v180, v155, v155
	v_fmac_f32_e32 v181, v159, v159
	v_fmac_f32_e32 v182, v163, v163
	v_fmac_f32_e32 v183, v167, v167
	v_add_f32_e32 v180, v180, v181
	v_add_f32_e32 v182, v182, v183
	v_add_f32_e32 v180, v180, v182
	s_nop 1
	v_add_f32_dpp v180, v180, v180 quad_perm:[1,0,3,2] row_mask:0xf bank_mask:0xf
	s_nop 1
	v_add_f32_dpp v180, v180, v180 quad_perm:[2,3,0,1] row_mask:0xf bank_mask:0xf
	s_nop 1
	v_add_f32_dpp v180, v180, v180 row_half_mirror row_mask:0xf bank_mask:0xf
	s_nop 1
	v_add_f32_dpp v180, v180, v180 row_mirror row_mask:0xf bank_mask:0xf
	s_nop 1
	v_add_f32_dpp v180, v180, v180 row_bcast:15 row_mask:0xa bank_mask:0xf
	s_nop 1
	v_add_f32_dpp v180, v180, v180 row_bcast:31 row_mask:0xc bank_mask:0xf
	s_nop 0
	v_readlane_b32 s20, v180, 63
	s_nop 1
	v_mov_b32_e32 v185, s20
	v_fma_f32 v185, v185, v2, v4
	v_rsq_f32_e32 v185, v185
	s_nop 0
	v_mul_f32_e32 v152, v152, v185
	v_mul_f32_e32 v153, v153, v185
	v_mul_f32_e32 v154, v154, v185
	v_mul_f32_e32 v155, v155, v185
	v_mul_f32_e32 v156, v156, v185
	v_mul_f32_e32 v157, v157, v185
	v_mul_f32_e32 v158, v158, v185
	v_mul_f32_e32 v159, v159, v185
	v_mul_f32_e32 v160, v160, v185
	v_mul_f32_e32 v161, v161, v185
	v_mul_f32_e32 v162, v162, v185
	v_mul_f32_e32 v163, v163, v185
	v_mul_f32_e32 v164, v164, v185
	v_mul_f32_e32 v165, v165, v185
	v_mul_f32_e32 v166, v166, v185
	v_mul_f32_e32 v167, v167, v185
	v_fma_f32 v152, v152, v8, v24
	v_fma_f32 v153, v153, v9, v25
	v_fma_f32 v154, v154, v10, v26
	v_fma_f32 v155, v155, v11, v27
	v_fma_f32 v156, v156, v12, v28
	v_fma_f32 v157, v157, v13, v29
	v_fma_f32 v158, v158, v14, v30
	v_fma_f32 v159, v159, v15, v31
	v_fma_f32 v160, v160, v16, v32
	v_fma_f32 v161, v161, v17, v33
	v_fma_f32 v162, v162, v18, v34
	v_fma_f32 v163, v163, v19, v35
	v_fma_f32 v164, v164, v20, v36
	v_fma_f32 v165, v165, v21, v37
	v_fma_f32 v166, v166, v22, v38
	v_fma_f32 v167, v167, v23, v39
	v_cvt_pk_bf16_f32 v152, v152, v153
	v_cvt_pk_bf16_f32 v153, v154, v155
	v_cvt_pk_bf16_f32 v156, v156, v157
	v_cvt_pk_bf16_f32 v157, v158, v159
	v_cvt_pk_bf16_f32 v160, v160, v161
	v_cvt_pk_bf16_f32 v161, v162, v163
	v_cvt_pk_bf16_f32 v164, v164, v165
	v_cvt_pk_bf16_f32 v165, v166, v167
	v_add_u32_e32 v171, 0x1500000, v5
	global_store_dwordx2 v171, v[152:153], s[8:9]
	global_store_dwordx2 v171, v[156:157], s[8:9] offset:512
	global_store_dwordx2 v171, v[160:161], s[8:9] offset:1024
	global_store_dwordx2 v171, v[164:165], s[8:9] offset:1536
	v_mov_b32_e32 v172, 0x15000
	s_mov_b64 exec, 1
	global_store_dwordx2 v172, v[184:185], s[38:39]
	s_mov_b64 exec, -1
	s_waitcnt vmcnt(43)
	v_add_f32_e32 v180, v40, v41
	v_add_f32_e32 v181, v44, v45
	v_add_f32_e32 v182, v48, v49
	v_add_f32_e32 v183, v52, v53
	v_add_f32_e32 v180, v180, v42
	v_add_f32_e32 v181, v181, v46
	v_add_f32_e32 v182, v182, v50
	v_add_f32_e32 v183, v183, v54
	v_add_f32_e32 v180, v180, v43
	v_add_f32_e32 v181, v181, v47
	v_add_f32_e32 v182, v182, v51
	v_add_f32_e32 v183, v183, v55
	v_add_f32_e32 v180, v180, v181
	v_add_f32_e32 v182, v182, v183
	v_add_f32_e32 v180, v180, v182
	s_nop 1
	v_add_f32_dpp v180, v180, v180 quad_perm:[1,0,3,2] row_mask:0xf bank_mask:0xf
	s_nop 1
	v_add_f32_dpp v180, v180, v180 quad_perm:[2,3,0,1] row_mask:0xf bank_mask:0xf
	s_nop 1
	v_add_f32_dpp v180, v180, v180 row_half_mirror row_mask:0xf bank_mask:0xf
	s_nop 1
	v_add_f32_dpp v180, v180, v180 row_mirror row_mask:0xf bank_mask:0xf
	s_nop 1
	v_add_f32_dpp v180, v180, v180 row_bcast:15 row_mask:0xa bank_mask:0xf
	s_nop 1
	v_add_f32_dpp v180, v180, v180 row_bcast:31 row_mask:0xc bank_mask:0xf
	s_nop 0
	v_readlane_b32 s20, v180, 63
	s_nop 1
	v_mul_f32_e32 v184, s20, v2
	v_sub_f32_e32 v40, v40, v184
	v_sub_f32_e32 v41, v41, v184
	v_sub_f32_e32 v42, v42, v184
	v_sub_f32_e32 v43, v43, v184
	v_sub_f32_e32 v44, v44, v184
	v_sub_f32_e32 v45, v45, v184
	v_sub_f32_e32 v46, v46, v184
	v_sub_f32_e32 v47, v47, v184
	v_sub_f32_e32 v48, v48, v184
	v_sub_f32_e32 v49, v49, v184
	v_sub_f32_e32 v50, v50, v184
	v_sub_f32_e32 v51, v51, v184
	v_sub_f32_e32 v52, v52, v184
	v_sub_f32_e32 v53, v53, v184
	v_sub_f32_e32 v54, v54, v184
	v_sub_f32_e32 v55, v55, v184
	v_mul_f32_e32 v180, v40, v40
	v_mul_f32_e32 v181, v44, v44
	v_mul_f32_e32 v182, v48, v48
	v_mul_f32_e32 v183, v52, v52
	v_fmac_f32_e32 v180, v41, v41
	v_fmac_f32_e32 v181, v45, v45
	v_fmac_f32_e32 v182, v49, v49
	v_fmac_f32_e32 v183, v53, v53
	v_fmac_f32_e32 v180, v42, v42
	v_fmac_f32_e32 v181, v46, v46
	v_fmac_f32_e32 v182, v50, v50
	v_fmac_f32_e32 v183, v54, v54
	v_fmac_f32_e32 v180, v43, v43
	v_fmac_f32_e32 v181, v47, v47
	v_fmac_f32_e32 v182, v51, v51
	v_fmac_f32_e32 v183, v55, v55
	v_add_f32_e32 v180, v180, v181
	v_add_f32_e32 v182, v182, v183
	v_add_f32_e32 v180, v180, v182
	s_nop 1
	v_add_f32_dpp v180, v180, v180 quad_perm:[1,0,3,2] row_mask:0xf bank_mask:0xf
	s_nop 1
	v_add_f32_dpp v180, v180, v180 quad_perm:[2,3,0,1] row_mask:0xf bank_mask:0xf
	s_nop 1
	v_add_f32_dpp v180, v180, v180 row_half_mirror row_mask:0xf bank_mask:0xf
	s_nop 1
	v_add_f32_dpp v180, v180, v180 row_mirror row_mask:0xf bank_mask:0xf
	s_nop 1
	v_add_f32_dpp v180, v180, v180 row_bcast:15 row_mask:0xa bank_mask:0xf
	s_nop 1
	v_add_f32_dpp v180, v180, v180 row_bcast:31 row_mask:0xc bank_mask:0xf
	s_nop 0
	v_readlane_b32 s20, v180, 63
	s_nop 1
	v_mov_b32_e32 v185, s20
	v_fma_f32 v185, v185, v2, v4
	v_rsq_f32_e32 v185, v185
	s_nop 0
	v_mul_f32_e32 v40, v40, v185
	v_mul_f32_e32 v41, v41, v185
	v_mul_f32_e32 v42, v42, v185
	v_mul_f32_e32 v43, v43, v185
	v_mul_f32_e32 v44, v44, v185
	v_mul_f32_e32 v45, v45, v185
	v_mul_f32_e32 v46, v46, v185
	v_mul_f32_e32 v47, v47, v185
	v_mul_f32_e32 v48, v48, v185
	v_mul_f32_e32 v49, v49, v185
	v_mul_f32_e32 v50, v50, v185
	v_mul_f32_e32 v51, v51, v185
	v_mul_f32_e32 v52, v52, v185
	v_mul_f32_e32 v53, v53, v185
	v_mul_f32_e32 v54, v54, v185
	v_mul_f32_e32 v55, v55, v185
	v_fma_f32 v40, v40, v8, v24
	v_fma_f32 v41, v41, v9, v25
	v_fma_f32 v42, v42, v10, v26
	v_fma_f32 v43, v43, v11, v27
	v_fma_f32 v44, v44, v12, v28
	v_fma_f32 v45, v45, v13, v29
	v_fma_f32 v46, v46, v14, v30
	v_fma_f32 v47, v47, v15, v31
	v_fma_f32 v48, v48, v16, v32
	v_fma_f32 v49, v49, v17, v33
	v_fma_f32 v50, v50, v18, v34
	v_fma_f32 v51, v51, v19, v35
	v_fma_f32 v52, v52, v20, v36
	v_fma_f32 v53, v53, v21, v37
	v_fma_f32 v54, v54, v22, v38
	v_fma_f32 v55, v55, v23, v39
	v_cvt_pk_bf16_f32 v40, v40, v41
	v_cvt_pk_bf16_f32 v41, v42, v43
	v_cvt_pk_bf16_f32 v44, v44, v45
	v_cvt_pk_bf16_f32 v45, v46, v47
	v_cvt_pk_bf16_f32 v48, v48, v49
	v_cvt_pk_bf16_f32 v49, v50, v51
	v_cvt_pk_bf16_f32 v52, v52, v53
	v_cvt_pk_bf16_f32 v53, v54, v55
	v_add_u32_e32 v171, 0x1800000, v5
	global_store_dwordx2 v171, v[40:41], s[8:9]
	global_store_dwordx2 v171, v[44:45], s[8:9] offset:512
	global_store_dwordx2 v171, v[48:49], s[8:9] offset:1024
	global_store_dwordx2 v171, v[52:53], s[8:9] offset:1536
	v_mov_b32_e32 v172, 0x18000
	s_mov_b64 exec, 1
	global_store_dwordx2 v172, v[184:185], s[38:39]
	s_mov_b64 exec, -1
	s_waitcnt vmcnt(39)
	v_add_f32_e32 v180, v56, v57
	v_add_f32_e32 v181, v60, v61
	v_add_f32_e32 v182, v64, v65
	v_add_f32_e32 v183, v68, v69
	v_add_f32_e32 v180, v180, v58
	v_add_f32_e32 v181, v181, v62
	v_add_f32_e32 v182, v182, v66
	v_add_f32_e32 v183, v183, v70
	v_add_f32_e32 v180, v180, v59
	v_add_f32_e32 v181, v181, v63
	v_add_f32_e32 v182, v182, v67
	v_add_f32_e32 v183, v183, v71
	v_add_f32_e32 v180, v180, v181
	v_add_f32_e32 v182, v182, v183
	v_add_f32_e32 v180, v180, v182
	s_nop 1
	v_add_f32_dpp v180, v180, v180 quad_perm:[1,0,3,2] row_mask:0xf bank_mask:0xf
	s_nop 1
	v_add_f32_dpp v180, v180, v180 quad_perm:[2,3,0,1] row_mask:0xf bank_mask:0xf
	s_nop 1
	v_add_f32_dpp v180, v180, v180 row_half_mirror row_mask:0xf bank_mask:0xf
	s_nop 1
	v_add_f32_dpp v180, v180, v180 row_mirror row_mask:0xf bank_mask:0xf
	s_nop 1
	v_add_f32_dpp v180, v180, v180 row_bcast:15 row_mask:0xa bank_mask:0xf
	s_nop 1
	v_add_f32_dpp v180, v180, v180 row_bcast:31 row_mask:0xc bank_mask:0xf
	s_nop 0
	v_readlane_b32 s20, v180, 63
	s_nop 1
	v_mul_f32_e32 v184, s20, v2
	v_sub_f32_e32 v56, v56, v184
	v_sub_f32_e32 v57, v57, v184
	v_sub_f32_e32 v58, v58, v184
	v_sub_f32_e32 v59, v59, v184
	v_sub_f32_e32 v60, v60, v184
	v_sub_f32_e32 v61, v61, v184
	v_sub_f32_e32 v62, v62, v184
	v_sub_f32_e32 v63, v63, v184
	v_sub_f32_e32 v64, v64, v184
	v_sub_f32_e32 v65, v65, v184
	v_sub_f32_e32 v66, v66, v184
	v_sub_f32_e32 v67, v67, v184
	v_sub_f32_e32 v68, v68, v184
	v_sub_f32_e32 v69, v69, v184
	v_sub_f32_e32 v70, v70, v184
	v_sub_f32_e32 v71, v71, v184
	v_mul_f32_e32 v180, v56, v56
	v_mul_f32_e32 v181, v60, v60
	v_mul_f32_e32 v182, v64, v64
	v_mul_f32_e32 v183, v68, v68
	v_fmac_f32_e32 v180, v57, v57
	v_fmac_f32_e32 v181, v61, v61
	v_fmac_f32_e32 v182, v65, v65
	v_fmac_f32_e32 v183, v69, v69
	v_fmac_f32_e32 v180, v58, v58
	v_fmac_f32_e32 v181, v62, v62
	v_fmac_f32_e32 v182, v66, v66
	v_fmac_f32_e32 v183, v70, v70
	v_fmac_f32_e32 v180, v59, v59
	v_fmac_f32_e32 v181, v63, v63
	v_fmac_f32_e32 v182, v67, v67
	v_fmac_f32_e32 v183, v71, v71
	v_add_f32_e32 v180, v180, v181
	v_add_f32_e32 v182, v182, v183
	v_add_f32_e32 v180, v180, v182
	s_nop 1
	v_add_f32_dpp v180, v180, v180 quad_perm:[1,0,3,2] row_mask:0xf bank_mask:0xf
	s_nop 1
	v_add_f32_dpp v180, v180, v180 quad_perm:[2,3,0,1] row_mask:0xf bank_mask:0xf
	s_nop 1
	v_add_f32_dpp v180, v180, v180 row_half_mirror row_mask:0xf bank_mask:0xf
	s_nop 1
	v_add_f32_dpp v180, v180, v180 row_mirror row_mask:0xf bank_mask:0xf
	s_nop 1
	v_add_f32_dpp v180, v180, v180 row_bcast:15 row_mask:0xa bank_mask:0xf
	s_nop 1
	v_add_f32_dpp v180, v180, v180 row_bcast:31 row_mask:0xc bank_mask:0xf
	s_nop 0
	v_readlane_b32 s20, v180, 63
	s_nop 1
	v_mov_b32_e32 v185, s20
	v_fma_f32 v185, v185, v2, v4
	v_rsq_f32_e32 v185, v185
	s_nop 0
	v_mul_f32_e32 v56, v56, v185
	v_mul_f32_e32 v57, v57, v185
	v_mul_f32_e32 v58, v58, v185
	v_mul_f32_e32 v59, v59, v185
	v_mul_f32_e32 v60, v60, v185
	v_mul_f32_e32 v61, v61, v185
	v_mul_f32_e32 v62, v62, v185
	v_mul_f32_e32 v63, v63, v185
	v_mul_f32_e32 v64, v64, v185
	v_mul_f32_e32 v65, v65, v185
	v_mul_f32_e32 v66, v66, v185
	v_mul_f32_e32 v67, v67, v185
	v_mul_f32_e32 v68, v68, v185
	v_mul_f32_e32 v69, v69, v185
	v_mul_f32_e32 v70, v70, v185
	v_mul_f32_e32 v71, v71, v185
	v_fma_f32 v56, v56, v8, v24
	v_fma_f32 v57, v57, v9, v25
	v_fma_f32 v58, v58, v10, v26
	v_fma_f32 v59, v59, v11, v27
	v_fma_f32 v60, v60, v12, v28
	v_fma_f32 v61, v61, v13, v29
	v_fma_f32 v62, v62, v14, v30
	v_fma_f32 v63, v63, v15, v31
	v_fma_f32 v64, v64, v16, v32
	v_fma_f32 v65, v65, v17, v33
	v_fma_f32 v66, v66, v18, v34
	v_fma_f32 v67, v67, v19, v35
	v_fma_f32 v68, v68, v20, v36
	v_fma_f32 v69, v69, v21, v37
	v_fma_f32 v70, v70, v22, v38
	v_fma_f32 v71, v71, v23, v39
	v_cvt_pk_bf16_f32 v56, v56, v57
	v_cvt_pk_bf16_f32 v57, v58, v59
	v_cvt_pk_bf16_f32 v60, v60, v61
	v_cvt_pk_bf16_f32 v61, v62, v63
	v_cvt_pk_bf16_f32 v64, v64, v65
	v_cvt_pk_bf16_f32 v65, v66, v67
	v_cvt_pk_bf16_f32 v68, v68, v69
	v_cvt_pk_bf16_f32 v69, v70, v71
	v_add_u32_e32 v171, 0x1b00000, v5
	global_store_dwordx2 v171, v[56:57], s[8:9]
	global_store_dwordx2 v171, v[60:61], s[8:9] offset:512
	global_store_dwordx2 v171, v[64:65], s[8:9] offset:1024
	global_store_dwordx2 v171, v[68:69], s[8:9] offset:1536
	v_mov_b32_e32 v172, 0x1b000
	s_mov_b64 exec, 1
	global_store_dwordx2 v172, v[184:185], s[38:39]
	s_mov_b64 exec, -1
	s_waitcnt vmcnt(35)
	v_add_f32_e32 v180, v72, v73
	v_add_f32_e32 v181, v76, v77
	v_add_f32_e32 v182, v80, v81
	v_add_f32_e32 v183, v84, v85
	v_add_f32_e32 v180, v180, v74
	v_add_f32_e32 v181, v181, v78
	v_add_f32_e32 v182, v182, v82
	v_add_f32_e32 v183, v183, v86
	v_add_f32_e32 v180, v180, v75
	v_add_f32_e32 v181, v181, v79
	v_add_f32_e32 v182, v182, v83
	v_add_f32_e32 v183, v183, v87
	v_add_f32_e32 v180, v180, v181
	v_add_f32_e32 v182, v182, v183
	v_add_f32_e32 v180, v180, v182
	s_nop 1
	v_add_f32_dpp v180, v180, v180 quad_perm:[1,0,3,2] row_mask:0xf bank_mask:0xf
	s_nop 1
	v_add_f32_dpp v180, v180, v180 quad_perm:[2,3,0,1] row_mask:0xf bank_mask:0xf
	s_nop 1
	v_add_f32_dpp v180, v180, v180 row_half_mirror row_mask:0xf bank_mask:0xf
	s_nop 1
	v_add_f32_dpp v180, v180, v180 row_mirror row_mask:0xf bank_mask:0xf
	s_nop 1
	v_add_f32_dpp v180, v180, v180 row_bcast:15 row_mask:0xa bank_mask:0xf
	s_nop 1
	v_add_f32_dpp v180, v180, v180 row_bcast:31 row_mask:0xc bank_mask:0xf
	s_nop 0
	v_readlane_b32 s20, v180, 63
	s_nop 1
	v_mul_f32_e32 v184, s20, v2
	v_sub_f32_e32 v72, v72, v184
	v_sub_f32_e32 v73, v73, v184
	v_sub_f32_e32 v74, v74, v184
	v_sub_f32_e32 v75, v75, v184
	v_sub_f32_e32 v76, v76, v184
	v_sub_f32_e32 v77, v77, v184
	v_sub_f32_e32 v78, v78, v184
	v_sub_f32_e32 v79, v79, v184
	v_sub_f32_e32 v80, v80, v184
	v_sub_f32_e32 v81, v81, v184
	v_sub_f32_e32 v82, v82, v184
	v_sub_f32_e32 v83, v83, v184
	v_sub_f32_e32 v84, v84, v184
	v_sub_f32_e32 v85, v85, v184
	v_sub_f32_e32 v86, v86, v184
	v_sub_f32_e32 v87, v87, v184
	v_mul_f32_e32 v180, v72, v72
	v_mul_f32_e32 v181, v76, v76
	v_mul_f32_e32 v182, v80, v80
	v_mul_f32_e32 v183, v84, v84
	v_fmac_f32_e32 v180, v73, v73
	v_fmac_f32_e32 v181, v77, v77
	v_fmac_f32_e32 v182, v81, v81
	v_fmac_f32_e32 v183, v85, v85
	v_fmac_f32_e32 v180, v74, v74
	v_fmac_f32_e32 v181, v78, v78
	v_fmac_f32_e32 v182, v82, v82
	v_fmac_f32_e32 v183, v86, v86
	v_fmac_f32_e32 v180, v75, v75
	v_fmac_f32_e32 v181, v79, v79
	v_fmac_f32_e32 v182, v83, v83
	v_fmac_f32_e32 v183, v87, v87
	v_add_f32_e32 v180, v180, v181
	v_add_f32_e32 v182, v182, v183
	v_add_f32_e32 v180, v180, v182
	s_nop 1
	v_add_f32_dpp v180, v180, v180 quad_perm:[1,0,3,2] row_mask:0xf bank_mask:0xf
	s_nop 1
	v_add_f32_dpp v180, v180, v180 quad_perm:[2,3,0,1] row_mask:0xf bank_mask:0xf
	s_nop 1
	v_add_f32_dpp v180, v180, v180 row_half_mirror row_mask:0xf bank_mask:0xf
	s_nop 1
	v_add_f32_dpp v180, v180, v180 row_mirror row_mask:0xf bank_mask:0xf
	s_nop 1
	v_add_f32_dpp v180, v180, v180 row_bcast:15 row_mask:0xa bank_mask:0xf
	s_nop 1
	v_add_f32_dpp v180, v180, v180 row_bcast:31 row_mask:0xc bank_mask:0xf
	s_nop 0
	v_readlane_b32 s20, v180, 63
	s_nop 1
	v_mov_b32_e32 v185, s20
	v_fma_f32 v185, v185, v2, v4
	v_rsq_f32_e32 v185, v185
	s_nop 0
	v_mul_f32_e32 v72, v72, v185
	v_mul_f32_e32 v73, v73, v185
	v_mul_f32_e32 v74, v74, v185
	v_mul_f32_e32 v75, v75, v185
	v_mul_f32_e32 v76, v76, v185
	v_mul_f32_e32 v77, v77, v185
	v_mul_f32_e32 v78, v78, v185
	v_mul_f32_e32 v79, v79, v185
	v_mul_f32_e32 v80, v80, v185
	v_mul_f32_e32 v81, v81, v185
	v_mul_f32_e32 v82, v82, v185
	v_mul_f32_e32 v83, v83, v185
	v_mul_f32_e32 v84, v84, v185
	v_mul_f32_e32 v85, v85, v185
	v_mul_f32_e32 v86, v86, v185
	v_mul_f32_e32 v87, v87, v185
	v_fma_f32 v72, v72, v8, v24
	v_fma_f32 v73, v73, v9, v25
	v_fma_f32 v74, v74, v10, v26
	v_fma_f32 v75, v75, v11, v27
	v_fma_f32 v76, v76, v12, v28
	v_fma_f32 v77, v77, v13, v29
	v_fma_f32 v78, v78, v14, v30
	v_fma_f32 v79, v79, v15, v31
	v_fma_f32 v80, v80, v16, v32
	v_fma_f32 v81, v81, v17, v33
	v_fma_f32 v82, v82, v18, v34
	v_fma_f32 v83, v83, v19, v35
	v_fma_f32 v84, v84, v20, v36
	v_fma_f32 v85, v85, v21, v37
	v_fma_f32 v86, v86, v22, v38
	v_fma_f32 v87, v87, v23, v39
	v_cvt_pk_bf16_f32 v72, v72, v73
	v_cvt_pk_bf16_f32 v73, v74, v75
	v_cvt_pk_bf16_f32 v76, v76, v77
	v_cvt_pk_bf16_f32 v77, v78, v79
	v_cvt_pk_bf16_f32 v80, v80, v81
	v_cvt_pk_bf16_f32 v81, v82, v83
	v_cvt_pk_bf16_f32 v84, v84, v85
	v_cvt_pk_bf16_f32 v85, v86, v87
	v_add_u32_e32 v171, 0x1e00000, v5
	global_store_dwordx2 v171, v[72:73], s[8:9]
	global_store_dwordx2 v171, v[76:77], s[8:9] offset:512
	global_store_dwordx2 v171, v[80:81], s[8:9] offset:1024
	global_store_dwordx2 v171, v[84:85], s[8:9] offset:1536
	v_mov_b32_e32 v172, 0x1e000
	s_mov_b64 exec, 1
	global_store_dwordx2 v172, v[184:185], s[38:39]
	s_mov_b64 exec, -1
	s_branch .LBB0_188

.LBB0_328:
	v_mbcnt_lo_u32_b32 v248, -1, 0
	v_mbcnt_hi_u32_b32 v248, -1, v248
	s_waitcnt vmcnt(0)
	v_mov_b64_e32 v[152:153], v[138:139]
	v_and_b32_e32 v228, 63, v248
	v_lshl_add_u32 v194, v228, 4, 0
	v_mov_b64_e32 v[150:151], v[136:137]
	ds_read_b128 v[136:139], v194
	ds_read_b128 v[154:157], v194 offset:1024
	ds_read_b128 v[158:161], v194 offset:8192
	v_and_b32_e32 v246, 15, v248
	s_add_i32 s8, s7, s20
	v_add_u32_e32 v0, s8, v246
	s_waitcnt lgkmcnt(2)
	v_mfma_f32_16x16x32_bf16 v[136:139], v[136:139], v[144:147], 0
	v_sub_u32_e32 v1, s11, v246
	v_cndmask_b32_e64 v0, v1, v0, s[38:39]
	v_add_u32_e32 v0, s10, v0
	s_waitcnt lgkmcnt(1)
	v_mfma_f32_16x16x32_bf16 v[188:191], v[154:157], v[140:143], v[136:139]
	v_mov_b64_e32 v[170:171], s[4:5]
	v_bfe_u32 v249, v248, 4, 2
	v_mad_i64_i32 v[0:1], s[8:9], v0, s62, v[170:171]
	ds_read_b128 v[136:139], v194 offset:9216
	v_lshlrev_b64 v[172:173], 1, v[208:209]
	v_lshl_add_u64 v[0:1], v[0:1], 0, v[172:173]
	v_lshlrev_b32_e32 v2, 3, v249
	s_waitcnt lgkmcnt(1)
	v_mfma_f32_16x16x32_bf16 v[154:157], v[158:161], v[132:135], 0
	ds_read_b128 v[158:161], v194 offset:2048
	v_lshl_add_u64 v[0:1], v[0:1], 0, v[2:3]
	v_lshl_add_u64 v[162:163], v[0:1], 0, s[16:17]
	v_add_co_u32_e32 v0, vcc, s19, v0
	s_waitcnt lgkmcnt(1)
	v_mfma_f32_16x16x32_bf16 v[154:157], v[136:139], v[150:153], v[154:157]
	v_addc_co_u32_e32 v1, vcc, 0, v1, vcc
	ds_read_b128 v[136:139], v194 offset:3072
	v_mov_b64_e32 v[192:193], v[202:203]
	v_mov_b64_e32 v[232:233], v[240:241]
	v_mov_b64_e32 v[148:149], v[242:243]

	v_mov_b64_e32 v[0:1], v[244:245]
	ds_read_b128 v[162:165], v194 offset:10240
	ds_read_b128 v[166:169], v194 offset:11264
	s_waitcnt lgkmcnt(3)
	v_mfma_f32_16x16x32_bf16 v[158:161], v[158:161], v[144:147], 0
	s_mov_b32 s21, s20
	s_add_i32 s20, s20, 16
	s_cmpk_eq_i32 s21, 0xf0
	s_waitcnt lgkmcnt(2)
	v_mfma_f32_16x16x32_bf16 v[180:183], v[136:139], v[140:143], v[158:161]
	s_cselect_b32 s8, s21, s20
	s_add_i32 s8, s8, s7
	s_nop 0
	ds_read_b128 v[158:161], v194 offset:4096
	s_waitcnt lgkmcnt(2)
	v_mfma_f32_16x16x32_bf16 v[136:139], v[162:165], v[132:135], 0
	v_or_b32_e32 v174, s8, v246
	v_xad_u32 v175, v174, -1, s58
	v_cndmask_b32_e64 v162, v175, v174, s[38:39]
	s_waitcnt lgkmcnt(1)
	v_mfma_f32_16x16x32_bf16 v[176:179], v[166:169], v[150:153], v[136:139]
	v_add_u32_e32 v162, s10, v162
	v_mad_i64_i32 v[184:185], s[8:9], v162, s62, v[170:171]
	s_nop 0
	ds_read_b128 v[136:139], v194 offset:5120
	ds_read_b128 v[162:165], v194 offset:12288
	s_waitcnt lgkmcnt(2)
	v_mfma_f32_16x16x32_bf16 v[158:161], v[158:161], v[144:147], 0
	v_lshl_add_u64 v[166:167], v[184:185], 0, v[172:173]
	v_lshl_add_u64 v[170:171], v[166:167], 0, v[2:3]
	ds_read_b128 v[166:169], v194 offset:13312
	s_waitcnt lgkmcnt(2)
	v_mfma_f32_16x16x32_bf16 v[172:175], v[136:139], v[140:143], v[158:161]
	v_lshl_add_u64 v[186:187], v[170:171], 0, s[22:23]
	s_nop 1
	ds_read_b128 v[158:161], v194 offset:6144
	v_add_co_u32_e32 v170, vcc, s31, v170
	s_waitcnt lgkmcnt(2)
	v_mfma_f32_16x16x32_bf16 v[136:139], v[162:165], v[132:135], 0
	v_addc_co_u32_e32 v171, vcc, 0, v171, vcc
	v_mov_b64_e32 v[198:199], v[216:217]
	v_mov_b64_e32 v[196:197], v[214:215]
	v_mov_b64_e32 v[204:205], v[212:213]
	v_mov_b64_e32 v[206:207], v[210:211]
	global_load_dwordx2 v[210:211], v[170:171], off offset:2048
	global_load_dwordx2 v[212:213], v[186:187], off offset:32
	global_load_dwordx2 v[214:215], v[186:187], off offset:64
	global_load_dwordx2 v[216:217], v[186:187], off offset:96
	global_load_dwordx2 v[202:203], v[186:187], off offset:2048
	global_load_dwordx2 v[240:241], v[186:187], off offset:2080
	global_load_dwordx2 v[242:243], v[186:187], off offset:2112
	global_load_dwordx2 v[244:245], v[186:187], off offset:2144
	ds_read_b128 v[162:165], v194 offset:7168
	s_waitcnt lgkmcnt(2)
	v_mfma_f32_16x16x32_bf16 v[168:171], v[166:169], v[150:153], v[136:139]
	v_lshl_add_u64 v[166:167], v[184:185], 0, s[96:97]
	v_and_b32_e32 v200, 48, v248
	v_mov_b32_e32 v201, v3
	s_waitcnt lgkmcnt(1)
	v_mfma_f32_16x16x32_bf16 v[136:139], v[158:161], v[144:147], 0
	ds_read_b128 v[144:147], v194 offset:14336
	v_lshl_add_u64 v[158:159], v[166:167], 0, v[200:201]
	v_add_co_u32_e32 v220, vcc, s64, v158
	v_add_u32_e32 v250, 0, v200
	v_lshl_add_u64 v[218:219], v[158:159], 0, s[24:25]
	s_waitcnt lgkmcnt(1)
	v_mfma_f32_16x16x32_bf16 v[164:167], v[162:165], v[140:143], v[136:139]
	v_addc_co_u32_e32 v221, vcc, 0, v159, vcc
	ds_read_b128 v[158:161], v194 offset:15360
	s_waitcnt lgkmcnt(1)
	v_mfma_f32_16x16x32_bf16 v[184:187], v[144:147], v[132:135], 0
	ds_read_b128 v[132:135], v250 offset:17664
	ds_read_b128 v[136:139], v250 offset:17728
	v_lshlrev_b32_e32 v194, 16, v206
	v_and_b32_e32 v195, 0xffff0000, v206
	v_lshlrev_b32_e32 v234, 16, v207
	v_and_b32_e32 v235, 0xffff0000, v207
	v_lshlrev_b32_e32 v162, 16, v204
	v_and_b32_e32 v163, 0xffff0000, v204
	v_lshlrev_b32_e32 v236, 16, v205
	v_and_b32_e32 v237, 0xffff0000, v205
	s_waitcnt lgkmcnt(1)
	v_mul_f32_e32 v226, v134, v234
	v_mul_f32_e32 v227, v135, v235
	v_mul_f32_e32 v238, v132, v194
	v_mul_f32_e32 v239, v133, v195
	s_waitcnt lgkmcnt(0)
	v_mul_f32_e32 v132, v138, v236
	v_mul_f32_e32 v133, v139, v237
	v_mul_f32_e32 v134, v136, v162
	v_mul_f32_e32 v135, v137, v163
	v_mul_f32_e32 v132, v132, v132
	v_mul_f32_e32 v133, v133, v133
	v_mul_f32_e32 v134, v134, v134
	v_mul_f32_e32 v135, v135, v135
	v_fma_f32 v140, v226, v226, v132
	v_fma_f32 v141, v227, v227, v133
	v_fma_f32 v142, v238, v238, v134
	v_fma_f32 v143, v239, v239, v135
	ds_read_b128 v[132:135], v250 offset:17792
	ds_read_b128 v[136:139], v250 offset:17856
	v_lshlrev_b32_e32 v222, 16, v196
	v_and_b32_e32 v223, 0xffff0000, v196
	v_lshlrev_b32_e32 v224, 16, v197
	v_and_b32_e32 v225, 0xffff0000, v197
	s_waitcnt lgkmcnt(1)
	v_mul_f32_e32 v134, v134, v224
	v_mul_f32_e32 v135, v135, v225
	v_mul_f32_e32 v132, v132, v222
	v_mul_f32_e32 v133, v133, v223
	v_lshlrev_b32_e32 v196, 16, v198
	v_and_b32_e32 v197, 0xffff0000, v198
	v_lshlrev_b32_e32 v198, 16, v199
	v_and_b32_e32 v199, 0xffff0000, v199
	v_fma_f32 v134, v134, v134, v140
	v_fma_f32 v135, v135, v135, v141
	v_fma_f32 v132, v132, v132, v142
	v_fma_f32 v133, v133, v133, v143
	s_waitcnt lgkmcnt(0)
	v_mul_f32_e32 v138, v138, v198
	v_mul_f32_e32 v139, v139, v199
	v_mul_f32_e32 v136, v136, v196
	v_mul_f32_e32 v137, v137, v197
	v_fma_f32 v134, v138, v138, v134
	v_fma_f32 v135, v139, v139, v135
	v_fma_f32 v132, v136, v136, v132
	v_fma_f32 v133, v137, v137, v133
	v_lshlrev_b32_e32 v204, 2, v228
	v_pk_mov_b32 v[136:137], v[132:133], v[134:135] op_sel:[1,0]
	v_mov_b32_e32 v133, v135
	v_add_f32_e32 v132, v136, v132
	v_add_f32_e32 v133, v137, v133
	v_mfma_f32_16x16x32_bf16 v[150:153], v[158:161], v[150:153], v[184:187]
	v_add_f32_e32 v201, v132, v133
	v_xor_b32_e32 v132, 64, v204
	ds_bpermute_b32 v205, v132, v201
	global_load_dwordx4 v[132:135], v[218:219], off offset:256
	global_load_dwordx4 v[140:143], v[218:219], off offset:64
	global_load_dwordx4 v[144:147], v[220:221], off
	global_load_dwordx4 v[136:139], v[218:219], off offset:320
	ds_read_b128 v[218:221], v250 offset:17152
	v_xor_b32_e32 v158, 0x80, v204
	v_cmp_eq_u32_e64 s[40:41], 15, v246
	s_waitcnt lgkmcnt(1)
	v_add_f32_e32 v229, v201, v205

	s_waitcnt lgkmcnt(0)
	v_add_f32_e32 v188, v188, v218
	v_exp_f32_e32 v188, v188
	v_add_f32_e32 v189, v189, v219
	v_exp_f32_e32 v189, v189
	v_add_f32_e32 v190, v190, v220
	v_add_f32_e32 v188, 1.0, v188
	v_rcp_f32_e32 v188, v188
	v_add_f32_e32 v189, 1.0, v189
	v_rcp_f32_e32 v189, v189
	v_exp_f32_e32 v190, v190
	v_mul_f32_e32 v188, 0xbf60028a, v188
	v_exp_f32_e32 v188, v188
	v_add_f32_e32 v191, v191, v221
	v_add_f32_e32 v190, 1.0, v190
	v_rcp_f32_e32 v190, v190

	v_mul_f32_dpp v188, v188, v188 row_shr:1 row_mask:0xf bank_mask:0xf

	v_exp_f32_e32 v191, v191
	ds_bpermute_b32 v230, v158, v229

	v_mul_f32_dpp v188, v188, v188 row_shr:2 row_mask:0xf bank_mask:0xf

	v_add_f32_e32 v191, 1.0, v191
	v_rcp_f32_e32 v191, v191

	v_mul_f32_dpp v188, v188, v188 row_shr:4 row_mask:0xf bank_mask:0xf

	ds_read_b128 v[184:187], v250 offset:17408
	ds_read_b128 v[158:161], v250 offset:17920

	v_mul_f32_dpp v188, v188, v188 row_shr:8 row_mask:0xf bank_mask:0xf
	v_mov_b32_e32 v228, v188
	v_mul_f32_e32 v188, 0xbf60028a, v189
	v_exp_f32_e32 v189, v188

	v_mov_b32_e32 v218, 1.0
	v_mov_b32_e32 v219, 1.0

	v_mul_f32_dpp v189, v189, v189 row_shr:1 row_mask:0xf bank_mask:0xf

	v_mov_b32_e32 v220, 1.0
	v_mov_b32_e32 v221, 1.0

	v_mul_f32_dpp v189, v189, v189 row_shr:2 row_mask:0xf bank_mask:0xf

	v_mov_b32_dpp v218, v228 row_shr:1 row_mask:0xf bank_mask:0xf


	s_nop 0
	v_mul_f32_dpp v189, v189, v189 row_shr:4 row_mask:0xf bank_mask:0xf

	v_add_u32_e32 v247, s33, v200
	s_nop 0

	v_mul_f32_dpp v189, v189, v189 row_shr:8 row_mask:0xf bank_mask:0xf
	v_mov_b32_e32 v231, v189
	v_mul_f32_e32 v189, 0xbf60028a, v190
	v_exp_f32_e32 v190, v189

	v_mov_b32_dpp v219, v231 row_shr:1 row_mask:0xf bank_mask:0xf


	s_nop 0
	v_mul_f32_dpp v190, v190, v190 row_shr:1 row_mask:0xf bank_mask:0xf

	s_nop 1

	v_mul_f32_dpp v190, v190, v190 row_shr:2 row_mask:0xf bank_mask:0xf

	s_nop 1

	v_mul_f32_dpp v190, v190, v190 row_shr:4 row_mask:0xf bank_mask:0xf

	s_nop 1

	v_mul_f32_dpp v190, v190, v190 row_shr:8 row_mask:0xf bank_mask:0xf
	v_mov_b32_e32 v251, v190
	v_mul_f32_e32 v190, 0xbf60028a, v191
	v_exp_f32_e32 v191, v190

	v_mov_b32_dpp v220, v251 row_shr:1 row_mask:0xf bank_mask:0xf


	s_nop 0
	v_mul_f32_dpp v191, v191, v191 row_shr:1 row_mask:0xf bank_mask:0xf

	s_nop 1

	v_mul_f32_dpp v191, v191, v191 row_shr:2 row_mask:0xf bank_mask:0xf

	s_nop 1

	v_mul_f32_dpp v191, v191, v191 row_shr:4 row_mask:0xf bank_mask:0xf

	s_nop 1

	v_mul_f32_dpp v191, v191, v191 row_shr:8 row_mask:0xf bank_mask:0xf
	v_mov_b32_e32 v252, v191
	s_nop 1
	v_mov_b32_dpp v221, v252 row_shr:1 row_mask:0xf bank_mask:0xf

	s_and_saveexec_b64 s[8:9], s[40:41]
	ds_write_b32 v247, v228 offset:25856
	ds_write_b32 v247, v231 offset:25860
	ds_write_b32 v247, v251 offset:25864
	ds_write_b32 v247, v252 offset:25868
	s_or_b64 exec, exec, s[8:9]
	s_waitcnt lgkmcnt(2)
	v_add_f32_e32 v188, v229, v230
	v_mul_f32_e32 v189, 0x4f800000, v188
	v_cmp_gt_f32_e32 vcc, s69, v188
	s_waitcnt lgkmcnt(1)
	v_add_f32_e32 v154, v154, v184
	v_add_f32_e32 v155, v155, v185
	v_cndmask_b32_e32 v188, v188, v189, vcc
	v_sqrt_f32_e32 v189, v188
	v_add_f32_e32 v156, v156, v186
	v_add_f32_e32 v157, v157, v187
	v_exp_f32_e32 v154, v154
	v_add_u32_e32 v190, -1, v189
	v_fma_f32 v200, -v190, v189, v188
	v_add_u32_e32 v191, 1, v189
	v_cmp_ge_f32_e64 s[42:43], 0, v200
	v_exp_f32_e32 v155, v155
	v_exp_f32_e32 v156, v156
	v_cndmask_b32_e64 v190, v189, v190, s[42:43]
	v_fma_f32 v189, -v191, v189, v188
	v_cmp_lt_f32_e64 s[42:43], 0, v189
	v_exp_f32_e32 v157, v157
	v_add_f32_e32 v154, 1.0, v154
	v_cndmask_b32_e64 v189, v190, v191, s[42:43]
	v_mul_f32_e32 v190, 0x37800000, v189
	v_cndmask_b32_e32 v189, v189, v190, vcc
	v_cmp_class_f32_e64 vcc, v188, s100
	v_add_f32_e32 v155, 1.0, v155
	v_add_f32_e32 v156, 1.0, v156
	v_cndmask_b32_e32 v188, v189, v188, vcc
	v_max_f32_e32 v188, 0x2b8cbccc, v188
	v_div_scale_f32 v189, s[8:9], v188, v188, 1.0
	v_rcp_f32_e32 v190, v189
	v_add_f32_e32 v157, 1.0, v157
	v_rcp_f32_e32 v154, v154
	v_rcp_f32_e32 v155, v155
	v_fma_f32 v191, -v189, v190, 1.0
	v_fmac_f32_e32 v190, v191, v190
	v_div_scale_f32 v191, vcc, 1.0, v188, 1.0
	v_mul_f32_e32 v200, v191, v190
	v_fma_f32 v201, -v189, v200, v191
	v_rcp_f32_e32 v156, v156
	v_rcp_f32_e32 v157, v157
	v_fmac_f32_e32 v200, v201, v190
	v_fma_f32 v189, -v189, v200, v191
	v_div_fmas_f32 v189, v189, v190, v200
	v_rcp_f32_e32 v184, v228
	v_rcp_f32_e32 v185, v231
	v_rcp_f32_e32 v186, v251
	v_rcp_f32_e32 v187, v252
	v_div_fixup_f32 v230, v189, v188, 1.0
	v_add_f32_e32 v188, -1.0, v154
	v_add_f32_e32 v189, -1.0, v155
	v_add_f32_e32 v190, -1.0, v156
	v_add_f32_e32 v191, -1.0, v157
	v_mul_f32_e32 v228, v226, v230
	v_mul_f32_e32 v229, v227, v230
	s_waitcnt lgkmcnt(0)
	v_fma_f32 v160, v160, v190, 1.0
	v_fma_f32 v161, v161, v191, 1.0
	v_fma_f32 v158, v158, v188, 1.0
	v_fma_f32 v159, v159, v189, 1.0
	v_mul_f32_e32 v226, v238, v230
	v_mul_f32_e32 v227, v239, v230
	v_mul_f32_e32 v158, v158, v194
	v_mul_f32_e32 v159, v159, v195
	v_mul_f32_e32 v160, v160, v234
	v_mul_f32_e32 v161, v161, v235
	v_mul_f32_e32 v156, v156, v228
	v_mul_f32_e32 v157, v157, v229
	v_mad_u32_u24 v2, v246, s63, v2
	v_mul_f32_e32 v154, v154, v226
	v_mul_f32_e32 v155, v155, v227
	v_mul_f32_e32 v188, v156, v186
	v_mul_f32_e32 v189, v157, v187
	v_mul_f32_e32 v156, v160, v186
	v_mul_f32_e32 v157, v161, v187
	v_mul_f32_e32 v158, v158, v184
	v_mul_f32_e32 v159, v159, v185
	v_mul_f32_e32 v154, v154, v184
	v_mul_f32_e32 v155, v155, v185
	v_cvt_pk_bf16_f32 v160, v158, v159
	v_cvt_pk_bf16_f32 v161, v156, v157
	v_add_u32_e32 v2, s33, v2
	v_cvt_pk_bf16_f32 v156, v154, v155
	v_cvt_pk_bf16_f32 v157, v188, v189
	ds_write_b64 v2, v[160:161] offset:21248
	ds_write_b64 v2, v[156:157] offset:23552

	ds_write_b64 v2, v[192:193] offset:18944
	ds_read_b128 v[204:207], v250 offset:17216
	ds_read_b128 v[192:195], v250 offset:17472
	ds_read_b128 v[188:191], v250 offset:17728
	ds_read_b128 v[184:187], v250 offset:17984

	s_waitcnt lgkmcnt(3)
	v_add_f32_e32 v158, v182, v206
	v_exp_f32_e32 v158, v158
	v_add_f32_e32 v155, v181, v205
	v_add_f32_e32 v154, v180, v204
	v_add_f32_e32 v159, v183, v207
	v_add_f32_e32 v158, 1.0, v158
	v_rcp_f32_e32 v181, v158
	v_exp_f32_e32 v154, v154
	v_exp_f32_e32 v155, v155
	v_exp_f32_e32 v159, v159
	v_mul_f32_e32 v181, 0xbf60028a, v181
	v_exp_f32_e32 v183, v181
	v_add_f32_e32 v154, 1.0, v154
	v_add_f32_e32 v155, 1.0, v155
	v_add_f32_e32 v158, 1.0, v159

	v_mul_f32_dpp v183, v183, v183 row_shr:1 row_mask:0xf bank_mask:0xf

	v_rcp_f32_e32 v154, v154
	v_rcp_f32_e32 v155, v155
	v_rcp_f32_e32 v182, v158

	v_mul_f32_dpp v183, v183, v183 row_shr:2 row_mask:0xf bank_mask:0xf

	v_mul_f32_e32 v154, 0xbf60028a, v154
	v_mul_f32_e32 v155, 0xbf60028a, v155

	v_mul_f32_dpp v183, v183, v183 row_shr:4 row_mask:0xf bank_mask:0xf

	v_mul_f32_e32 v182, 0xbf60028a, v182
	v_exp_f32_e32 v154, v154

	v_exp_f32_e32 v155, v155
	v_mul_f32_dpp v183, v183, v183 row_shr:8 row_mask:0xf bank_mask:0xf
	v_mov_b32_e32 v238, v183
	v_exp_f32_e32 v183, v182


	v_mul_f32_dpp v154, v154, v154 row_shr:1 row_mask:0xf bank_mask:0xf

	v_mul_f32_dpp v155, v155, v155 row_shr:1 row_mask:0xf bank_mask:0xf

	v_mul_f32_dpp v183, v183, v183 row_shr:1 row_mask:0xf bank_mask:0xf


	v_mul_f32_dpp v154, v154, v154 row_shr:2 row_mask:0xf bank_mask:0xf

	v_mul_f32_dpp v155, v155, v155 row_shr:2 row_mask:0xf bank_mask:0xf

	v_mul_f32_dpp v183, v183, v183 row_shr:2 row_mask:0xf bank_mask:0xf


	v_mul_f32_dpp v154, v154, v154 row_shr:4 row_mask:0xf bank_mask:0xf

	v_mul_f32_dpp v155, v155, v155 row_shr:4 row_mask:0xf bank_mask:0xf

	v_mul_f32_dpp v183, v183, v183 row_shr:4 row_mask:0xf bank_mask:0xf


	v_mul_f32_dpp v154, v154, v154 row_shr:8 row_mask:0xf bank_mask:0xf
	v_mov_b32_e32 v158, v154
	v_mov_b32_e32 v154, 1.0
	v_mul_f32_dpp v155, v155, v155 row_shr:8 row_mask:0xf bank_mask:0xf
	v_mov_b32_e32 v159, v155
	v_mov_b32_e32 v155, 1.0
	v_mov_b32_e32 v234, 1.0
	v_mul_f32_dpp v183, v183, v183 row_shr:8 row_mask:0xf bank_mask:0xf
	v_mov_b32_e32 v239, v183
	v_mov_b32_e32 v235, 1.0
	v_mov_b32_dpp v154, v158 row_shr:1 row_mask:0xf bank_mask:0xf

	v_mov_b32_dpp v155, v159 row_shr:1 row_mask:0xf bank_mask:0xf

	v_mov_b32_dpp v234, v238 row_shr:1 row_mask:0xf bank_mask:0xf

	v_mov_b32_dpp v235, v239 row_shr:1 row_mask:0xf bank_mask:0xf

	s_and_saveexec_b64 s[8:9], s[40:41]
	ds_write_b64 v247, v[158:159] offset:25920
	ds_write_b64 v247, v[238:239] offset:25928
	s_or_b64 exec, exec, s[8:9]
	s_waitcnt lgkmcnt(2)
	v_add_f32_e32 v176, v176, v192
	v_add_f32_e32 v177, v177, v193
	v_add_f32_e32 v178, v178, v194
	v_add_f32_e32 v179, v179, v195
	v_exp_f32_e32 v176, v176
	v_exp_f32_e32 v177, v177
	v_exp_f32_e32 v178, v178
	v_exp_f32_e32 v179, v179
	v_add_f32_e32 v176, 1.0, v176
	v_add_f32_e32 v177, 1.0, v177
	v_add_f32_e32 v178, 1.0, v178
	v_add_f32_e32 v179, 1.0, v179
	v_rcp_f32_e32 v176, v176
	v_rcp_f32_e32 v177, v177
	v_rcp_f32_e32 v178, v178
	v_rcp_f32_e32 v179, v179
	v_rcp_f32_e32 v158, v158
	v_rcp_f32_e32 v159, v159
	v_rcp_f32_e32 v180, v238
	v_rcp_f32_e32 v181, v239
	s_waitcnt lgkmcnt(1)
	v_mul_f32_e32 v182, v190, v236
	v_mul_f32_e32 v183, v191, v237
	v_mov_b32_e32 v238, v230
	v_mov_b32_e32 v239, v230
	v_mov_b32_e32 v231, v230
	v_mul_f32_e32 v188, v188, v162
	v_mul_f32_e32 v189, v189, v163
	v_mul_f32_e32 v190, v238, v182
	v_mul_f32_e32 v191, v239, v183
	v_add_f32_e32 v182, -1.0, v176
	v_add_f32_e32 v183, -1.0, v177
	v_add_f32_e32 v192, -1.0, v178
	v_add_f32_e32 v193, -1.0, v179
	v_mul_f32_e32 v188, v230, v188
	v_mul_f32_e32 v189, v231, v189
	s_waitcnt lgkmcnt(0)
	v_fma_f32 v186, v186, v192, 1.0
	v_fma_f32 v187, v187, v193, 1.0
	v_fma_f32 v182, v184, v182, 1.0
	v_fma_f32 v183, v185, v183, 1.0
	v_mul_f32_e32 v178, v190, v178
	v_mul_f32_e32 v179, v191, v179
	v_mul_f32_e32 v162, v182, v162
	v_mul_f32_e32 v163, v183, v163
	v_mul_f32_e32 v182, v186, v236
	v_mul_f32_e32 v183, v187, v237
	v_mul_f32_e32 v176, v188, v176
	v_mul_f32_e32 v177, v189, v177
	v_mul_f32_e32 v178, v178, v180
	v_mul_f32_e32 v179, v179, v181
	v_mul_f32_e32 v176, v176, v158
	v_mul_f32_e32 v177, v177, v159
	v_mul_f32_e32 v180, v182, v180
	v_mul_f32_e32 v181, v183, v181
	v_mul_f32_e32 v158, v162, v158
	v_mul_f32_e32 v159, v163, v159
	v_cvt_pk_bf16_f32 v163, v180, v181
	v_cvt_pk_bf16_f32 v162, v158, v159
	v_cvt_pk_bf16_f32 v158, v176, v177
	v_cvt_pk_bf16_f32 v159, v178, v179
	ds_write_b64 v2, v[162:163] offset:21280
	ds_write_b64 v2, v[158:159] offset:23584

	ds_write_b64 v2, v[232:233] offset:18976
	ds_read_b128 v[192:195], v250 offset:17280
	ds_read_b128 v[184:187], v250 offset:17536
	ds_read_b128 v[180:183], v250 offset:17792
	ds_read_b128 v[176:179], v250 offset:18048
	s_waitcnt lgkmcnt(3)
	v_add_f32_e32 v172, v172, v192
	v_exp_f32_e32 v172, v172
	v_add_f32_e32 v173, v173, v193
	v_exp_f32_e32 v173, v173

	v_add_f32_e32 v172, 1.0, v172
	v_rcp_f32_e32 v172, v172
	v_add_f32_e32 v173, 1.0, v173
	v_rcp_f32_e32 v173, v173
	v_add_f32_e32 v174, v174, v194
	v_mul_f32_e32 v172, 0xbf60028a, v172
	v_exp_f32_e32 v172, v172
	v_exp_f32_e32 v174, v174

	v_add_f32_e32 v175, v175, v195

	v_mul_f32_dpp v172, v172, v172 row_shr:1 row_mask:0xf bank_mask:0xf

	v_add_f32_e32 v174, 1.0, v174
	v_rcp_f32_e32 v174, v174

	v_mul_f32_dpp v172, v172, v172 row_shr:2 row_mask:0xf bank_mask:0xf

	v_exp_f32_e32 v175, v175


	s_nop 0
	v_mul_f32_dpp v172, v172, v172 row_shr:4 row_mask:0xf bank_mask:0xf

	v_add_f32_e32 v175, 1.0, v175
	v_rcp_f32_e32 v175, v175

	v_mul_f32_dpp v172, v172, v172 row_shr:8 row_mask:0xf bank_mask:0xf
	v_mov_b32_e32 v232, v172
	v_mul_f32_e32 v172, 0xbf60028a, v173
	v_exp_f32_e32 v173, v172

	v_mov_b32_e32 v192, 1.0


	s_nop 0
	v_mul_f32_dpp v173, v173, v173 row_shr:1 row_mask:0xf bank_mask:0xf

	v_mov_b32_dpp v192, v232 row_shr:1 row_mask:0xf bank_mask:0xf
	s_nop 0

	v_mul_f32_dpp v173, v173, v173 row_shr:2 row_mask:0xf bank_mask:0xf

	s_nop 1

	v_mul_f32_dpp v173, v173, v173 row_shr:4 row_mask:0xf bank_mask:0xf

	s_nop 1

	v_mul_f32_dpp v173, v173, v173 row_shr:8 row_mask:0xf bank_mask:0xf
	v_mov_b32_e32 v233, v173
	v_mul_f32_e32 v173, 0xbf60028a, v174
	v_exp_f32_e32 v174, v173
	v_mov_b32_e32 v193, 1.0


	s_nop 0
	v_mul_f32_dpp v174, v174, v174 row_shr:1 row_mask:0xf bank_mask:0xf

	v_mov_b32_dpp v193, v233 row_shr:1 row_mask:0xf bank_mask:0xf
	s_nop 0

	v_mul_f32_dpp v174, v174, v174 row_shr:2 row_mask:0xf bank_mask:0xf

	s_nop 1

	v_mul_f32_dpp v174, v174, v174 row_shr:4 row_mask:0xf bank_mask:0xf

	s_nop 1

	v_mul_f32_dpp v174, v174, v174 row_shr:8 row_mask:0xf bank_mask:0xf
	v_mov_b32_e32 v236, v174
	v_mul_f32_e32 v174, 0xbf60028a, v175
	v_exp_f32_e32 v175, v174
	v_mov_b32_e32 v194, 1.0


	s_nop 0
	v_mul_f32_dpp v175, v175, v175 row_shr:1 row_mask:0xf bank_mask:0xf

	v_mov_b32_dpp v194, v236 row_shr:1 row_mask:0xf bank_mask:0xf
	s_nop 0

	v_mul_f32_dpp v175, v175, v175 row_shr:2 row_mask:0xf bank_mask:0xf

	s_nop 1

	v_mul_f32_dpp v175, v175, v175 row_shr:4 row_mask:0xf bank_mask:0xf

	s_nop 1

	v_mul_f32_dpp v175, v175, v175 row_shr:8 row_mask:0xf bank_mask:0xf
	v_mov_b32_e32 v237, v175
	v_mov_b32_e32 v195, 1.0
	s_nop 0

	s_nop 0
	v_mov_b32_dpp v195, v237 row_shr:1 row_mask:0xf bank_mask:0xf
	s_and_saveexec_b64 s[8:9], s[40:41]
	ds_write_b64 v247, v[232:233] offset:25984
	ds_write_b64 v247, v[236:237] offset:25992
	s_or_b64 exec, exec, s[8:9]
	s_waitcnt lgkmcnt(2)
	v_add_f32_e32 v170, v170, v186
	v_add_f32_e32 v168, v168, v184
	v_add_f32_e32 v169, v169, v185
	v_exp_f32_e32 v170, v170
	v_add_f32_e32 v171, v171, v187
	v_exp_f32_e32 v168, v168
	v_exp_f32_e32 v169, v169
	v_exp_f32_e32 v171, v171
	v_add_f32_e32 v170, 1.0, v170
	v_add_f32_e32 v168, 1.0, v168
	v_add_f32_e32 v169, 1.0, v169
	v_rcp_f32_e32 v172, v170
	v_add_f32_e32 v170, 1.0, v171
	v_rcp_f32_e32 v168, v168
	v_rcp_f32_e32 v169, v169
	v_rcp_f32_e32 v173, v170
	v_rcp_f32_e32 v174, v232
	v_rcp_f32_e32 v175, v233
	v_rcp_f32_e32 v184, v236
	v_rcp_f32_e32 v185, v237
	s_waitcnt lgkmcnt(1)
	v_mul_f32_e32 v170, v182, v224
	v_mul_f32_e32 v171, v183, v225
	v_mul_f32_e32 v180, v180, v222
	v_mul_f32_e32 v181, v181, v223
	v_mul_f32_e32 v186, v238, v170
	v_mul_f32_e32 v187, v239, v171
	v_mul_f32_e32 v170, v230, v180
	v_mul_f32_e32 v171, v231, v181
	v_add_f32_e32 v180, -1.0, v168
	v_add_f32_e32 v181, -1.0, v169
	v_add_f32_e32 v182, -1.0, v172
	v_add_f32_e32 v183, -1.0, v173
	s_waitcnt lgkmcnt(0)
	v_fma_f32 v176, v176, v180, 1.0
	v_fma_f32 v177, v177, v181, 1.0
	v_fma_f32 v178, v178, v182, 1.0
	v_fma_f32 v179, v179, v183, 1.0
	v_mul_f32_e32 v176, v176, v222
	v_mul_f32_e32 v177, v177, v223
	v_mul_f32_e32 v178, v178, v224
	v_mul_f32_e32 v179, v179, v225
	v_mul_f32_e32 v172, v186, v172
	v_mul_f32_e32 v173, v187, v173
	v_mul_f32_e32 v168, v170, v168
	v_mul_f32_e32 v169, v171, v169
	v_mul_f32_e32 v180, v172, v184
	v_mul_f32_e32 v181, v173, v185
	v_mul_f32_e32 v172, v168, v174
	v_mul_f32_e32 v173, v169, v175
	v_mul_f32_e32 v178, v178, v184
	v_mul_f32_e32 v179, v179, v185
	v_mul_f32_e32 v168, v176, v174
	v_mul_f32_e32 v169, v177, v175
	v_cvt_pk_bf16_f32 v172, v172, v173
	v_cvt_pk_bf16_f32 v168, v168, v169
	v_cvt_pk_bf16_f32 v169, v178, v179
	v_cvt_pk_bf16_f32 v173, v180, v181
	ds_write_b64 v2, v[168:169] offset:21312
	ds_write_b64 v2, v[172:173] offset:23616

	ds_write_b64 v2, v[148:149] offset:19008
	ds_read_b128 v[204:207], v250 offset:17344
	ds_read_b128 v[182:185], v250 offset:17600
	ds_read_b128 v[178:181], v250 offset:17856
	ds_read_b128 v[174:177], v250 offset:18112
	v_mov_b32_e32 v222, 1.0
	s_waitcnt lgkmcnt(3)
	v_add_f32_e32 v148, v164, v204
	v_exp_f32_e32 v148, v148
	v_add_f32_e32 v164, v166, v206
	v_add_f32_e32 v149, v165, v205
	v_exp_f32_e32 v164, v164
	v_add_f32_e32 v148, 1.0, v148
	v_rcp_f32_e32 v148, v148
	v_add_f32_e32 v165, v167, v207
	v_exp_f32_e32 v165, v165
	v_add_f32_e32 v164, 1.0, v164
	v_mul_f32_e32 v148, 0xbf60028a, v148
	v_exp_f32_e32 v148, v148
	v_exp_f32_e32 v149, v149
	v_rcp_f32_e32 v166, v164
	v_add_f32_e32 v164, 1.0, v165
	v_rcp_f32_e32 v167, v164

	v_add_f32_e32 v149, 1.0, v149
	v_rcp_f32_e32 v149, v149

	v_mul_f32_dpp v148, v148, v148 row_shr:1 row_mask:0xf bank_mask:0xf

	v_mov_b32_e32 v223, 1.0
	v_mov_b32_e32 v224, 1.0

	v_mul_f32_dpp v148, v148, v148 row_shr:2 row_mask:0xf bank_mask:0xf

	v_mov_b32_e32 v225, 1.0
	s_nop 0

	v_mul_f32_dpp v148, v148, v148 row_shr:4 row_mask:0xf bank_mask:0xf

	s_nop 1

	v_mul_f32_dpp v148, v148, v148 row_shr:8 row_mask:0xf bank_mask:0xf
	v_mov_b32_e32 v232, v148
	v_mul_f32_e32 v148, 0xbf60028a, v149
	v_exp_f32_e32 v148, v148

	v_mov_b32_dpp v222, v232 row_shr:1 row_mask:0xf bank_mask:0xf


	s_nop 0
	v_mul_f32_dpp v148, v148, v148 row_shr:1 row_mask:0xf bank_mask:0xf

	s_nop 1

	v_mul_f32_dpp v148, v148, v148 row_shr:2 row_mask:0xf bank_mask:0xf

	s_nop 1

	v_mul_f32_dpp v148, v148, v148 row_shr:4 row_mask:0xf bank_mask:0xf

	s_nop 1

	v_mul_f32_dpp v148, v148, v148 row_shr:8 row_mask:0xf bank_mask:0xf
	v_mov_b32_e32 v233, v148
	v_mul_f32_e32 v148, 0xbf60028a, v166
	v_exp_f32_e32 v148, v148

	v_mov_b32_dpp v223, v233 row_shr:1 row_mask:0xf bank_mask:0xf


	s_nop 0
	v_mul_f32_dpp v148, v148, v148 row_shr:1 row_mask:0xf bank_mask:0xf

	s_nop 1

	v_mul_f32_dpp v148, v148, v148 row_shr:2 row_mask:0xf bank_mask:0xf

	s_nop 1

	v_mul_f32_dpp v148, v148, v148 row_shr:4 row_mask:0xf bank_mask:0xf

	s_nop 1

	v_mul_f32_dpp v148, v148, v148 row_shr:8 row_mask:0xf bank_mask:0xf
	v_mov_b32_e32 v236, v148
	v_mul_f32_e32 v148, 0xbf60028a, v167
	v_exp_f32_e32 v148, v148

	v_mov_b32_dpp v224, v236 row_shr:1 row_mask:0xf bank_mask:0xf


	s_nop 0
	v_mul_f32_dpp v148, v148, v148 row_shr:1 row_mask:0xf bank_mask:0xf

	s_nop 1

	v_mul_f32_dpp v148, v148, v148 row_shr:2 row_mask:0xf bank_mask:0xf

	s_nop 1

	v_mul_f32_dpp v148, v148, v148 row_shr:4 row_mask:0xf bank_mask:0xf

	s_nop 1

	v_mul_f32_dpp v148, v148, v148 row_shr:8 row_mask:0xf bank_mask:0xf
	v_mov_b32_e32 v237, v148
	s_nop 1
	v_mov_b32_dpp v225, v237 row_shr:1 row_mask:0xf bank_mask:0xf

	s_and_saveexec_b64 s[8:9], s[40:41]
	s_cbranch_execz .LBB0_327
	ds_write_b64 v247, v[232:233] offset:26048
	ds_write_b64 v247, v[236:237] offset:26056
	s_branch .LBB0_327
.Ltr_29:
	s_branch .LBB0_29
.Ltr_28:
	s_branch .LBB0_28
.LBB0_336:
	s_waitcnt vmcnt(0)
	s_barrier
	s_and_saveexec_b64 s[0:1], s[90:91]
	v_readlane_b32 s50, v254, 46
	v_readlane_b32 s51, v254, 47
	s_cbranch_execz .LBB0_388
	v_readlane_b32 s4, v254, 32
	s_waitcnt vmcnt(0) expcnt(0) lgkmcnt(0)
	s_nop 0
	v_mov_b32_e32 v0, s4
	ds_read_b32 v2, v0
	v_readlane_b32 s4, v254, 33
	s_waitcnt lgkmcnt(0)
	v_cmp_ne_u32_e32 vcc, 0, v2
	v_mov_b32_e32 v0, s4
	ds_read_b32 v0, v0
	s_cbranch_vccnz .LBB0_352
	s_mov_b32 s10, 1
	s_branch .LBB0_340

.LBB0_745:
	s_or_b64 exec, exec, s[0:1]
	s_mov_b64 s[4:5], s[88:89]
	s_waitcnt lgkmcnt(0)
	s_barrier
	s_cmpk_lg_u32 s56, 0x100
	s_cbranch_scc1 .Llo_generic
	s_load_dwordx2 s[6:7], s[4:5], 0xa0
	s_load_dwordx4 s[40:43], s[4:5], 0x90
	v_mbcnt_lo_u32_b32 v0, -1, 0
	v_mbcnt_hi_u32_b32 v0, -1, v0
	v_lshlrev_b32_e32 v1, 4, v0
	s_lshr_b32 s0, s29, 6
	s_lshl_b32 s96, s92, 24
	s_lshl_b64 s[8:9], s[96:97], 2
	v_mov_b32_e32 v2, 0x3a800000
	v_mov_b32_e32 v4, 0x3727c5ac
	s_waitcnt lgkmcnt(0)
	s_add_u32 s4, s6, s8
	s_addc_u32 s5, s7, s9
	s_cmp_eq_u32 s92, 2
	s_cbranch_scc1 .Llo_even
	s_cmp_lt_u32 s86, 64
	s_cbranch_scc1 .Llo_small
	s_sub_u32 s1, s86, 64
	s_lshl_b32 s1, s1, 3
	s_add_i32 s0, s0, s1
	s_mul_i32 s0, s0, 0xa000
	s_add_u32 s0, s0, 0x400000
	s_add_u32 s4, s4, s0
	s_addc_u32 s5, s5, 0
	global_load_dwordx4 v[40:43], v1, s[4:5]
	global_load_dwordx4 v[44:47], v1, s[4:5] offset:1024
	global_load_dwordx4 v[48:51], v1, s[4:5] offset:2048
	global_load_dwordx4 v[52:55], v1, s[4:5] offset:3072
	global_load_dwordx4 v[8:11], v1, s[40:41]
	global_load_dwordx4 v[12:15], v1, s[40:41] offset:1024
	global_load_dwordx4 v[16:19], v1, s[40:41] offset:2048
	global_load_dwordx4 v[20:23], v1, s[40:41] offset:3072
	global_load_dwordx4 v[24:27], v1, s[42:43]
	global_load_dwordx4 v[28:31], v1, s[42:43] offset:1024
	global_load_dwordx4 v[32:35], v1, s[42:43] offset:2048
	global_load_dwordx4 v[36:39], v1, s[42:43] offset:3072
	v_add_u32_e32 v170, 0x1000, v1
	global_load_dwordx4 v[56:59], v170, s[4:5]
	global_load_dwordx4 v[60:63], v170, s[4:5] offset:1024
	global_load_dwordx4 v[64:67], v170, s[4:5] offset:2048
	global_load_dwordx4 v[68:71], v170, s[4:5] offset:3072
	v_add_u32_e32 v170, 0x2000, v1
	global_load_dwordx4 v[72:75], v170, s[4:5]
	global_load_dwordx4 v[76:79], v170, s[4:5] offset:1024
	global_load_dwordx4 v[80:83], v170, s[4:5] offset:2048
	global_load_dwordx4 v[84:87], v170, s[4:5] offset:3072
	v_add_u32_e32 v170, 0x3000, v1
	global_load_dwordx4 v[88:91], v170, s[4:5]
	global_load_dwordx4 v[92:95], v170, s[4:5] offset:1024
	global_load_dwordx4 v[96:99], v170, s[4:5] offset:2048
	global_load_dwordx4 v[100:103], v170, s[4:5] offset:3072
	v_add_u32_e32 v170, 0x4000, v1
	global_load_dwordx4 v[104:107], v170, s[4:5]
	global_load_dwordx4 v[108:111], v170, s[4:5] offset:1024
	global_load_dwordx4 v[112:115], v170, s[4:5] offset:2048
	global_load_dwordx4 v[116:119], v170, s[4:5] offset:3072
	v_add_u32_e32 v170, 0x5000, v1
	global_load_dwordx4 v[120:123], v170, s[4:5]
	global_load_dwordx4 v[124:127], v170, s[4:5] offset:1024
	global_load_dwordx4 v[128:131], v170, s[4:5] offset:2048
	global_load_dwordx4 v[132:135], v170, s[4:5] offset:3072
	v_add_u32_e32 v170, 0x6000, v1
	global_load_dwordx4 v[136:139], v170, s[4:5]
	global_load_dwordx4 v[140:143], v170, s[4:5] offset:1024
	global_load_dwordx4 v[144:147], v170, s[4:5] offset:2048
	global_load_dwordx4 v[148:151], v170, s[4:5] offset:3072
	v_add_u32_e32 v170, 0x7000, v1
	global_load_dwordx4 v[152:155], v170, s[4:5]
	global_load_dwordx4 v[156:159], v170, s[4:5] offset:1024
	global_load_dwordx4 v[160:163], v170, s[4:5] offset:2048
	global_load_dwordx4 v[164:167], v170, s[4:5] offset:3072
	s_waitcnt vmcnt(36)
	v_add_f32_e32 v180, v40, v41
	v_add_f32_e32 v181, v44, v45
	v_add_f32_e32 v182, v48, v49
	v_add_f32_e32 v183, v52, v53
	v_add_f32_e32 v180, v180, v42
	v_add_f32_e32 v181, v181, v46
	v_add_f32_e32 v182, v182, v50
	v_add_f32_e32 v183, v183, v54
	v_add_f32_e32 v180, v180, v43
	v_add_f32_e32 v181, v181, v47
	v_add_f32_e32 v182, v182, v51
	v_add_f32_e32 v183, v183, v55
	v_add_f32_e32 v180, v180, v181
	v_add_f32_e32 v182, v182, v183
	v_add_f32_e32 v180, v180, v182
	s_nop 1
	v_add_f32_dpp v180, v180, v180 quad_perm:[1,0,3,2] row_mask:0xf bank_mask:0xf
	s_nop 1
	v_add_f32_dpp v180, v180, v180 quad_perm:[2,3,0,1] row_mask:0xf bank_mask:0xf
	s_nop 1
	v_add_f32_dpp v180, v180, v180 row_half_mirror row_mask:0xf bank_mask:0xf
	s_nop 1
	v_add_f32_dpp v180, v180, v180 row_mirror row_mask:0xf bank_mask:0xf
	s_nop 1
	v_add_f32_dpp v180, v180, v180 row_bcast:15 row_mask:0xa bank_mask:0xf
	s_nop 1
	v_add_f32_dpp v180, v180, v180 row_bcast:31 row_mask:0xc bank_mask:0xf
	s_nop 0
	v_readlane_b32 s20, v180, 63
	s_nop 1
	v_mul_f32_e32 v184, s20, v2
	v_sub_f32_e32 v40, v40, v184
	v_sub_f32_e32 v41, v41, v184
	v_sub_f32_e32 v42, v42, v184
	v_sub_f32_e32 v43, v43, v184
	v_sub_f32_e32 v44, v44, v184
	v_sub_f32_e32 v45, v45, v184
	v_sub_f32_e32 v46, v46, v184
	v_sub_f32_e32 v47, v47, v184
	v_sub_f32_e32 v48, v48, v184
	v_sub_f32_e32 v49, v49, v184
	v_sub_f32_e32 v50, v50, v184
	v_sub_f32_e32 v51, v51, v184
	v_sub_f32_e32 v52, v52, v184
	v_sub_f32_e32 v53, v53, v184
	v_sub_f32_e32 v54, v54, v184
	v_sub_f32_e32 v55, v55, v184
	v_mul_f32_e32 v180, v40, v40
	v_mul_f32_e32 v181, v44, v44
	v_mul_f32_e32 v182, v48, v48
	v_mul_f32_e32 v183, v52, v52
	v_fmac_f32_e32 v180, v41, v41
	v_fmac_f32_e32 v181, v45, v45
	v_fmac_f32_e32 v182, v49, v49
	v_fmac_f32_e32 v183, v53, v53
	v_fmac_f32_e32 v180, v42, v42
	v_fmac_f32_e32 v181, v46, v46
	v_fmac_f32_e32 v182, v50, v50
	v_fmac_f32_e32 v183, v54, v54
	v_fmac_f32_e32 v180, v43, v43
	v_fmac_f32_e32 v181, v47, v47
	v_fmac_f32_e32 v182, v51, v51
	v_fmac_f32_e32 v183, v55, v55
	v_add_f32_e32 v180, v180, v181
	v_add_f32_e32 v182, v182, v183
	v_add_f32_e32 v180, v180, v182
	s_nop 1
	v_add_f32_dpp v180, v180, v180 quad_perm:[1,0,3,2] row_mask:0xf bank_mask:0xf
	s_nop 1
	v_add_f32_dpp v180, v180, v180 quad_perm:[2,3,0,1] row_mask:0xf bank_mask:0xf
	s_nop 1
	v_add_f32_dpp v180, v180, v180 row_half_mirror row_mask:0xf bank_mask:0xf
	s_nop 1
	v_add_f32_dpp v180, v180, v180 row_mirror row_mask:0xf bank_mask:0xf
	s_nop 1
	v_add_f32_dpp v180, v180, v180 row_bcast:15 row_mask:0xa bank_mask:0xf
	s_nop 1
	v_add_f32_dpp v180, v180, v180 row_bcast:31 row_mask:0xc bank_mask:0xf
	s_nop 0
	v_readlane_b32 s20, v180, 63
	s_nop 1
	v_mov_b32_e32 v185, s20
	v_fma_f32 v185, v185, v2, v4
	v_rsq_f32_e32 v185, v185
	s_nop 0
	v_mul_f32_e32 v40, v40, v185
	v_mul_f32_e32 v41, v41, v185
	v_mul_f32_e32 v42, v42, v185
	v_mul_f32_e32 v43, v43, v185
	v_mul_f32_e32 v44, v44, v185
	v_mul_f32_e32 v45, v45, v185
	v_mul_f32_e32 v46, v46, v185
	v_mul_f32_e32 v47, v47, v185
	v_mul_f32_e32 v48, v48, v185
	v_mul_f32_e32 v49, v49, v185
	v_mul_f32_e32 v50, v50, v185
	v_mul_f32_e32 v51, v51, v185
	v_mul_f32_e32 v52, v52, v185
	v_mul_f32_e32 v53, v53, v185
	v_mul_f32_e32 v54, v54, v185
	v_mul_f32_e32 v55, v55, v185
	s_waitcnt vmcnt(28)
	v_fma_f32 v40, v40, v8, v24
	v_fma_f32 v41, v41, v9, v25
	v_fma_f32 v42, v42, v10, v26
	v_fma_f32 v43, v43, v11, v27
	v_fma_f32 v44, v44, v12, v28
	v_fma_f32 v45, v45, v13, v29
	v_fma_f32 v46, v46, v14, v30
	v_fma_f32 v47, v47, v15, v31
	v_fma_f32 v48, v48, v16, v32
	v_fma_f32 v49, v49, v17, v33
	v_fma_f32 v50, v50, v18, v34
	v_fma_f32 v51, v51, v19, v35
	v_fma_f32 v52, v52, v20, v36
	v_fma_f32 v53, v53, v21, v37
	v_fma_f32 v54, v54, v22, v38
	v_fma_f32 v55, v55, v23, v39
	global_store_dwordx4 v1, v[40:43], s[4:5]
	global_store_dwordx4 v1, v[44:47], s[4:5] offset:1024
	global_store_dwordx4 v1, v[48:51], s[4:5] offset:2048
	global_store_dwordx4 v1, v[52:55], s[4:5] offset:3072
	s_nop 1
	v_add_u32_e32 v170, 0x8000, v1
	global_load_dwordx4 v[40:43], v170, s[4:5]
	global_load_dwordx4 v[44:47], v170, s[4:5] offset:1024
	global_load_dwordx4 v[48:51], v170, s[4:5] offset:2048
	global_load_dwordx4 v[52:55], v170, s[4:5] offset:3072
	s_waitcnt vmcnt(32)
	v_add_f32_e32 v180, v56, v57
	v_add_f32_e32 v181, v60, v61
	v_add_f32_e32 v182, v64, v65
	v_add_f32_e32 v183, v68, v69
	v_add_f32_e32 v180, v180, v58
	v_add_f32_e32 v181, v181, v62
	v_add_f32_e32 v182, v182, v66
	v_add_f32_e32 v183, v183, v70
	v_add_f32_e32 v180, v180, v59
	v_add_f32_e32 v181, v181, v63
	v_add_f32_e32 v182, v182, v67
	v_add_f32_e32 v183, v183, v71
	v_add_f32_e32 v180, v180, v181
	v_add_f32_e32 v182, v182, v183
	v_add_f32_e32 v180, v180, v182
	s_nop 1
	v_add_f32_dpp v180, v180, v180 quad_perm:[1,0,3,2] row_mask:0xf bank_mask:0xf
	s_nop 1
	v_add_f32_dpp v180, v180, v180 quad_perm:[2,3,0,1] row_mask:0xf bank_mask:0xf
	s_nop 1
	v_add_f32_dpp v180, v180, v180 row_half_mirror row_mask:0xf bank_mask:0xf
	s_nop 1
	v_add_f32_dpp v180, v180, v180 row_mirror row_mask:0xf bank_mask:0xf
	s_nop 1
	v_add_f32_dpp v180, v180, v180 row_bcast:15 row_mask:0xa bank_mask:0xf
	s_nop 1
	v_add_f32_dpp v180, v180, v180 row_bcast:31 row_mask:0xc bank_mask:0xf
	s_nop 0
	v_readlane_b32 s20, v180, 63
	s_nop 1
	v_mul_f32_e32 v184, s20, v2
	v_sub_f32_e32 v56, v56, v184
	v_sub_f32_e32 v57, v57, v184
	v_sub_f32_e32 v58, v58, v184
	v_sub_f32_e32 v59, v59, v184
	v_sub_f32_e32 v60, v60, v184
	v_sub_f32_e32 v61, v61, v184
	v_sub_f32_e32 v62, v62, v184
	v_sub_f32_e32 v63, v63, v184
	v_sub_f32_e32 v64, v64, v184
	v_sub_f32_e32 v65, v65, v184
	v_sub_f32_e32 v66, v66, v184
	v_sub_f32_e32 v67, v67, v184
	v_sub_f32_e32 v68, v68, v184
	v_sub_f32_e32 v69, v69, v184
	v_sub_f32_e32 v70, v70, v184
	v_sub_f32_e32 v71, v71, v184
	v_mul_f32_e32 v180, v56, v56
	v_mul_f32_e32 v181, v60, v60
	v_mul_f32_e32 v182, v64, v64
	v_mul_f32_e32 v183, v68, v68
	v_fmac_f32_e32 v180, v57, v57
	v_fmac_f32_e32 v181, v61, v61
	v_fmac_f32_e32 v182, v65, v65
	v_fmac_f32_e32 v183, v69, v69
	v_fmac_f32_e32 v180, v58, v58
	v_fmac_f32_e32 v181, v62, v62
	v_fmac_f32_e32 v182, v66, v66
	v_fmac_f32_e32 v183, v70, v70
	v_fmac_f32_e32 v180, v59, v59
	v_fmac_f32_e32 v181, v63, v63
	v_fmac_f32_e32 v182, v67, v67
	v_fmac_f32_e32 v183, v71, v71
	v_add_f32_e32 v180, v180, v181
	v_add_f32_e32 v182, v182, v183
	v_add_f32_e32 v180, v180, v182
	s_nop 1
	v_add_f32_dpp v180, v180, v180 quad_perm:[1,0,3,2] row_mask:0xf bank_mask:0xf
	s_nop 1
	v_add_f32_dpp v180, v180, v180 quad_perm:[2,3,0,1] row_mask:0xf bank_mask:0xf
	s_nop 1
	v_add_f32_dpp v180, v180, v180 row_half_mirror row_mask:0xf bank_mask:0xf
	s_nop 1
	v_add_f32_dpp v180, v180, v180 row_mirror row_mask:0xf bank_mask:0xf
	s_nop 1
	v_add_f32_dpp v180, v180, v180 row_bcast:15 row_mask:0xa bank_mask:0xf
	s_nop 1
	v_add_f32_dpp v180, v180, v180 row_bcast:31 row_mask:0xc bank_mask:0xf
	s_nop 0
	v_readlane_b32 s20, v180, 63
	s_nop 1
	v_mov_b32_e32 v185, s20
	v_fma_f32 v185, v185, v2, v4
	v_rsq_f32_e32 v185, v185
	s_nop 0
	v_mul_f32_e32 v56, v56, v185
	v_mul_f32_e32 v57, v57, v185
	v_mul_f32_e32 v58, v58, v185
	v_mul_f32_e32 v59, v59, v185
	v_mul_f32_e32 v60, v60, v185
	v_mul_f32_e32 v61, v61, v185
	v_mul_f32_e32 v62, v62, v185
	v_mul_f32_e32 v63, v63, v185
	v_mul_f32_e32 v64, v64, v185
	v_mul_f32_e32 v65, v65, v185
	v_mul_f32_e32 v66, v66, v185
	v_mul_f32_e32 v67, v67, v185
	v_mul_f32_e32 v68, v68, v185
	v_mul_f32_e32 v69, v69, v185
	v_mul_f32_e32 v70, v70, v185
	v_mul_f32_e32 v71, v71, v185
	v_fma_f32 v56, v56, v8, v24
	v_fma_f32 v57, v57, v9, v25
	v_fma_f32 v58, v58, v10, v26
	v_fma_f32 v59, v59, v11, v27
	v_fma_f32 v60, v60, v12, v28
	v_fma_f32 v61, v61, v13, v29
	v_fma_f32 v62, v62, v14, v30
	v_fma_f32 v63, v63, v15, v31
	v_fma_f32 v64, v64, v16, v32
	v_fma_f32 v65, v65, v17, v33
	v_fma_f32 v66, v66, v18, v34
	v_fma_f32 v67, v67, v19, v35
	v_fma_f32 v68, v68, v20, v36
	v_fma_f32 v69, v69, v21, v37
	v_fma_f32 v70, v70, v22, v38
	v_fma_f32 v71, v71, v23, v39
	v_add_u32_e32 v171, 0x1000, v1
	global_store_dwordx4 v171, v[56:59], s[4:5]
	global_store_dwordx4 v171, v[60:63], s[4:5] offset:1024
	global_store_dwordx4 v171, v[64:67], s[4:5] offset:2048
	global_store_dwordx4 v171, v[68:71], s[4:5] offset:3072
	s_nop 1
	v_add_u32_e32 v170, 0x9000, v1
	global_load_dwordx4 v[56:59], v170, s[4:5]
	global_load_dwordx4 v[60:63], v170, s[4:5] offset:1024
	global_load_dwordx4 v[64:67], v170, s[4:5] offset:2048
	global_load_dwordx4 v[68:71], v170, s[4:5] offset:3072
	s_waitcnt vmcnt(36)
	v_add_f32_e32 v180, v72, v73
	v_add_f32_e32 v181, v76, v77
	v_add_f32_e32 v182, v80, v81
	v_add_f32_e32 v183, v84, v85
	v_add_f32_e32 v180, v180, v74
	v_add_f32_e32 v181, v181, v78
	v_add_f32_e32 v182, v182, v82
	v_add_f32_e32 v183, v183, v86
	v_add_f32_e32 v180, v180, v75
	v_add_f32_e32 v181, v181, v79
	v_add_f32_e32 v182, v182, v83
	v_add_f32_e32 v183, v183, v87
	v_add_f32_e32 v180, v180, v181
	v_add_f32_e32 v182, v182, v183
	v_add_f32_e32 v180, v180, v182
	s_nop 1
	v_add_f32_dpp v180, v180, v180 quad_perm:[1,0,3,2] row_mask:0xf bank_mask:0xf
	s_nop 1
	v_add_f32_dpp v180, v180, v180 quad_perm:[2,3,0,1] row_mask:0xf bank_mask:0xf
	s_nop 1
	v_add_f32_dpp v180, v180, v180 row_half_mirror row_mask:0xf bank_mask:0xf
	s_nop 1
	v_add_f32_dpp v180, v180, v180 row_mirror row_mask:0xf bank_mask:0xf
	s_nop 1
	v_add_f32_dpp v180, v180, v180 row_bcast:15 row_mask:0xa bank_mask:0xf
	s_nop 1
	v_add_f32_dpp v180, v180, v180 row_bcast:31 row_mask:0xc bank_mask:0xf
	s_nop 0
	v_readlane_b32 s20, v180, 63
	s_nop 1
	v_mul_f32_e32 v184, s20, v2
	v_sub_f32_e32 v72, v72, v184
	v_sub_f32_e32 v73, v73, v184
	v_sub_f32_e32 v74, v74, v184
	v_sub_f32_e32 v75, v75, v184
	v_sub_f32_e32 v76, v76, v184
	v_sub_f32_e32 v77, v77, v184
	v_sub_f32_e32 v78, v78, v184
	v_sub_f32_e32 v79, v79, v184
	v_sub_f32_e32 v80, v80, v184
	v_sub_f32_e32 v81, v81, v184
	v_sub_f32_e32 v82, v82, v184
	v_sub_f32_e32 v83, v83, v184
	v_sub_f32_e32 v84, v84, v184
	v_sub_f32_e32 v85, v85, v184
	v_sub_f32_e32 v86, v86, v184
	v_sub_f32_e32 v87, v87, v184
	v_mul_f32_e32 v180, v72, v72
	v_mul_f32_e32 v181, v76, v76
	v_mul_f32_e32 v182, v80, v80
	v_mul_f32_e32 v183, v84, v84
	v_fmac_f32_e32 v180, v73, v73
	v_fmac_f32_e32 v181, v77, v77
	v_fmac_f32_e32 v182, v81, v81
	v_fmac_f32_e32 v183, v85, v85
	v_fmac_f32_e32 v180, v74, v74
	v_fmac_f32_e32 v181, v78, v78
	v_fmac_f32_e32 v182, v82, v82
	v_fmac_f32_e32 v183, v86, v86
	v_fmac_f32_e32 v180, v75, v75
	v_fmac_f32_e32 v181, v79, v79
	v_fmac_f32_e32 v182, v83, v83
	v_fmac_f32_e32 v183, v87, v87
	v_add_f32_e32 v180, v180, v181
	v_add_f32_e32 v182, v182, v183
	v_add_f32_e32 v180, v180, v182
	s_nop 1
	v_add_f32_dpp v180, v180, v180 quad_perm:[1,0,3,2] row_mask:0xf bank_mask:0xf
	s_nop 1
	v_add_f32_dpp v180, v180, v180 quad_perm:[2,3,0,1] row_mask:0xf bank_mask:0xf
	s_nop 1
	v_add_f32_dpp v180, v180, v180 row_half_mirror row_mask:0xf bank_mask:0xf
	s_nop 1
	v_add_f32_dpp v180, v180, v180 row_mirror row_mask:0xf bank_mask:0xf
	s_nop 1
	v_add_f32_dpp v180, v180, v180 row_bcast:15 row_mask:0xa bank_mask:0xf
	s_nop 1
	v_add_f32_dpp v180, v180, v180 row_bcast:31 row_mask:0xc bank_mask:0xf
	s_nop 0
	v_readlane_b32 s20, v180, 63
	s_nop 1
	v_mov_b32_e32 v185, s20
	v_fma_f32 v185, v185, v2, v4
	v_rsq_f32_e32 v185, v185
	s_nop 0
	v_mul_f32_e32 v72, v72, v185
	v_mul_f32_e32 v73, v73, v185
	v_mul_f32_e32 v74, v74, v185
	v_mul_f32_e32 v75, v75, v185
	v_mul_f32_e32 v76, v76, v185
	v_mul_f32_e32 v77, v77, v185
	v_mul_f32_e32 v78, v78, v185
	v_mul_f32_e32 v79, v79, v185
	v_mul_f32_e32 v80, v80, v185
	v_mul_f32_e32 v81, v81, v185
	v_mul_f32_e32 v82, v82, v185
	v_mul_f32_e32 v83, v83, v185
	v_mul_f32_e32 v84, v84, v185
	v_mul_f32_e32 v85, v85, v185
	v_mul_f32_e32 v86, v86, v185
	v_mul_f32_e32 v87, v87, v185
	v_fma_f32 v72, v72, v8, v24
	v_fma_f32 v73, v73, v9, v25
	v_fma_f32 v74, v74, v10, v26
	v_fma_f32 v75, v75, v11, v27
	v_fma_f32 v76, v76, v12, v28
	v_fma_f32 v77, v77, v13, v29
	v_fma_f32 v78, v78, v14, v30
	v_fma_f32 v79, v79, v15, v31
	v_fma_f32 v80, v80, v16, v32
	v_fma_f32 v81, v81, v17, v33
	v_fma_f32 v82, v82, v18, v34
	v_fma_f32 v83, v83, v19, v35
	v_fma_f32 v84, v84, v20, v36
	v_fma_f32 v85, v85, v21, v37
	v_fma_f32 v86, v86, v22, v38
	v_fma_f32 v87, v87, v23, v39
	v_add_u32_e32 v171, 0x2000, v1
	global_store_dwordx4 v171, v[72:75], s[4:5]
	global_store_dwordx4 v171, v[76:79], s[4:5] offset:1024
	global_store_dwordx4 v171, v[80:83], s[4:5] offset:2048
	global_store_dwordx4 v171, v[84:87], s[4:5] offset:3072
	s_waitcnt vmcnt(36)
	v_add_f32_e32 v180, v88, v89
	v_add_f32_e32 v181, v92, v93
	v_add_f32_e32 v182, v96, v97
	v_add_f32_e32 v183, v100, v101
	v_add_f32_e32 v180, v180, v90
	v_add_f32_e32 v181, v181, v94
	v_add_f32_e32 v182, v182, v98
	v_add_f32_e32 v183, v183, v102
	v_add_f32_e32 v180, v180, v91
	v_add_f32_e32 v181, v181, v95
	v_add_f32_e32 v182, v182, v99
	v_add_f32_e32 v183, v183, v103
	v_add_f32_e32 v180, v180, v181
	v_add_f32_e32 v182, v182, v183
	v_add_f32_e32 v180, v180, v182
	s_nop 1
	v_add_f32_dpp v180, v180, v180 quad_perm:[1,0,3,2] row_mask:0xf bank_mask:0xf
	s_nop 1
	v_add_f32_dpp v180, v180, v180 quad_perm:[2,3,0,1] row_mask:0xf bank_mask:0xf
	s_nop 1
	v_add_f32_dpp v180, v180, v180 row_half_mirror row_mask:0xf bank_mask:0xf
	s_nop 1
	v_add_f32_dpp v180, v180, v180 row_mirror row_mask:0xf bank_mask:0xf
	s_nop 1
	v_add_f32_dpp v180, v180, v180 row_bcast:15 row_mask:0xa bank_mask:0xf
	s_nop 1
	v_add_f32_dpp v180, v180, v180 row_bcast:31 row_mask:0xc bank_mask:0xf
	s_nop 0
	v_readlane_b32 s20, v180, 63
	s_nop 1
	v_mul_f32_e32 v184, s20, v2
	v_sub_f32_e32 v88, v88, v184
	v_sub_f32_e32 v89, v89, v184
	v_sub_f32_e32 v90, v90, v184
	v_sub_f32_e32 v91, v91, v184
	v_sub_f32_e32 v92, v92, v184
	v_sub_f32_e32 v93, v93, v184
	v_sub_f32_e32 v94, v94, v184
	v_sub_f32_e32 v95, v95, v184
	v_sub_f32_e32 v96, v96, v184
	v_sub_f32_e32 v97, v97, v184
	v_sub_f32_e32 v98, v98, v184
	v_sub_f32_e32 v99, v99, v184
	v_sub_f32_e32 v100, v100, v184
	v_sub_f32_e32 v101, v101, v184
	v_sub_f32_e32 v102, v102, v184
	v_sub_f32_e32 v103, v103, v184
	v_mul_f32_e32 v180, v88, v88
	v_mul_f32_e32 v181, v92, v92
	v_mul_f32_e32 v182, v96, v96
	v_mul_f32_e32 v183, v100, v100
	v_fmac_f32_e32 v180, v89, v89
	v_fmac_f32_e32 v181, v93, v93
	v_fmac_f32_e32 v182, v97, v97
	v_fmac_f32_e32 v183, v101, v101
	v_fmac_f32_e32 v180, v90, v90
	v_fmac_f32_e32 v181, v94, v94
	v_fmac_f32_e32 v182, v98, v98
	v_fmac_f32_e32 v183, v102, v102
	v_fmac_f32_e32 v180, v91, v91
	v_fmac_f32_e32 v181, v95, v95
	v_fmac_f32_e32 v182, v99, v99
	v_fmac_f32_e32 v183, v103, v103
	v_add_f32_e32 v180, v180, v181
	v_add_f32_e32 v182, v182, v183
	v_add_f32_e32 v180, v180, v182
	s_nop 1
	v_add_f32_dpp v180, v180, v180 quad_perm:[1,0,3,2] row_mask:0xf bank_mask:0xf
	s_nop 1
	v_add_f32_dpp v180, v180, v180 quad_perm:[2,3,0,1] row_mask:0xf bank_mask:0xf
	s_nop 1
	v_add_f32_dpp v180, v180, v180 row_half_mirror row_mask:0xf bank_mask:0xf
	s_nop 1
	v_add_f32_dpp v180, v180, v180 row_mirror row_mask:0xf bank_mask:0xf
	s_nop 1
	v_add_f32_dpp v180, v180, v180 row_bcast:15 row_mask:0xa bank_mask:0xf
	s_nop 1
	v_add_f32_dpp v180, v180, v180 row_bcast:31 row_mask:0xc bank_mask:0xf
	s_nop 0
	v_readlane_b32 s20, v180, 63
	s_nop 1
	v_mov_b32_e32 v185, s20
	v_fma_f32 v185, v185, v2, v4
	v_rsq_f32_e32 v185, v185
	s_nop 0
	v_mul_f32_e32 v88, v88, v185
	v_mul_f32_e32 v89, v89, v185
	v_mul_f32_e32 v90, v90, v185
	v_mul_f32_e32 v91, v91, v185
	v_mul_f32_e32 v92, v92, v185
	v_mul_f32_e32 v93, v93, v185
	v_mul_f32_e32 v94, v94, v185
	v_mul_f32_e32 v95, v95, v185
	v_mul_f32_e32 v96, v96, v185
	v_mul_f32_e32 v97, v97, v185
	v_mul_f32_e32 v98, v98, v185
	v_mul_f32_e32 v99, v99, v185
	v_mul_f32_e32 v100, v100, v185
	v_mul_f32_e32 v101, v101, v185
	v_mul_f32_e32 v102, v102, v185
	v_mul_f32_e32 v103, v103, v185
	v_fma_f32 v88, v88, v8, v24
	v_fma_f32 v89, v89, v9, v25
	v_fma_f32 v90, v90, v10, v26
	v_fma_f32 v91, v91, v11, v27
	v_fma_f32 v92, v92, v12, v28
	v_fma_f32 v93, v93, v13, v29
	v_fma_f32 v94, v94, v14, v30
	v_fma_f32 v95, v95, v15, v31
	v_fma_f32 v96, v96, v16, v32
	v_fma_f32 v97, v97, v17, v33
	v_fma_f32 v98, v98, v18, v34
	v_fma_f32 v99, v99, v19, v35
	v_fma_f32 v100, v100, v20, v36
	v_fma_f32 v101, v101, v21, v37
	v_fma_f32 v102, v102, v22, v38
	v_fma_f32 v103, v103, v23, v39
	v_add_u32_e32 v171, 0x3000, v1
	global_store_dwordx4 v171, v[88:91], s[4:5]
	global_store_dwordx4 v171, v[92:95], s[4:5] offset:1024
	global_store_dwordx4 v171, v[96:99], s[4:5] offset:2048
	global_store_dwordx4 v171, v[100:103], s[4:5] offset:3072
	s_waitcnt vmcnt(36)
	v_add_f32_e32 v180, v104, v105
	v_add_f32_e32 v181, v108, v109
	v_add_f32_e32 v182, v112, v113
	v_add_f32_e32 v183, v116, v117
	v_add_f32_e32 v180, v180, v106
	v_add_f32_e32 v181, v181, v110
	v_add_f32_e32 v182, v182, v114
	v_add_f32_e32 v183, v183, v118
	v_add_f32_e32 v180, v180, v107
	v_add_f32_e32 v181, v181, v111
	v_add_f32_e32 v182, v182, v115
	v_add_f32_e32 v183, v183, v119
	v_add_f32_e32 v180, v180, v181
	v_add_f32_e32 v182, v182, v183
	v_add_f32_e32 v180, v180, v182
	s_nop 1
	v_add_f32_dpp v180, v180, v180 quad_perm:[1,0,3,2] row_mask:0xf bank_mask:0xf
	s_nop 1
	v_add_f32_dpp v180, v180, v180 quad_perm:[2,3,0,1] row_mask:0xf bank_mask:0xf
	s_nop 1
	v_add_f32_dpp v180, v180, v180 row_half_mirror row_mask:0xf bank_mask:0xf
	s_nop 1
	v_add_f32_dpp v180, v180, v180 row_mirror row_mask:0xf bank_mask:0xf
	s_nop 1
	v_add_f32_dpp v180, v180, v180 row_bcast:15 row_mask:0xa bank_mask:0xf
	s_nop 1
	v_add_f32_dpp v180, v180, v180 row_bcast:31 row_mask:0xc bank_mask:0xf
	s_nop 0
	v_readlane_b32 s20, v180, 63
	s_nop 1
	v_mul_f32_e32 v184, s20, v2
	v_sub_f32_e32 v104, v104, v184
	v_sub_f32_e32 v105, v105, v184
	v_sub_f32_e32 v106, v106, v184
	v_sub_f32_e32 v107, v107, v184
	v_sub_f32_e32 v108, v108, v184
	v_sub_f32_e32 v109, v109, v184
	v_sub_f32_e32 v110, v110, v184
	v_sub_f32_e32 v111, v111, v184
	v_sub_f32_e32 v112, v112, v184
	v_sub_f32_e32 v113, v113, v184
	v_sub_f32_e32 v114, v114, v184
	v_sub_f32_e32 v115, v115, v184
	v_sub_f32_e32 v116, v116, v184
	v_sub_f32_e32 v117, v117, v184
	v_sub_f32_e32 v118, v118, v184
	v_sub_f32_e32 v119, v119, v184
	v_mul_f32_e32 v180, v104, v104
	v_mul_f32_e32 v181, v108, v108
	v_mul_f32_e32 v182, v112, v112
	v_mul_f32_e32 v183, v116, v116
	v_fmac_f32_e32 v180, v105, v105
	v_fmac_f32_e32 v181, v109, v109
	v_fmac_f32_e32 v182, v113, v113
	v_fmac_f32_e32 v183, v117, v117
	v_fmac_f32_e32 v180, v106, v106
	v_fmac_f32_e32 v181, v110, v110
	v_fmac_f32_e32 v182, v114, v114
	v_fmac_f32_e32 v183, v118, v118
	v_fmac_f32_e32 v180, v107, v107
	v_fmac_f32_e32 v181, v111, v111
	v_fmac_f32_e32 v182, v115, v115
	v_fmac_f32_e32 v183, v119, v119
	v_add_f32_e32 v180, v180, v181
	v_add_f32_e32 v182, v182, v183
	v_add_f32_e32 v180, v180, v182
	s_nop 1
	v_add_f32_dpp v180, v180, v180 quad_perm:[1,0,3,2] row_mask:0xf bank_mask:0xf
	s_nop 1
	v_add_f32_dpp v180, v180, v180 quad_perm:[2,3,0,1] row_mask:0xf bank_mask:0xf
	s_nop 1
	v_add_f32_dpp v180, v180, v180 row_half_mirror row_mask:0xf bank_mask:0xf
	s_nop 1
	v_add_f32_dpp v180, v180, v180 row_mirror row_mask:0xf bank_mask:0xf
	s_nop 1
	v_add_f32_dpp v180, v180, v180 row_bcast:15 row_mask:0xa bank_mask:0xf
	s_nop 1
	v_add_f32_dpp v180, v180, v180 row_bcast:31 row_mask:0xc bank_mask:0xf
	s_nop 0
	v_readlane_b32 s20, v180, 63
	s_nop 1
	v_mov_b32_e32 v185, s20
	v_fma_f32 v185, v185, v2, v4
	v_rsq_f32_e32 v185, v185
	s_nop 0
	v_mul_f32_e32 v104, v104, v185
	v_mul_f32_e32 v105, v105, v185
	v_mul_f32_e32 v106, v106, v185
	v_mul_f32_e32 v107, v107, v185
	v_mul_f32_e32 v108, v108, v185
	v_mul_f32_e32 v109, v109, v185
	v_mul_f32_e32 v110, v110, v185
	v_mul_f32_e32 v111, v111, v185
	v_mul_f32_e32 v112, v112, v185
	v_mul_f32_e32 v113, v113, v185
	v_mul_f32_e32 v114, v114, v185
	v_mul_f32_e32 v115, v115, v185
	v_mul_f32_e32 v116, v116, v185
	v_mul_f32_e32 v117, v117, v185
	v_mul_f32_e32 v118, v118, v185
	v_mul_f32_e32 v119, v119, v185
	v_fma_f32 v104, v104, v8, v24
	v_fma_f32 v105, v105, v9, v25
	v_fma_f32 v106, v106, v10, v26
	v_fma_f32 v107, v107, v11, v27
	v_fma_f32 v108, v108, v12, v28
	v_fma_f32 v109, v109, v13, v29
	v_fma_f32 v110, v110, v14, v30
	v_fma_f32 v111, v111, v15, v31
	v_fma_f32 v112, v112, v16, v32
	v_fma_f32 v113, v113, v17, v33
	v_fma_f32 v114, v114, v18, v34
	v_fma_f32 v115, v115, v19, v35
	v_fma_f32 v116, v116, v20, v36
	v_fma_f32 v117, v117, v21, v37
	v_fma_f32 v118, v118, v22, v38
	v_fma_f32 v119, v119, v23, v39
	v_add_u32_e32 v171, 0x4000, v1
	global_store_dwordx4 v171, v[104:107], s[4:5]
	global_store_dwordx4 v171, v[108:111], s[4:5] offset:1024
	global_store_dwordx4 v171, v[112:115], s[4:5] offset:2048
	global_store_dwordx4 v171, v[116:119], s[4:5] offset:3072
	s_waitcnt vmcnt(36)
	v_add_f32_e32 v180, v120, v121
	v_add_f32_e32 v181, v124, v125
	v_add_f32_e32 v182, v128, v129
	v_add_f32_e32 v183, v132, v133
	v_add_f32_e32 v180, v180, v122
	v_add_f32_e32 v181, v181, v126
	v_add_f32_e32 v182, v182, v130
	v_add_f32_e32 v183, v183, v134
	v_add_f32_e32 v180, v180, v123
	v_add_f32_e32 v181, v181, v127
	v_add_f32_e32 v182, v182, v131
	v_add_f32_e32 v183, v183, v135
	v_add_f32_e32 v180, v180, v181
	v_add_f32_e32 v182, v182, v183
	v_add_f32_e32 v180, v180, v182
	s_nop 1
	v_add_f32_dpp v180, v180, v180 quad_perm:[1,0,3,2] row_mask:0xf bank_mask:0xf
	s_nop 1
	v_add_f32_dpp v180, v180, v180 quad_perm:[2,3,0,1] row_mask:0xf bank_mask:0xf
	s_nop 1
	v_add_f32_dpp v180, v180, v180 row_half_mirror row_mask:0xf bank_mask:0xf
	s_nop 1
	v_add_f32_dpp v180, v180, v180 row_mirror row_mask:0xf bank_mask:0xf
	s_nop 1
	v_add_f32_dpp v180, v180, v180 row_bcast:15 row_mask:0xa bank_mask:0xf
	s_nop 1
	v_add_f32_dpp v180, v180, v180 row_bcast:31 row_mask:0xc bank_mask:0xf
	s_nop 0
	v_readlane_b32 s20, v180, 63
	s_nop 1
	v_mul_f32_e32 v184, s20, v2
	v_sub_f32_e32 v120, v120, v184
	v_sub_f32_e32 v121, v121, v184
	v_sub_f32_e32 v122, v122, v184
	v_sub_f32_e32 v123, v123, v184
	v_sub_f32_e32 v124, v124, v184
	v_sub_f32_e32 v125, v125, v184
	v_sub_f32_e32 v126, v126, v184
	v_sub_f32_e32 v127, v127, v184
	v_sub_f32_e32 v128, v128, v184
	v_sub_f32_e32 v129, v129, v184
	v_sub_f32_e32 v130, v130, v184
	v_sub_f32_e32 v131, v131, v184
	v_sub_f32_e32 v132, v132, v184
	v_sub_f32_e32 v133, v133, v184
	v_sub_f32_e32 v134, v134, v184
	v_sub_f32_e32 v135, v135, v184
	v_mul_f32_e32 v180, v120, v120
	v_mul_f32_e32 v181, v124, v124
	v_mul_f32_e32 v182, v128, v128
	v_mul_f32_e32 v183, v132, v132
	v_fmac_f32_e32 v180, v121, v121
	v_fmac_f32_e32 v181, v125, v125
	v_fmac_f32_e32 v182, v129, v129
	v_fmac_f32_e32 v183, v133, v133
	v_fmac_f32_e32 v180, v122, v122
	v_fmac_f32_e32 v181, v126, v126
	v_fmac_f32_e32 v182, v130, v130
	v_fmac_f32_e32 v183, v134, v134
	v_fmac_f32_e32 v180, v123, v123
	v_fmac_f32_e32 v181, v127, v127
	v_fmac_f32_e32 v182, v131, v131
	v_fmac_f32_e32 v183, v135, v135
	v_add_f32_e32 v180, v180, v181
	v_add_f32_e32 v182, v182, v183
	v_add_f32_e32 v180, v180, v182
	s_nop 1
	v_add_f32_dpp v180, v180, v180 quad_perm:[1,0,3,2] row_mask:0xf bank_mask:0xf
	s_nop 1
	v_add_f32_dpp v180, v180, v180 quad_perm:[2,3,0,1] row_mask:0xf bank_mask:0xf
	s_nop 1
	v_add_f32_dpp v180, v180, v180 row_half_mirror row_mask:0xf bank_mask:0xf
	s_nop 1
	v_add_f32_dpp v180, v180, v180 row_mirror row_mask:0xf bank_mask:0xf
	s_nop 1
	v_add_f32_dpp v180, v180, v180 row_bcast:15 row_mask:0xa bank_mask:0xf
	s_nop 1
	v_add_f32_dpp v180, v180, v180 row_bcast:31 row_mask:0xc bank_mask:0xf
	s_nop 0
	v_readlane_b32 s20, v180, 63
	s_nop 1
	v_mov_b32_e32 v185, s20
	v_fma_f32 v185, v185, v2, v4
	v_rsq_f32_e32 v185, v185
	s_nop 0
	v_mul_f32_e32 v120, v120, v185
	v_mul_f32_e32 v121, v121, v185
	v_mul_f32_e32 v122, v122, v185
	v_mul_f32_e32 v123, v123, v185
	v_mul_f32_e32 v124, v124, v185
	v_mul_f32_e32 v125, v125, v185
	v_mul_f32_e32 v126, v126, v185
	v_mul_f32_e32 v127, v127, v185
	v_mul_f32_e32 v128, v128, v185
	v_mul_f32_e32 v129, v129, v185
	v_mul_f32_e32 v130, v130, v185
	v_mul_f32_e32 v131, v131, v185
	v_mul_f32_e32 v132, v132, v185
	v_mul_f32_e32 v133, v133, v185
	v_mul_f32_e32 v134, v134, v185
	v_mul_f32_e32 v135, v135, v185
	v_fma_f32 v120, v120, v8, v24
	v_fma_f32 v121, v121, v9, v25
	v_fma_f32 v122, v122, v10, v26
	v_fma_f32 v123, v123, v11, v27
	v_fma_f32 v124, v124, v12, v28
	v_fma_f32 v125, v125, v13, v29
	v_fma_f32 v126, v126, v14, v30
	v_fma_f32 v127, v127, v15, v31
	v_fma_f32 v128, v128, v16, v32
	v_fma_f32 v129, v129, v17, v33
	v_fma_f32 v130, v130, v18, v34
	v_fma_f32 v131, v131, v19, v35
	v_fma_f32 v132, v132, v20, v36
	v_fma_f32 v133, v133, v21, v37
	v_fma_f32 v134, v134, v22, v38
	v_fma_f32 v135, v135, v23, v39
	v_add_u32_e32 v171, 0x5000, v1
	global_store_dwordx4 v171, v[120:123], s[4:5]
	global_store_dwordx4 v171, v[124:127], s[4:5] offset:1024
	global_store_dwordx4 v171, v[128:131], s[4:5] offset:2048
	global_store_dwordx4 v171, v[132:135], s[4:5] offset:3072
	s_waitcnt vmcnt(36)
	v_add_f32_e32 v180, v136, v137
	v_add_f32_e32 v181, v140, v141
	v_add_f32_e32 v182, v144, v145
	v_add_f32_e32 v183, v148, v149
	v_add_f32_e32 v180, v180, v138
	v_add_f32_e32 v181, v181, v142
	v_add_f32_e32 v182, v182, v146
	v_add_f32_e32 v183, v183, v150
	v_add_f32_e32 v180, v180, v139
	v_add_f32_e32 v181, v181, v143
	v_add_f32_e32 v182, v182, v147
	v_add_f32_e32 v183, v183, v151
	v_add_f32_e32 v180, v180, v181
	v_add_f32_e32 v182, v182, v183
	v_add_f32_e32 v180, v180, v182
	s_nop 1
	v_add_f32_dpp v180, v180, v180 quad_perm:[1,0,3,2] row_mask:0xf bank_mask:0xf
	s_nop 1
	v_add_f32_dpp v180, v180, v180 quad_perm:[2,3,0,1] row_mask:0xf bank_mask:0xf
	s_nop 1
	v_add_f32_dpp v180, v180, v180 row_half_mirror row_mask:0xf bank_mask:0xf
	s_nop 1
	v_add_f32_dpp v180, v180, v180 row_mirror row_mask:0xf bank_mask:0xf
	s_nop 1
	v_add_f32_dpp v180, v180, v180 row_bcast:15 row_mask:0xa bank_mask:0xf
	s_nop 1
	v_add_f32_dpp v180, v180, v180 row_bcast:31 row_mask:0xc bank_mask:0xf
	s_nop 0
	v_readlane_b32 s20, v180, 63
	s_nop 1
	v_mul_f32_e32 v184, s20, v2
	v_sub_f32_e32 v136, v136, v184
	v_sub_f32_e32 v137, v137, v184
	v_sub_f32_e32 v138, v138, v184
	v_sub_f32_e32 v139, v139, v184
	v_sub_f32_e32 v140, v140, v184
	v_sub_f32_e32 v141, v141, v184
	v_sub_f32_e32 v142, v142, v184
	v_sub_f32_e32 v143, v143, v184
	v_sub_f32_e32 v144, v144, v184
	v_sub_f32_e32 v145, v145, v184
	v_sub_f32_e32 v146, v146, v184
	v_sub_f32_e32 v147, v147, v184
	v_sub_f32_e32 v148, v148, v184
	v_sub_f32_e32 v149, v149, v184
	v_sub_f32_e32 v150, v150, v184
	v_sub_f32_e32 v151, v151, v184
	v_mul_f32_e32 v180, v136, v136
	v_mul_f32_e32 v181, v140, v140
	v_mul_f32_e32 v182, v144, v144
	v_mul_f32_e32 v183, v148, v148
	v_fmac_f32_e32 v180, v137, v137
	v_fmac_f32_e32 v181, v141, v141
	v_fmac_f32_e32 v182, v145, v145
	v_fmac_f32_e32 v183, v149, v149
	v_fmac_f32_e32 v180, v138, v138
	v_fmac_f32_e32 v181, v142, v142
	v_fmac_f32_e32 v182, v146, v146
	v_fmac_f32_e32 v183, v150, v150
	v_fmac_f32_e32 v180, v139, v139
	v_fmac_f32_e32 v181, v143, v143
	v_fmac_f32_e32 v182, v147, v147
	v_fmac_f32_e32 v183, v151, v151
	v_add_f32_e32 v180, v180, v181
	v_add_f32_e32 v182, v182, v183
	v_add_f32_e32 v180, v180, v182
	s_nop 1
	v_add_f32_dpp v180, v180, v180 quad_perm:[1,0,3,2] row_mask:0xf bank_mask:0xf
	s_nop 1
	v_add_f32_dpp v180, v180, v180 quad_perm:[2,3,0,1] row_mask:0xf bank_mask:0xf
	s_nop 1
	v_add_f32_dpp v180, v180, v180 row_half_mirror row_mask:0xf bank_mask:0xf
	s_nop 1
	v_add_f32_dpp v180, v180, v180 row_mirror row_mask:0xf bank_mask:0xf
	s_nop 1
	v_add_f32_dpp v180, v180, v180 row_bcast:15 row_mask:0xa bank_mask:0xf
	s_nop 1
	v_add_f32_dpp v180, v180, v180 row_bcast:31 row_mask:0xc bank_mask:0xf
	s_nop 0
	v_readlane_b32 s20, v180, 63
	s_nop 1
	v_mov_b32_e32 v185, s20
	v_fma_f32 v185, v185, v2, v4
	v_rsq_f32_e32 v185, v185
	s_nop 0
	v_mul_f32_e32 v136, v136, v185
	v_mul_f32_e32 v137, v137, v185
	v_mul_f32_e32 v138, v138, v185
	v_mul_f32_e32 v139, v139, v185
	v_mul_f32_e32 v140, v140, v185
	v_mul_f32_e32 v141, v141, v185
	v_mul_f32_e32 v142, v142, v185
	v_mul_f32_e32 v143, v143, v185
	v_mul_f32_e32 v144, v144, v185
	v_mul_f32_e32 v145, v145, v185
	v_mul_f32_e32 v146, v146, v185
	v_mul_f32_e32 v147, v147, v185
	v_mul_f32_e32 v148, v148, v185
	v_mul_f32_e32 v149, v149, v185
	v_mul_f32_e32 v150, v150, v185
	v_mul_f32_e32 v151, v151, v185
	v_fma_f32 v136, v136, v8, v24
	v_fma_f32 v137, v137, v9, v25
	v_fma_f32 v138, v138, v10, v26
	v_fma_f32 v139, v139, v11, v27
	v_fma_f32 v140, v140, v12, v28
	v_fma_f32 v141, v141, v13, v29
	v_fma_f32 v142, v142, v14, v30
	v_fma_f32 v143, v143, v15, v31
	v_fma_f32 v144, v144, v16, v32
	v_fma_f32 v145, v145, v17, v33
	v_fma_f32 v146, v146, v18, v34
	v_fma_f32 v147, v147, v19, v35
	v_fma_f32 v148, v148, v20, v36
	v_fma_f32 v149, v149, v21, v37
	v_fma_f32 v150, v150, v22, v38
	v_fma_f32 v151, v151, v23, v39
	v_add_u32_e32 v171, 0x6000, v1
	global_store_dwordx4 v171, v[136:139], s[4:5]
	global_store_dwordx4 v171, v[140:143], s[4:5] offset:1024
	global_store_dwordx4 v171, v[144:147], s[4:5] offset:2048
	global_store_dwordx4 v171, v[148:151], s[4:5] offset:3072
	s_waitcnt vmcnt(36)
	v_add_f32_e32 v180, v152, v153
	v_add_f32_e32 v181, v156, v157
	v_add_f32_e32 v182, v160, v161
	v_add_f32_e32 v183, v164, v165
	v_add_f32_e32 v180, v180, v154
	v_add_f32_e32 v181, v181, v158
	v_add_f32_e32 v182, v182, v162
	v_add_f32_e32 v183, v183, v166
	v_add_f32_e32 v180, v180, v155
	v_add_f32_e32 v181, v181, v159
	v_add_f32_e32 v182, v182, v163
	v_add_f32_e32 v183, v183, v167
	v_add_f32_e32 v180, v180, v181
	v_add_f32_e32 v182, v182, v183
	v_add_f32_e32 v180, v180, v182
	s_nop 1
	v_add_f32_dpp v180, v180, v180 quad_perm:[1,0,3,2] row_mask:0xf bank_mask:0xf
	s_nop 1
	v_add_f32_dpp v180, v180, v180 quad_perm:[2,3,0,1] row_mask:0xf bank_mask:0xf
	s_nop 1
	v_add_f32_dpp v180, v180, v180 row_half_mirror row_mask:0xf bank_mask:0xf
	s_nop 1
	v_add_f32_dpp v180, v180, v180 row_mirror row_mask:0xf bank_mask:0xf
	s_nop 1
	v_add_f32_dpp v180, v180, v180 row_bcast:15 row_mask:0xa bank_mask:0xf
	s_nop 1
	v_add_f32_dpp v180, v180, v180 row_bcast:31 row_mask:0xc bank_mask:0xf
	s_nop 0
	v_readlane_b32 s20, v180, 63
	s_nop 1
	v_mul_f32_e32 v184, s20, v2
	v_sub_f32_e32 v152, v152, v184
	v_sub_f32_e32 v153, v153, v184
	v_sub_f32_e32 v154, v154, v184
	v_sub_f32_e32 v155, v155, v184
	v_sub_f32_e32 v156, v156, v184
	v_sub_f32_e32 v157, v157, v184
	v_sub_f32_e32 v158, v158, v184
	v_sub_f32_e32 v159, v159, v184
	v_sub_f32_e32 v160, v160, v184
	v_sub_f32_e32 v161, v161, v184
	v_sub_f32_e32 v162, v162, v184
	v_sub_f32_e32 v163, v163, v184
	v_sub_f32_e32 v164, v164, v184
	v_sub_f32_e32 v165, v165, v184
	v_sub_f32_e32 v166, v166, v184
	v_sub_f32_e32 v167, v167, v184
	v_mul_f32_e32 v180, v152, v152
	v_mul_f32_e32 v181, v156, v156
	v_mul_f32_e32 v182, v160, v160
	v_mul_f32_e32 v183, v164, v164
	v_fmac_f32_e32 v180, v153, v153
	v_fmac_f32_e32 v181, v157, v157
	v_fmac_f32_e32 v182, v161, v161
	v_fmac_f32_e32 v183, v165, v165
	v_fmac_f32_e32 v180, v154, v154
	v_fmac_f32_e32 v181, v158, v158
	v_fmac_f32_e32 v182, v162, v162
	v_fmac_f32_e32 v183, v166, v166
	v_fmac_f32_e32 v180, v155, v155
	v_fmac_f32_e32 v181, v159, v159
	v_fmac_f32_e32 v182, v163, v163
	v_fmac_f32_e32 v183, v167, v167
	v_add_f32_e32 v180, v180, v181
	v_add_f32_e32 v182, v182, v183
	v_add_f32_e32 v180, v180, v182
	s_nop 1
	v_add_f32_dpp v180, v180, v180 quad_perm:[1,0,3,2] row_mask:0xf bank_mask:0xf
	s_nop 1
	v_add_f32_dpp v180, v180, v180 quad_perm:[2,3,0,1] row_mask:0xf bank_mask:0xf
	s_nop 1
	v_add_f32_dpp v180, v180, v180 row_half_mirror row_mask:0xf bank_mask:0xf
	s_nop 1
	v_add_f32_dpp v180, v180, v180 row_mirror row_mask:0xf bank_mask:0xf
	s_nop 1
	v_add_f32_dpp v180, v180, v180 row_bcast:15 row_mask:0xa bank_mask:0xf
	s_nop 1
	v_add_f32_dpp v180, v180, v180 row_bcast:31 row_mask:0xc bank_mask:0xf
	s_nop 0
	v_readlane_b32 s20, v180, 63
	s_nop 1
	v_mov_b32_e32 v185, s20
	v_fma_f32 v185, v185, v2, v4
	v_rsq_f32_e32 v185, v185
	s_nop 0
	v_mul_f32_e32 v152, v152, v185
	v_mul_f32_e32 v153, v153, v185
	v_mul_f32_e32 v154, v154, v185
	v_mul_f32_e32 v155, v155, v185
	v_mul_f32_e32 v156, v156, v185
	v_mul_f32_e32 v157, v157, v185
	v_mul_f32_e32 v158, v158, v185
	v_mul_f32_e32 v159, v159, v185
	v_mul_f32_e32 v160, v160, v185
	v_mul_f32_e32 v161, v161, v185
	v_mul_f32_e32 v162, v162, v185
	v_mul_f32_e32 v163, v163, v185
	v_mul_f32_e32 v164, v164, v185
	v_mul_f32_e32 v165, v165, v185
	v_mul_f32_e32 v166, v166, v185
	v_mul_f32_e32 v167, v167, v185
	v_fma_f32 v152, v152, v8, v24
	v_fma_f32 v153, v153, v9, v25
	v_fma_f32 v154, v154, v10, v26
	v_fma_f32 v155, v155, v11, v27
	v_fma_f32 v156, v156, v12, v28
	v_fma_f32 v157, v157, v13, v29
	v_fma_f32 v158, v158, v14, v30
	v_fma_f32 v159, v159, v15, v31
	v_fma_f32 v160, v160, v16, v32
	v_fma_f32 v161, v161, v17, v33
	v_fma_f32 v162, v162, v18, v34
	v_fma_f32 v163, v163, v19, v35
	v_fma_f32 v164, v164, v20, v36
	v_fma_f32 v165, v165, v21, v37
	v_fma_f32 v166, v166, v22, v38
	v_fma_f32 v167, v167, v23, v39
	v_add_u32_e32 v171, 0x7000, v1
	global_store_dwordx4 v171, v[152:155], s[4:5]
	global_store_dwordx4 v171, v[156:159], s[4:5] offset:1024
	global_store_dwordx4 v171, v[160:163], s[4:5] offset:2048
	global_store_dwordx4 v171, v[164:167], s[4:5] offset:3072
	s_waitcnt vmcnt(32)
	v_add_f32_e32 v180, v40, v41
	v_add_f32_e32 v181, v44, v45
	v_add_f32_e32 v182, v48, v49
	v_add_f32_e32 v183, v52, v53
	v_add_f32_e32 v180, v180, v42
	v_add_f32_e32 v181, v181, v46
	v_add_f32_e32 v182, v182, v50
	v_add_f32_e32 v183, v183, v54
	v_add_f32_e32 v180, v180, v43
	v_add_f32_e32 v181, v181, v47
	v_add_f32_e32 v182, v182, v51
	v_add_f32_e32 v183, v183, v55
	v_add_f32_e32 v180, v180, v181
	v_add_f32_e32 v182, v182, v183
	v_add_f32_e32 v180, v180, v182
	s_nop 1
	v_add_f32_dpp v180, v180, v180 quad_perm:[1,0,3,2] row_mask:0xf bank_mask:0xf
	s_nop 1
	v_add_f32_dpp v180, v180, v180 quad_perm:[2,3,0,1] row_mask:0xf bank_mask:0xf
	s_nop 1
	v_add_f32_dpp v180, v180, v180 row_half_mirror row_mask:0xf bank_mask:0xf
	s_nop 1
	v_add_f32_dpp v180, v180, v180 row_mirror row_mask:0xf bank_mask:0xf
	s_nop 1
	v_add_f32_dpp v180, v180, v180 row_bcast:15 row_mask:0xa bank_mask:0xf
	s_nop 1
	v_add_f32_dpp v180, v180, v180 row_bcast:31 row_mask:0xc bank_mask:0xf
	s_nop 0
	v_readlane_b32 s20, v180, 63
	s_nop 1
	v_mul_f32_e32 v184, s20, v2
	v_sub_f32_e32 v40, v40, v184
	v_sub_f32_e32 v41, v41, v184
	v_sub_f32_e32 v42, v42, v184
	v_sub_f32_e32 v43, v43, v184
	v_sub_f32_e32 v44, v44, v184
	v_sub_f32_e32 v45, v45, v184
	v_sub_f32_e32 v46, v46, v184
	v_sub_f32_e32 v47, v47, v184
	v_sub_f32_e32 v48, v48, v184
	v_sub_f32_e32 v49, v49, v184
	v_sub_f32_e32 v50, v50, v184
	v_sub_f32_e32 v51, v51, v184
	v_sub_f32_e32 v52, v52, v184
	v_sub_f32_e32 v53, v53, v184
	v_sub_f32_e32 v54, v54, v184
	v_sub_f32_e32 v55, v55, v184
	v_mul_f32_e32 v180, v40, v40
	v_mul_f32_e32 v181, v44, v44
	v_mul_f32_e32 v182, v48, v48
	v_mul_f32_e32 v183, v52, v52
	v_fmac_f32_e32 v180, v41, v41
	v_fmac_f32_e32 v181, v45, v45
	v_fmac_f32_e32 v182, v49, v49
	v_fmac_f32_e32 v183, v53, v53
	v_fmac_f32_e32 v180, v42, v42
	v_fmac_f32_e32 v181, v46, v46
	v_fmac_f32_e32 v182, v50, v50
	v_fmac_f32_e32 v183, v54, v54
	v_fmac_f32_e32 v180, v43, v43
	v_fmac_f32_e32 v181, v47, v47
	v_fmac_f32_e32 v182, v51, v51
	v_fmac_f32_e32 v183, v55, v55
	v_add_f32_e32 v180, v180, v181
	v_add_f32_e32 v182, v182, v183
	v_add_f32_e32 v180, v180, v182
	s_nop 1
	v_add_f32_dpp v180, v180, v180 quad_perm:[1,0,3,2] row_mask:0xf bank_mask:0xf
	s_nop 1
	v_add_f32_dpp v180, v180, v180 quad_perm:[2,3,0,1] row_mask:0xf bank_mask:0xf
	s_nop 1
	v_add_f32_dpp v180, v180, v180 row_half_mirror row_mask:0xf bank_mask:0xf
	s_nop 1
	v_add_f32_dpp v180, v180, v180 row_mirror row_mask:0xf bank_mask:0xf
	s_nop 1
	v_add_f32_dpp v180, v180, v180 row_bcast:15 row_mask:0xa bank_mask:0xf
	s_nop 1
	v_add_f32_dpp v180, v180, v180 row_bcast:31 row_mask:0xc bank_mask:0xf
	s_nop 0
	v_readlane_b32 s20, v180, 63
	s_nop 1
	v_mov_b32_e32 v185, s20
	v_fma_f32 v185, v185, v2, v4
	v_rsq_f32_e32 v185, v185
	s_nop 0
	v_mul_f32_e32 v40, v40, v185
	v_mul_f32_e32 v41, v41, v185
	v_mul_f32_e32 v42, v42, v185
	v_mul_f32_e32 v43, v43, v185
	v_mul_f32_e32 v44, v44, v185
	v_mul_f32_e32 v45, v45, v185
	v_mul_f32_e32 v46, v46, v185
	v_mul_f32_e32 v47, v47, v185
	v_mul_f32_e32 v48, v48, v185
	v_mul_f32_e32 v49, v49, v185
	v_mul_f32_e32 v50, v50, v185
	v_mul_f32_e32 v51, v51, v185
	v_mul_f32_e32 v52, v52, v185
	v_mul_f32_e32 v53, v53, v185
	v_mul_f32_e32 v54, v54, v185
	v_mul_f32_e32 v55, v55, v185
	v_fma_f32 v40, v40, v8, v24
	v_fma_f32 v41, v41, v9, v25
	v_fma_f32 v42, v42, v10, v26
	v_fma_f32 v43, v43, v11, v27
	v_fma_f32 v44, v44, v12, v28
	v_fma_f32 v45, v45, v13, v29
	v_fma_f32 v46, v46, v14, v30
	v_fma_f32 v47, v47, v15, v31
	v_fma_f32 v48, v48, v16, v32
	v_fma_f32 v49, v49, v17, v33
	v_fma_f32 v50, v50, v18, v34
	v_fma_f32 v51, v51, v19, v35
	v_fma_f32 v52, v52, v20, v36
	v_fma_f32 v53, v53, v21, v37
	v_fma_f32 v54, v54, v22, v38
	v_fma_f32 v55, v55, v23, v39
	v_add_u32_e32 v171, 0x8000, v1
	global_store_dwordx4 v171, v[40:43], s[4:5]
	global_store_dwordx4 v171, v[44:47], s[4:5] offset:1024
	global_store_dwordx4 v171, v[48:51], s[4:5] offset:2048
	global_store_dwordx4 v171, v[52:55], s[4:5] offset:3072
	s_waitcnt vmcnt(28)
	v_add_f32_e32 v180, v56, v57
	v_add_f32_e32 v181, v60, v61
	v_add_f32_e32 v182, v64, v65
	v_add_f32_e32 v183, v68, v69
	v_add_f32_e32 v180, v180, v58
	v_add_f32_e32 v181, v181, v62
	v_add_f32_e32 v182, v182, v66
	v_add_f32_e32 v183, v183, v70
	v_add_f32_e32 v180, v180, v59
	v_add_f32_e32 v181, v181, v63
	v_add_f32_e32 v182, v182, v67
	v_add_f32_e32 v183, v183, v71
	v_add_f32_e32 v180, v180, v181
	v_add_f32_e32 v182, v182, v183
	v_add_f32_e32 v180, v180, v182
	s_nop 1
	v_add_f32_dpp v180, v180, v180 quad_perm:[1,0,3,2] row_mask:0xf bank_mask:0xf
	s_nop 1
	v_add_f32_dpp v180, v180, v180 quad_perm:[2,3,0,1] row_mask:0xf bank_mask:0xf
	s_nop 1
	v_add_f32_dpp v180, v180, v180 row_half_mirror row_mask:0xf bank_mask:0xf
	s_nop 1
	v_add_f32_dpp v180, v180, v180 row_mirror row_mask:0xf bank_mask:0xf
	s_nop 1
	v_add_f32_dpp v180, v180, v180 row_bcast:15 row_mask:0xa bank_mask:0xf
	s_nop 1
	v_add_f32_dpp v180, v180, v180 row_bcast:31 row_mask:0xc bank_mask:0xf
	s_nop 0
	v_readlane_b32 s20, v180, 63
	s_nop 1
	v_mul_f32_e32 v184, s20, v2
	v_sub_f32_e32 v56, v56, v184
	v_sub_f32_e32 v57, v57, v184
	v_sub_f32_e32 v58, v58, v184
	v_sub_f32_e32 v59, v59, v184
	v_sub_f32_e32 v60, v60, v184
	v_sub_f32_e32 v61, v61, v184
	v_sub_f32_e32 v62, v62, v184
	v_sub_f32_e32 v63, v63, v184
	v_sub_f32_e32 v64, v64, v184
	v_sub_f32_e32 v65, v65, v184
	v_sub_f32_e32 v66, v66, v184
	v_sub_f32_e32 v67, v67, v184
	v_sub_f32_e32 v68, v68, v184
	v_sub_f32_e32 v69, v69, v184
	v_sub_f32_e32 v70, v70, v184
	v_sub_f32_e32 v71, v71, v184
	v_mul_f32_e32 v180, v56, v56
	v_mul_f32_e32 v181, v60, v60
	v_mul_f32_e32 v182, v64, v64
	v_mul_f32_e32 v183, v68, v68
	v_fmac_f32_e32 v180, v57, v57
	v_fmac_f32_e32 v181, v61, v61
	v_fmac_f32_e32 v182, v65, v65
	v_fmac_f32_e32 v183, v69, v69
	v_fmac_f32_e32 v180, v58, v58
	v_fmac_f32_e32 v181, v62, v62
	v_fmac_f32_e32 v182, v66, v66
	v_fmac_f32_e32 v183, v70, v70
	v_fmac_f32_e32 v180, v59, v59
	v_fmac_f32_e32 v181, v63, v63
	v_fmac_f32_e32 v182, v67, v67
	v_fmac_f32_e32 v183, v71, v71
	v_add_f32_e32 v180, v180, v181
	v_add_f32_e32 v182, v182, v183
	v_add_f32_e32 v180, v180, v182
	s_nop 1
	v_add_f32_dpp v180, v180, v180 quad_perm:[1,0,3,2] row_mask:0xf bank_mask:0xf
	s_nop 1
	v_add_f32_dpp v180, v180, v180 quad_perm:[2,3,0,1] row_mask:0xf bank_mask:0xf
	s_nop 1
	v_add_f32_dpp v180, v180, v180 row_half_mirror row_mask:0xf bank_mask:0xf
	s_nop 1
	v_add_f32_dpp v180, v180, v180 row_mirror row_mask:0xf bank_mask:0xf
	s_nop 1
	v_add_f32_dpp v180, v180, v180 row_bcast:15 row_mask:0xa bank_mask:0xf
	s_nop 1
	v_add_f32_dpp v180, v180, v180 row_bcast:31 row_mask:0xc bank_mask:0xf
	s_nop 0
	v_readlane_b32 s20, v180, 63
	s_nop 1
	v_mov_b32_e32 v185, s20
	v_fma_f32 v185, v185, v2, v4
	v_rsq_f32_e32 v185, v185
	s_nop 0
	v_mul_f32_e32 v56, v56, v185
	v_mul_f32_e32 v57, v57, v185
	v_mul_f32_e32 v58, v58, v185
	v_mul_f32_e32 v59, v59, v185
	v_mul_f32_e32 v60, v60, v185
	v_mul_f32_e32 v61, v61, v185
	v_mul_f32_e32 v62, v62, v185
	v_mul_f32_e32 v63, v63, v185
	v_mul_f32_e32 v64, v64, v185
	v_mul_f32_e32 v65, v65, v185
	v_mul_f32_e32 v66, v66, v185
	v_mul_f32_e32 v67, v67, v185
	v_mul_f32_e32 v68, v68, v185
	v_mul_f32_e32 v69, v69, v185
	v_mul_f32_e32 v70, v70, v185
	v_mul_f32_e32 v71, v71, v185
	v_fma_f32 v56, v56, v8, v24
	v_fma_f32 v57, v57, v9, v25
	v_fma_f32 v58, v58, v10, v26
	v_fma_f32 v59, v59, v11, v27
	v_fma_f32 v60, v60, v12, v28
	v_fma_f32 v61, v61, v13, v29
	v_fma_f32 v62, v62, v14, v30
	v_fma_f32 v63, v63, v15, v31
	v_fma_f32 v64, v64, v16, v32
	v_fma_f32 v65, v65, v17, v33
	v_fma_f32 v66, v66, v18, v34
	v_fma_f32 v67, v67, v19, v35
	v_fma_f32 v68, v68, v20, v36
	v_fma_f32 v69, v69, v21, v37
	v_fma_f32 v70, v70, v22, v38
	v_fma_f32 v71, v71, v23, v39
	v_add_u32_e32 v171, 0x9000, v1
	global_store_dwordx4 v171, v[56:59], s[4:5]
	global_store_dwordx4 v171, v[60:63], s[4:5] offset:1024
	global_store_dwordx4 v171, v[64:67], s[4:5] offset:2048
	global_store_dwordx4 v171, v[68:71], s[4:5] offset:3072
	s_branch .Ltr_29

.Llo_even:
	s_lshl_b32 s1, s86, 3
	s_add_i32 s0, s0, s1
	s_lshl_b32 s0, s0, 15
	s_add_u32 s4, s4, s0
	s_addc_u32 s5, s5, 0
	global_load_dwordx4 v[40:43], v1, s[4:5]
	global_load_dwordx4 v[44:47], v1, s[4:5] offset:1024
	global_load_dwordx4 v[48:51], v1, s[4:5] offset:2048
	global_load_dwordx4 v[52:55], v1, s[4:5] offset:3072
	global_load_dwordx4 v[8:11], v1, s[40:41]
	global_load_dwordx4 v[12:15], v1, s[40:41] offset:1024
	global_load_dwordx4 v[16:19], v1, s[40:41] offset:2048
	global_load_dwordx4 v[20:23], v1, s[40:41] offset:3072
	global_load_dwordx4 v[24:27], v1, s[42:43]
	global_load_dwordx4 v[28:31], v1, s[42:43] offset:1024
	global_load_dwordx4 v[32:35], v1, s[42:43] offset:2048
	global_load_dwordx4 v[36:39], v1, s[42:43] offset:3072
	v_add_u32_e32 v170, 0x1000, v1
	global_load_dwordx4 v[56:59], v170, s[4:5]
	global_load_dwordx4 v[60:63], v170, s[4:5] offset:1024
	global_load_dwordx4 v[64:67], v170, s[4:5] offset:2048
	global_load_dwordx4 v[68:71], v170, s[4:5] offset:3072
	v_add_u32_e32 v170, 0x2000, v1
	global_load_dwordx4 v[72:75], v170, s[4:5]
	global_load_dwordx4 v[76:79], v170, s[4:5] offset:1024
	global_load_dwordx4 v[80:83], v170, s[4:5] offset:2048
	global_load_dwordx4 v[84:87], v170, s[4:5] offset:3072
	v_add_u32_e32 v170, 0x3000, v1
	global_load_dwordx4 v[88:91], v170, s[4:5]
	global_load_dwordx4 v[92:95], v170, s[4:5] offset:1024
	global_load_dwordx4 v[96:99], v170, s[4:5] offset:2048
	global_load_dwordx4 v[100:103], v170, s[4:5] offset:3072
	v_add_u32_e32 v170, 0x4000, v1
	global_load_dwordx4 v[104:107], v170, s[4:5]
	global_load_dwordx4 v[108:111], v170, s[4:5] offset:1024
	global_load_dwordx4 v[112:115], v170, s[4:5] offset:2048
	global_load_dwordx4 v[116:119], v170, s[4:5] offset:3072
	v_add_u32_e32 v170, 0x5000, v1
	global_load_dwordx4 v[120:123], v170, s[4:5]
	global_load_dwordx4 v[124:127], v170, s[4:5] offset:1024
	global_load_dwordx4 v[128:131], v170, s[4:5] offset:2048
	global_load_dwordx4 v[132:135], v170, s[4:5] offset:3072
	v_add_u32_e32 v170, 0x6000, v1
	global_load_dwordx4 v[136:139], v170, s[4:5]
	global_load_dwordx4 v[140:143], v170, s[4:5] offset:1024
	global_load_dwordx4 v[144:147], v170, s[4:5] offset:2048
	global_load_dwordx4 v[148:151], v170, s[4:5] offset:3072
	v_add_u32_e32 v170, 0x7000, v1
	global_load_dwordx4 v[152:155], v170, s[4:5]
	global_load_dwordx4 v[156:159], v170, s[4:5] offset:1024
	global_load_dwordx4 v[160:163], v170, s[4:5] offset:2048
	global_load_dwordx4 v[164:167], v170, s[4:5] offset:3072
	s_waitcnt vmcnt(36)
	v_add_f32_e32 v180, v40, v41
	v_add_f32_e32 v181, v44, v45
	v_add_f32_e32 v182, v48, v49
	v_add_f32_e32 v183, v52, v53
	v_add_f32_e32 v180, v180, v42
	v_add_f32_e32 v181, v181, v46
	v_add_f32_e32 v182, v182, v50
	v_add_f32_e32 v183, v183, v54
	v_add_f32_e32 v180, v180, v43
	v_add_f32_e32 v181, v181, v47
	v_add_f32_e32 v182, v182, v51
	v_add_f32_e32 v183, v183, v55
	v_add_f32_e32 v180, v180, v181
	v_add_f32_e32 v182, v182, v183
	v_add_f32_e32 v180, v180, v182
	s_nop 1
	v_add_f32_dpp v180, v180, v180 quad_perm:[1,0,3,2] row_mask:0xf bank_mask:0xf
	s_nop 1
	v_add_f32_dpp v180, v180, v180 quad_perm:[2,3,0,1] row_mask:0xf bank_mask:0xf
	s_nop 1
	v_add_f32_dpp v180, v180, v180 row_half_mirror row_mask:0xf bank_mask:0xf
	s_nop 1
	v_add_f32_dpp v180, v180, v180 row_mirror row_mask:0xf bank_mask:0xf
	s_nop 1
	v_add_f32_dpp v180, v180, v180 row_bcast:15 row_mask:0xa bank_mask:0xf
	s_nop 1
	v_add_f32_dpp v180, v180, v180 row_bcast:31 row_mask:0xc bank_mask:0xf
	s_nop 0
	v_readlane_b32 s20, v180, 63
	s_nop 1
	v_mul_f32_e32 v184, s20, v2
	v_sub_f32_e32 v40, v40, v184
	v_sub_f32_e32 v41, v41, v184
	v_sub_f32_e32 v42, v42, v184
	v_sub_f32_e32 v43, v43, v184
	v_sub_f32_e32 v44, v44, v184
	v_sub_f32_e32 v45, v45, v184
	v_sub_f32_e32 v46, v46, v184
	v_sub_f32_e32 v47, v47, v184
	v_sub_f32_e32 v48, v48, v184
	v_sub_f32_e32 v49, v49, v184
	v_sub_f32_e32 v50, v50, v184
	v_sub_f32_e32 v51, v51, v184
	v_sub_f32_e32 v52, v52, v184
	v_sub_f32_e32 v53, v53, v184
	v_sub_f32_e32 v54, v54, v184
	v_sub_f32_e32 v55, v55, v184
	v_mul_f32_e32 v180, v40, v40
	v_mul_f32_e32 v181, v44, v44
	v_mul_f32_e32 v182, v48, v48
	v_mul_f32_e32 v183, v52, v52
	v_fmac_f32_e32 v180, v41, v41
	v_fmac_f32_e32 v181, v45, v45
	v_fmac_f32_e32 v182, v49, v49
	v_fmac_f32_e32 v183, v53, v53
	v_fmac_f32_e32 v180, v42, v42
	v_fmac_f32_e32 v181, v46, v46
	v_fmac_f32_e32 v182, v50, v50
	v_fmac_f32_e32 v183, v54, v54
	v_fmac_f32_e32 v180, v43, v43
	v_fmac_f32_e32 v181, v47, v47
	v_fmac_f32_e32 v182, v51, v51
	v_fmac_f32_e32 v183, v55, v55
	v_add_f32_e32 v180, v180, v181
	v_add_f32_e32 v182, v182, v183
	v_add_f32_e32 v180, v180, v182
	s_nop 1
	v_add_f32_dpp v180, v180, v180 quad_perm:[1,0,3,2] row_mask:0xf bank_mask:0xf
	s_nop 1
	v_add_f32_dpp v180, v180, v180 quad_perm:[2,3,0,1] row_mask:0xf bank_mask:0xf
	s_nop 1
	v_add_f32_dpp v180, v180, v180 row_half_mirror row_mask:0xf bank_mask:0xf
	s_nop 1
	v_add_f32_dpp v180, v180, v180 row_mirror row_mask:0xf bank_mask:0xf
	s_nop 1
	v_add_f32_dpp v180, v180, v180 row_bcast:15 row_mask:0xa bank_mask:0xf
	s_nop 1
	v_add_f32_dpp v180, v180, v180 row_bcast:31 row_mask:0xc bank_mask:0xf
	s_nop 0
	v_readlane_b32 s20, v180, 63
	s_nop 1
	v_mov_b32_e32 v185, s20
	v_fma_f32 v185, v185, v2, v4
	v_rsq_f32_e32 v185, v185
	s_nop 0
	v_mul_f32_e32 v40, v40, v185
	v_mul_f32_e32 v41, v41, v185
	v_mul_f32_e32 v42, v42, v185
	v_mul_f32_e32 v43, v43, v185
	v_mul_f32_e32 v44, v44, v185
	v_mul_f32_e32 v45, v45, v185
	v_mul_f32_e32 v46, v46, v185
	v_mul_f32_e32 v47, v47, v185
	v_mul_f32_e32 v48, v48, v185
	v_mul_f32_e32 v49, v49, v185
	v_mul_f32_e32 v50, v50, v185
	v_mul_f32_e32 v51, v51, v185
	v_mul_f32_e32 v52, v52, v185
	v_mul_f32_e32 v53, v53, v185
	v_mul_f32_e32 v54, v54, v185
	v_mul_f32_e32 v55, v55, v185
	s_waitcnt vmcnt(28)
	v_fma_f32 v40, v40, v8, v24
	v_fma_f32 v41, v41, v9, v25
	v_fma_f32 v42, v42, v10, v26
	v_fma_f32 v43, v43, v11, v27
	v_fma_f32 v44, v44, v12, v28
	v_fma_f32 v45, v45, v13, v29
	v_fma_f32 v46, v46, v14, v30
	v_fma_f32 v47, v47, v15, v31
	v_fma_f32 v48, v48, v16, v32
	v_fma_f32 v49, v49, v17, v33
	v_fma_f32 v50, v50, v18, v34
	v_fma_f32 v51, v51, v19, v35
	v_fma_f32 v52, v52, v20, v36
	v_fma_f32 v53, v53, v21, v37
	v_fma_f32 v54, v54, v22, v38
	v_fma_f32 v55, v55, v23, v39
	global_store_dwordx4 v1, v[40:43], s[4:5]
	global_store_dwordx4 v1, v[44:47], s[4:5] offset:1024
	global_store_dwordx4 v1, v[48:51], s[4:5] offset:2048
	global_store_dwordx4 v1, v[52:55], s[4:5] offset:3072
	s_waitcnt vmcnt(28)
	v_add_f32_e32 v180, v56, v57
	v_add_f32_e32 v181, v60, v61
	v_add_f32_e32 v182, v64, v65
	v_add_f32_e32 v183, v68, v69
	v_add_f32_e32 v180, v180, v58
	v_add_f32_e32 v181, v181, v62
	v_add_f32_e32 v182, v182, v66
	v_add_f32_e32 v183, v183, v70
	v_add_f32_e32 v180, v180, v59
	v_add_f32_e32 v181, v181, v63
	v_add_f32_e32 v182, v182, v67
	v_add_f32_e32 v183, v183, v71
	v_add_f32_e32 v180, v180, v181
	v_add_f32_e32 v182, v182, v183
	v_add_f32_e32 v180, v180, v182
	s_nop 1
	v_add_f32_dpp v180, v180, v180 quad_perm:[1,0,3,2] row_mask:0xf bank_mask:0xf
	s_nop 1
	v_add_f32_dpp v180, v180, v180 quad_perm:[2,3,0,1] row_mask:0xf bank_mask:0xf
	s_nop 1
	v_add_f32_dpp v180, v180, v180 row_half_mirror row_mask:0xf bank_mask:0xf
	s_nop 1
	v_add_f32_dpp v180, v180, v180 row_mirror row_mask:0xf bank_mask:0xf
	s_nop 1
	v_add_f32_dpp v180, v180, v180 row_bcast:15 row_mask:0xa bank_mask:0xf
	s_nop 1
	v_add_f32_dpp v180, v180, v180 row_bcast:31 row_mask:0xc bank_mask:0xf
	s_nop 0
	v_readlane_b32 s20, v180, 63
	s_nop 1
	v_mul_f32_e32 v184, s20, v2
	v_sub_f32_e32 v56, v56, v184
	v_sub_f32_e32 v57, v57, v184
	v_sub_f32_e32 v58, v58, v184
	v_sub_f32_e32 v59, v59, v184
	v_sub_f32_e32 v60, v60, v184
	v_sub_f32_e32 v61, v61, v184
	v_sub_f32_e32 v62, v62, v184
	v_sub_f32_e32 v63, v63, v184
	v_sub_f32_e32 v64, v64, v184
	v_sub_f32_e32 v65, v65, v184
	v_sub_f32_e32 v66, v66, v184
	v_sub_f32_e32 v67, v67, v184
	v_sub_f32_e32 v68, v68, v184
	v_sub_f32_e32 v69, v69, v184
	v_sub_f32_e32 v70, v70, v184
	v_sub_f32_e32 v71, v71, v184
	v_mul_f32_e32 v180, v56, v56
	v_mul_f32_e32 v181, v60, v60
	v_mul_f32_e32 v182, v64, v64
	v_mul_f32_e32 v183, v68, v68
	v_fmac_f32_e32 v180, v57, v57
	v_fmac_f32_e32 v181, v61, v61
	v_fmac_f32_e32 v182, v65, v65
	v_fmac_f32_e32 v183, v69, v69
	v_fmac_f32_e32 v180, v58, v58
	v_fmac_f32_e32 v181, v62, v62
	v_fmac_f32_e32 v182, v66, v66
	v_fmac_f32_e32 v183, v70, v70
	v_fmac_f32_e32 v180, v59, v59
	v_fmac_f32_e32 v181, v63, v63
	v_fmac_f32_e32 v182, v67, v67
	v_fmac_f32_e32 v183, v71, v71
	v_add_f32_e32 v180, v180, v181
	v_add_f32_e32 v182, v182, v183
	v_add_f32_e32 v180, v180, v182
	s_nop 1
	v_add_f32_dpp v180, v180, v180 quad_perm:[1,0,3,2] row_mask:0xf bank_mask:0xf
	s_nop 1
	v_add_f32_dpp v180, v180, v180 quad_perm:[2,3,0,1] row_mask:0xf bank_mask:0xf
	s_nop 1
	v_add_f32_dpp v180, v180, v180 row_half_mirror row_mask:0xf bank_mask:0xf
	s_nop 1
	v_add_f32_dpp v180, v180, v180 row_mirror row_mask:0xf bank_mask:0xf
	s_nop 1
	v_add_f32_dpp v180, v180, v180 row_bcast:15 row_mask:0xa bank_mask:0xf
	s_nop 1
	v_add_f32_dpp v180, v180, v180 row_bcast:31 row_mask:0xc bank_mask:0xf
	s_nop 0
	v_readlane_b32 s20, v180, 63
	s_nop 1
	v_mov_b32_e32 v185, s20
	v_fma_f32 v185, v185, v2, v4
	v_rsq_f32_e32 v185, v185
	s_nop 0
	v_mul_f32_e32 v56, v56, v185
	v_mul_f32_e32 v57, v57, v185
	v_mul_f32_e32 v58, v58, v185
	v_mul_f32_e32 v59, v59, v185
	v_mul_f32_e32 v60, v60, v185
	v_mul_f32_e32 v61, v61, v185
	v_mul_f32_e32 v62, v62, v185
	v_mul_f32_e32 v63, v63, v185
	v_mul_f32_e32 v64, v64, v185
	v_mul_f32_e32 v65, v65, v185
	v_mul_f32_e32 v66, v66, v185
	v_mul_f32_e32 v67, v67, v185
	v_mul_f32_e32 v68, v68, v185
	v_mul_f32_e32 v69, v69, v185
	v_mul_f32_e32 v70, v70, v185
	v_mul_f32_e32 v71, v71, v185
	v_fma_f32 v56, v56, v8, v24
	v_fma_f32 v57, v57, v9, v25
	v_fma_f32 v58, v58, v10, v26
	v_fma_f32 v59, v59, v11, v27
	v_fma_f32 v60, v60, v12, v28
	v_fma_f32 v61, v61, v13, v29
	v_fma_f32 v62, v62, v14, v30
	v_fma_f32 v63, v63, v15, v31
	v_fma_f32 v64, v64, v16, v32
	v_fma_f32 v65, v65, v17, v33
	v_fma_f32 v66, v66, v18, v34
	v_fma_f32 v67, v67, v19, v35
	v_fma_f32 v68, v68, v20, v36
	v_fma_f32 v69, v69, v21, v37
	v_fma_f32 v70, v70, v22, v38
	v_fma_f32 v71, v71, v23, v39
	v_add_u32_e32 v171, 0x1000, v1
	global_store_dwordx4 v171, v[56:59], s[4:5]
	global_store_dwordx4 v171, v[60:63], s[4:5] offset:1024
	global_store_dwordx4 v171, v[64:67], s[4:5] offset:2048
	global_store_dwordx4 v171, v[68:71], s[4:5] offset:3072
	s_waitcnt vmcnt(28)
	v_add_f32_e32 v180, v72, v73
	v_add_f32_e32 v181, v76, v77
	v_add_f32_e32 v182, v80, v81
	v_add_f32_e32 v183, v84, v85
	v_add_f32_e32 v180, v180, v74
	v_add_f32_e32 v181, v181, v78
	v_add_f32_e32 v182, v182, v82
	v_add_f32_e32 v183, v183, v86
	v_add_f32_e32 v180, v180, v75
	v_add_f32_e32 v181, v181, v79
	v_add_f32_e32 v182, v182, v83
	v_add_f32_e32 v183, v183, v87
	v_add_f32_e32 v180, v180, v181
	v_add_f32_e32 v182, v182, v183
	v_add_f32_e32 v180, v180, v182
	s_nop 1
	v_add_f32_dpp v180, v180, v180 quad_perm:[1,0,3,2] row_mask:0xf bank_mask:0xf
	s_nop 1
	v_add_f32_dpp v180, v180, v180 quad_perm:[2,3,0,1] row_mask:0xf bank_mask:0xf
	s_nop 1
	v_add_f32_dpp v180, v180, v180 row_half_mirror row_mask:0xf bank_mask:0xf
	s_nop 1
	v_add_f32_dpp v180, v180, v180 row_mirror row_mask:0xf bank_mask:0xf
	s_nop 1
	v_add_f32_dpp v180, v180, v180 row_bcast:15 row_mask:0xa bank_mask:0xf
	s_nop 1
	v_add_f32_dpp v180, v180, v180 row_bcast:31 row_mask:0xc bank_mask:0xf
	s_nop 0
	v_readlane_b32 s20, v180, 63
	s_nop 1
	v_mul_f32_e32 v184, s20, v2
	v_sub_f32_e32 v72, v72, v184
	v_sub_f32_e32 v73, v73, v184
	v_sub_f32_e32 v74, v74, v184
	v_sub_f32_e32 v75, v75, v184
	v_sub_f32_e32 v76, v76, v184
	v_sub_f32_e32 v77, v77, v184
	v_sub_f32_e32 v78, v78, v184
	v_sub_f32_e32 v79, v79, v184
	v_sub_f32_e32 v80, v80, v184
	v_sub_f32_e32 v81, v81, v184
	v_sub_f32_e32 v82, v82, v184
	v_sub_f32_e32 v83, v83, v184
	v_sub_f32_e32 v84, v84, v184
	v_sub_f32_e32 v85, v85, v184
	v_sub_f32_e32 v86, v86, v184
	v_sub_f32_e32 v87, v87, v184
	v_mul_f32_e32 v180, v72, v72
	v_mul_f32_e32 v181, v76, v76
	v_mul_f32_e32 v182, v80, v80
	v_mul_f32_e32 v183, v84, v84
	v_fmac_f32_e32 v180, v73, v73
	v_fmac_f32_e32 v181, v77, v77
	v_fmac_f32_e32 v182, v81, v81
	v_fmac_f32_e32 v183, v85, v85
	v_fmac_f32_e32 v180, v74, v74
	v_fmac_f32_e32 v181, v78, v78
	v_fmac_f32_e32 v182, v82, v82
	v_fmac_f32_e32 v183, v86, v86
	v_fmac_f32_e32 v180, v75, v75
	v_fmac_f32_e32 v181, v79, v79
	v_fmac_f32_e32 v182, v83, v83
	v_fmac_f32_e32 v183, v87, v87
	v_add_f32_e32 v180, v180, v181
	v_add_f32_e32 v182, v182, v183
	v_add_f32_e32 v180, v180, v182
	s_nop 1
	v_add_f32_dpp v180, v180, v180 quad_perm:[1,0,3,2] row_mask:0xf bank_mask:0xf
	s_nop 1
	v_add_f32_dpp v180, v180, v180 quad_perm:[2,3,0,1] row_mask:0xf bank_mask:0xf
	s_nop 1
	v_add_f32_dpp v180, v180, v180 row_half_mirror row_mask:0xf bank_mask:0xf
	s_nop 1
	v_add_f32_dpp v180, v180, v180 row_mirror row_mask:0xf bank_mask:0xf
	s_nop 1
	v_add_f32_dpp v180, v180, v180 row_bcast:15 row_mask:0xa bank_mask:0xf
	s_nop 1
	v_add_f32_dpp v180, v180, v180 row_bcast:31 row_mask:0xc bank_mask:0xf
	s_nop 0
	v_readlane_b32 s20, v180, 63
	s_nop 1
	v_mov_b32_e32 v185, s20
	v_fma_f32 v185, v185, v2, v4
	v_rsq_f32_e32 v185, v185
	s_nop 0
	v_mul_f32_e32 v72, v72, v185
	v_mul_f32_e32 v73, v73, v185
	v_mul_f32_e32 v74, v74, v185
	v_mul_f32_e32 v75, v75, v185
	v_mul_f32_e32 v76, v76, v185
	v_mul_f32_e32 v77, v77, v185
	v_mul_f32_e32 v78, v78, v185
	v_mul_f32_e32 v79, v79, v185
	v_mul_f32_e32 v80, v80, v185
	v_mul_f32_e32 v81, v81, v185
	v_mul_f32_e32 v82, v82, v185
	v_mul_f32_e32 v83, v83, v185
	v_mul_f32_e32 v84, v84, v185
	v_mul_f32_e32 v85, v85, v185
	v_mul_f32_e32 v86, v86, v185
	v_mul_f32_e32 v87, v87, v185
	v_fma_f32 v72, v72, v8, v24
	v_fma_f32 v73, v73, v9, v25
	v_fma_f32 v74, v74, v10, v26
	v_fma_f32 v75, v75, v11, v27
	v_fma_f32 v76, v76, v12, v28
	v_fma_f32 v77, v77, v13, v29
	v_fma_f32 v78, v78, v14, v30
	v_fma_f32 v79, v79, v15, v31
	v_fma_f32 v80, v80, v16, v32
	v_fma_f32 v81, v81, v17, v33
	v_fma_f32 v82, v82, v18, v34
	v_fma_f32 v83, v83, v19, v35
	v_fma_f32 v84, v84, v20, v36
	v_fma_f32 v85, v85, v21, v37
	v_fma_f32 v86, v86, v22, v38
	v_fma_f32 v87, v87, v23, v39
	v_add_u32_e32 v171, 0x2000, v1
	global_store_dwordx4 v171, v[72:75], s[4:5]
	global_store_dwordx4 v171, v[76:79], s[4:5] offset:1024
	global_store_dwordx4 v171, v[80:83], s[4:5] offset:2048
	global_store_dwordx4 v171, v[84:87], s[4:5] offset:3072
	s_waitcnt vmcnt(28)
	v_add_f32_e32 v180, v88, v89
	v_add_f32_e32 v181, v92, v93
	v_add_f32_e32 v182, v96, v97
	v_add_f32_e32 v183, v100, v101
	v_add_f32_e32 v180, v180, v90
	v_add_f32_e32 v181, v181, v94
	v_add_f32_e32 v182, v182, v98
	v_add_f32_e32 v183, v183, v102
	v_add_f32_e32 v180, v180, v91
	v_add_f32_e32 v181, v181, v95
	v_add_f32_e32 v182, v182, v99
	v_add_f32_e32 v183, v183, v103
	v_add_f32_e32 v180, v180, v181
	v_add_f32_e32 v182, v182, v183
	v_add_f32_e32 v180, v180, v182
	s_nop 1
	v_add_f32_dpp v180, v180, v180 quad_perm:[1,0,3,2] row_mask:0xf bank_mask:0xf
	s_nop 1
	v_add_f32_dpp v180, v180, v180 quad_perm:[2,3,0,1] row_mask:0xf bank_mask:0xf
	s_nop 1
	v_add_f32_dpp v180, v180, v180 row_half_mirror row_mask:0xf bank_mask:0xf
	s_nop 1
	v_add_f32_dpp v180, v180, v180 row_mirror row_mask:0xf bank_mask:0xf
	s_nop 1
	v_add_f32_dpp v180, v180, v180 row_bcast:15 row_mask:0xa bank_mask:0xf
	s_nop 1
	v_add_f32_dpp v180, v180, v180 row_bcast:31 row_mask:0xc bank_mask:0xf
	s_nop 0
	v_readlane_b32 s20, v180, 63
	s_nop 1
	v_mul_f32_e32 v184, s20, v2
	v_sub_f32_e32 v88, v88, v184
	v_sub_f32_e32 v89, v89, v184
	v_sub_f32_e32 v90, v90, v184
	v_sub_f32_e32 v91, v91, v184
	v_sub_f32_e32 v92, v92, v184
	v_sub_f32_e32 v93, v93, v184
	v_sub_f32_e32 v94, v94, v184
	v_sub_f32_e32 v95, v95, v184
	v_sub_f32_e32 v96, v96, v184
	v_sub_f32_e32 v97, v97, v184
	v_sub_f32_e32 v98, v98, v184
	v_sub_f32_e32 v99, v99, v184
	v_sub_f32_e32 v100, v100, v184
	v_sub_f32_e32 v101, v101, v184
	v_sub_f32_e32 v102, v102, v184
	v_sub_f32_e32 v103, v103, v184
	v_mul_f32_e32 v180, v88, v88
	v_mul_f32_e32 v181, v92, v92
	v_mul_f32_e32 v182, v96, v96
	v_mul_f32_e32 v183, v100, v100
	v_fmac_f32_e32 v180, v89, v89
	v_fmac_f32_e32 v181, v93, v93
	v_fmac_f32_e32 v182, v97, v97
	v_fmac_f32_e32 v183, v101, v101
	v_fmac_f32_e32 v180, v90, v90
	v_fmac_f32_e32 v181, v94, v94
	v_fmac_f32_e32 v182, v98, v98
	v_fmac_f32_e32 v183, v102, v102
	v_fmac_f32_e32 v180, v91, v91
	v_fmac_f32_e32 v181, v95, v95
	v_fmac_f32_e32 v182, v99, v99
	v_fmac_f32_e32 v183, v103, v103
	v_add_f32_e32 v180, v180, v181
	v_add_f32_e32 v182, v182, v183
	v_add_f32_e32 v180, v180, v182
	s_nop 1
	v_add_f32_dpp v180, v180, v180 quad_perm:[1,0,3,2] row_mask:0xf bank_mask:0xf
	s_nop 1
	v_add_f32_dpp v180, v180, v180 quad_perm:[2,3,0,1] row_mask:0xf bank_mask:0xf
	s_nop 1
	v_add_f32_dpp v180, v180, v180 row_half_mirror row_mask:0xf bank_mask:0xf
	s_nop 1
	v_add_f32_dpp v180, v180, v180 row_mirror row_mask:0xf bank_mask:0xf
	s_nop 1
	v_add_f32_dpp v180, v180, v180 row_bcast:15 row_mask:0xa bank_mask:0xf
	s_nop 1
	v_add_f32_dpp v180, v180, v180 row_bcast:31 row_mask:0xc bank_mask:0xf
	s_nop 0
	v_readlane_b32 s20, v180, 63
	s_nop 1
	v_mov_b32_e32 v185, s20
	v_fma_f32 v185, v185, v2, v4
	v_rsq_f32_e32 v185, v185
	s_nop 0
	v_mul_f32_e32 v88, v88, v185
	v_mul_f32_e32 v89, v89, v185
	v_mul_f32_e32 v90, v90, v185
	v_mul_f32_e32 v91, v91, v185
	v_mul_f32_e32 v92, v92, v185
	v_mul_f32_e32 v93, v93, v185
	v_mul_f32_e32 v94, v94, v185
	v_mul_f32_e32 v95, v95, v185
	v_mul_f32_e32 v96, v96, v185
	v_mul_f32_e32 v97, v97, v185
	v_mul_f32_e32 v98, v98, v185
	v_mul_f32_e32 v99, v99, v185
	v_mul_f32_e32 v100, v100, v185
	v_mul_f32_e32 v101, v101, v185
	v_mul_f32_e32 v102, v102, v185
	v_mul_f32_e32 v103, v103, v185
	v_fma_f32 v88, v88, v8, v24
	v_fma_f32 v89, v89, v9, v25
	v_fma_f32 v90, v90, v10, v26
	v_fma_f32 v91, v91, v11, v27
	v_fma_f32 v92, v92, v12, v28
	v_fma_f32 v93, v93, v13, v29
	v_fma_f32 v94, v94, v14, v30
	v_fma_f32 v95, v95, v15, v31
	v_fma_f32 v96, v96, v16, v32
	v_fma_f32 v97, v97, v17, v33
	v_fma_f32 v98, v98, v18, v34
	v_fma_f32 v99, v99, v19, v35
	v_fma_f32 v100, v100, v20, v36
	v_fma_f32 v101, v101, v21, v37
	v_fma_f32 v102, v102, v22, v38
	v_fma_f32 v103, v103, v23, v39
	v_add_u32_e32 v171, 0x3000, v1
	global_store_dwordx4 v171, v[88:91], s[4:5]
	global_store_dwordx4 v171, v[92:95], s[4:5] offset:1024
	global_store_dwordx4 v171, v[96:99], s[4:5] offset:2048
	global_store_dwordx4 v171, v[100:103], s[4:5] offset:3072
	s_waitcnt vmcnt(28)
	v_add_f32_e32 v180, v104, v105
	v_add_f32_e32 v181, v108, v109
	v_add_f32_e32 v182, v112, v113
	v_add_f32_e32 v183, v116, v117
	v_add_f32_e32 v180, v180, v106
	v_add_f32_e32 v181, v181, v110
	v_add_f32_e32 v182, v182, v114
	v_add_f32_e32 v183, v183, v118
	v_add_f32_e32 v180, v180, v107
	v_add_f32_e32 v181, v181, v111
	v_add_f32_e32 v182, v182, v115
	v_add_f32_e32 v183, v183, v119
	v_add_f32_e32 v180, v180, v181
	v_add_f32_e32 v182, v182, v183
	v_add_f32_e32 v180, v180, v182
	s_nop 1
	v_add_f32_dpp v180, v180, v180 quad_perm:[1,0,3,2] row_mask:0xf bank_mask:0xf
	s_nop 1
	v_add_f32_dpp v180, v180, v180 quad_perm:[2,3,0,1] row_mask:0xf bank_mask:0xf
	s_nop 1
	v_add_f32_dpp v180, v180, v180 row_half_mirror row_mask:0xf bank_mask:0xf
	s_nop 1
	v_add_f32_dpp v180, v180, v180 row_mirror row_mask:0xf bank_mask:0xf
	s_nop 1
	v_add_f32_dpp v180, v180, v180 row_bcast:15 row_mask:0xa bank_mask:0xf
	s_nop 1
	v_add_f32_dpp v180, v180, v180 row_bcast:31 row_mask:0xc bank_mask:0xf
	s_nop 0
	v_readlane_b32 s20, v180, 63
	s_nop 1
	v_mul_f32_e32 v184, s20, v2
	v_sub_f32_e32 v104, v104, v184
	v_sub_f32_e32 v105, v105, v184
	v_sub_f32_e32 v106, v106, v184
	v_sub_f32_e32 v107, v107, v184
	v_sub_f32_e32 v108, v108, v184
	v_sub_f32_e32 v109, v109, v184
	v_sub_f32_e32 v110, v110, v184
	v_sub_f32_e32 v111, v111, v184
	v_sub_f32_e32 v112, v112, v184
	v_sub_f32_e32 v113, v113, v184
	v_sub_f32_e32 v114, v114, v184
	v_sub_f32_e32 v115, v115, v184
	v_sub_f32_e32 v116, v116, v184
	v_sub_f32_e32 v117, v117, v184
	v_sub_f32_e32 v118, v118, v184
	v_sub_f32_e32 v119, v119, v184
	v_mul_f32_e32 v180, v104, v104
	v_mul_f32_e32 v181, v108, v108
	v_mul_f32_e32 v182, v112, v112
	v_mul_f32_e32 v183, v116, v116
	v_fmac_f32_e32 v180, v105, v105
	v_fmac_f32_e32 v181, v109, v109
	v_fmac_f32_e32 v182, v113, v113
	v_fmac_f32_e32 v183, v117, v117
	v_fmac_f32_e32 v180, v106, v106
	v_fmac_f32_e32 v181, v110, v110
	v_fmac_f32_e32 v182, v114, v114
	v_fmac_f32_e32 v183, v118, v118
	v_fmac_f32_e32 v180, v107, v107
	v_fmac_f32_e32 v181, v111, v111
	v_fmac_f32_e32 v182, v115, v115
	v_fmac_f32_e32 v183, v119, v119
	v_add_f32_e32 v180, v180, v181
	v_add_f32_e32 v182, v182, v183
	v_add_f32_e32 v180, v180, v182
	s_nop 1
	v_add_f32_dpp v180, v180, v180 quad_perm:[1,0,3,2] row_mask:0xf bank_mask:0xf
	s_nop 1
	v_add_f32_dpp v180, v180, v180 quad_perm:[2,3,0,1] row_mask:0xf bank_mask:0xf
	s_nop 1
	v_add_f32_dpp v180, v180, v180 row_half_mirror row_mask:0xf bank_mask:0xf
	s_nop 1
	v_add_f32_dpp v180, v180, v180 row_mirror row_mask:0xf bank_mask:0xf
	s_nop 1
	v_add_f32_dpp v180, v180, v180 row_bcast:15 row_mask:0xa bank_mask:0xf
	s_nop 1
	v_add_f32_dpp v180, v180, v180 row_bcast:31 row_mask:0xc bank_mask:0xf
	s_nop 0
	v_readlane_b32 s20, v180, 63
	s_nop 1
	v_mov_b32_e32 v185, s20
	v_fma_f32 v185, v185, v2, v4
	v_rsq_f32_e32 v185, v185
	s_nop 0
	v_mul_f32_e32 v104, v104, v185
	v_mul_f32_e32 v105, v105, v185
	v_mul_f32_e32 v106, v106, v185
	v_mul_f32_e32 v107, v107, v185
	v_mul_f32_e32 v108, v108, v185
	v_mul_f32_e32 v109, v109, v185
	v_mul_f32_e32 v110, v110, v185
	v_mul_f32_e32 v111, v111, v185
	v_mul_f32_e32 v112, v112, v185
	v_mul_f32_e32 v113, v113, v185
	v_mul_f32_e32 v114, v114, v185
	v_mul_f32_e32 v115, v115, v185
	v_mul_f32_e32 v116, v116, v185
	v_mul_f32_e32 v117, v117, v185
	v_mul_f32_e32 v118, v118, v185
	v_mul_f32_e32 v119, v119, v185
	v_fma_f32 v104, v104, v8, v24
	v_fma_f32 v105, v105, v9, v25
	v_fma_f32 v106, v106, v10, v26
	v_fma_f32 v107, v107, v11, v27
	v_fma_f32 v108, v108, v12, v28
	v_fma_f32 v109, v109, v13, v29
	v_fma_f32 v110, v110, v14, v30
	v_fma_f32 v111, v111, v15, v31
	v_fma_f32 v112, v112, v16, v32
	v_fma_f32 v113, v113, v17, v33
	v_fma_f32 v114, v114, v18, v34
	v_fma_f32 v115, v115, v19, v35
	v_fma_f32 v116, v116, v20, v36
	v_fma_f32 v117, v117, v21, v37
	v_fma_f32 v118, v118, v22, v38
	v_fma_f32 v119, v119, v23, v39
	v_add_u32_e32 v171, 0x4000, v1
	global_store_dwordx4 v171, v[104:107], s[4:5]
	global_store_dwordx4 v171, v[108:111], s[4:5] offset:1024
	global_store_dwordx4 v171, v[112:115], s[4:5] offset:2048
	global_store_dwordx4 v171, v[116:119], s[4:5] offset:3072
	s_waitcnt vmcnt(28)
	v_add_f32_e32 v180, v120, v121
	v_add_f32_e32 v181, v124, v125
	v_add_f32_e32 v182, v128, v129
	v_add_f32_e32 v183, v132, v133
	v_add_f32_e32 v180, v180, v122
	v_add_f32_e32 v181, v181, v126
	v_add_f32_e32 v182, v182, v130
	v_add_f32_e32 v183, v183, v134
	v_add_f32_e32 v180, v180, v123
	v_add_f32_e32 v181, v181, v127
	v_add_f32_e32 v182, v182, v131
	v_add_f32_e32 v183, v183, v135
	v_add_f32_e32 v180, v180, v181
	v_add_f32_e32 v182, v182, v183
	v_add_f32_e32 v180, v180, v182
	s_nop 1
	v_add_f32_dpp v180, v180, v180 quad_perm:[1,0,3,2] row_mask:0xf bank_mask:0xf
	s_nop 1
	v_add_f32_dpp v180, v180, v180 quad_perm:[2,3,0,1] row_mask:0xf bank_mask:0xf
	s_nop 1
	v_add_f32_dpp v180, v180, v180 row_half_mirror row_mask:0xf bank_mask:0xf
	s_nop 1
	v_add_f32_dpp v180, v180, v180 row_mirror row_mask:0xf bank_mask:0xf
	s_nop 1
	v_add_f32_dpp v180, v180, v180 row_bcast:15 row_mask:0xa bank_mask:0xf
	s_nop 1
	v_add_f32_dpp v180, v180, v180 row_bcast:31 row_mask:0xc bank_mask:0xf
	s_nop 0
	v_readlane_b32 s20, v180, 63
	s_nop 1
	v_mul_f32_e32 v184, s20, v2
	v_sub_f32_e32 v120, v120, v184
	v_sub_f32_e32 v121, v121, v184
	v_sub_f32_e32 v122, v122, v184
	v_sub_f32_e32 v123, v123, v184
	v_sub_f32_e32 v124, v124, v184
	v_sub_f32_e32 v125, v125, v184
	v_sub_f32_e32 v126, v126, v184
	v_sub_f32_e32 v127, v127, v184
	v_sub_f32_e32 v128, v128, v184
	v_sub_f32_e32 v129, v129, v184
	v_sub_f32_e32 v130, v130, v184
	v_sub_f32_e32 v131, v131, v184
	v_sub_f32_e32 v132, v132, v184
	v_sub_f32_e32 v133, v133, v184
	v_sub_f32_e32 v134, v134, v184
	v_sub_f32_e32 v135, v135, v184
	v_mul_f32_e32 v180, v120, v120
	v_mul_f32_e32 v181, v124, v124
	v_mul_f32_e32 v182, v128, v128
	v_mul_f32_e32 v183, v132, v132
	v_fmac_f32_e32 v180, v121, v121
	v_fmac_f32_e32 v181, v125, v125
	v_fmac_f32_e32 v182, v129, v129
	v_fmac_f32_e32 v183, v133, v133
	v_fmac_f32_e32 v180, v122, v122
	v_fmac_f32_e32 v181, v126, v126
	v_fmac_f32_e32 v182, v130, v130
	v_fmac_f32_e32 v183, v134, v134
	v_fmac_f32_e32 v180, v123, v123
	v_fmac_f32_e32 v181, v127, v127
	v_fmac_f32_e32 v182, v131, v131
	v_fmac_f32_e32 v183, v135, v135
	v_add_f32_e32 v180, v180, v181
	v_add_f32_e32 v182, v182, v183
	v_add_f32_e32 v180, v180, v182
	s_nop 1
	v_add_f32_dpp v180, v180, v180 quad_perm:[1,0,3,2] row_mask:0xf bank_mask:0xf
	s_nop 1
	v_add_f32_dpp v180, v180, v180 quad_perm:[2,3,0,1] row_mask:0xf bank_mask:0xf
	s_nop 1
	v_add_f32_dpp v180, v180, v180 row_half_mirror row_mask:0xf bank_mask:0xf
	s_nop 1
	v_add_f32_dpp v180, v180, v180 row_mirror row_mask:0xf bank_mask:0xf
	s_nop 1
	v_add_f32_dpp v180, v180, v180 row_bcast:15 row_mask:0xa bank_mask:0xf
	s_nop 1
	v_add_f32_dpp v180, v180, v180 row_bcast:31 row_mask:0xc bank_mask:0xf
	s_nop 0
	v_readlane_b32 s20, v180, 63
	s_nop 1
	v_mov_b32_e32 v185, s20
	v_fma_f32 v185, v185, v2, v4
	v_rsq_f32_e32 v185, v185
	s_nop 0
	v_mul_f32_e32 v120, v120, v185
	v_mul_f32_e32 v121, v121, v185
	v_mul_f32_e32 v122, v122, v185
	v_mul_f32_e32 v123, v123, v185
	v_mul_f32_e32 v124, v124, v185
	v_mul_f32_e32 v125, v125, v185
	v_mul_f32_e32 v126, v126, v185
	v_mul_f32_e32 v127, v127, v185
	v_mul_f32_e32 v128, v128, v185
	v_mul_f32_e32 v129, v129, v185
	v_mul_f32_e32 v130, v130, v185
	v_mul_f32_e32 v131, v131, v185
	v_mul_f32_e32 v132, v132, v185
	v_mul_f32_e32 v133, v133, v185
	v_mul_f32_e32 v134, v134, v185
	v_mul_f32_e32 v135, v135, v185
	v_fma_f32 v120, v120, v8, v24
	v_fma_f32 v121, v121, v9, v25
	v_fma_f32 v122, v122, v10, v26
	v_fma_f32 v123, v123, v11, v27
	v_fma_f32 v124, v124, v12, v28
	v_fma_f32 v125, v125, v13, v29
	v_fma_f32 v126, v126, v14, v30
	v_fma_f32 v127, v127, v15, v31
	v_fma_f32 v128, v128, v16, v32
	v_fma_f32 v129, v129, v17, v33
	v_fma_f32 v130, v130, v18, v34
	v_fma_f32 v131, v131, v19, v35
	v_fma_f32 v132, v132, v20, v36
	v_fma_f32 v133, v133, v21, v37
	v_fma_f32 v134, v134, v22, v38
	v_fma_f32 v135, v135, v23, v39
	v_add_u32_e32 v171, 0x5000, v1
	global_store_dwordx4 v171, v[120:123], s[4:5]
	global_store_dwordx4 v171, v[124:127], s[4:5] offset:1024
	global_store_dwordx4 v171, v[128:131], s[4:5] offset:2048
	global_store_dwordx4 v171, v[132:135], s[4:5] offset:3072
	s_waitcnt vmcnt(28)
	v_add_f32_e32 v180, v136, v137
	v_add_f32_e32 v181, v140, v141
	v_add_f32_e32 v182, v144, v145
	v_add_f32_e32 v183, v148, v149
	v_add_f32_e32 v180, v180, v138
	v_add_f32_e32 v181, v181, v142
	v_add_f32_e32 v182, v182, v146
	v_add_f32_e32 v183, v183, v150
	v_add_f32_e32 v180, v180, v139
	v_add_f32_e32 v181, v181, v143
	v_add_f32_e32 v182, v182, v147
	v_add_f32_e32 v183, v183, v151
	v_add_f32_e32 v180, v180, v181
	v_add_f32_e32 v182, v182, v183
	v_add_f32_e32 v180, v180, v182
	s_nop 1
	v_add_f32_dpp v180, v180, v180 quad_perm:[1,0,3,2] row_mask:0xf bank_mask:0xf
	s_nop 1
	v_add_f32_dpp v180, v180, v180 quad_perm:[2,3,0,1] row_mask:0xf bank_mask:0xf
	s_nop 1
	v_add_f32_dpp v180, v180, v180 row_half_mirror row_mask:0xf bank_mask:0xf
	s_nop 1
	v_add_f32_dpp v180, v180, v180 row_mirror row_mask:0xf bank_mask:0xf
	s_nop 1
	v_add_f32_dpp v180, v180, v180 row_bcast:15 row_mask:0xa bank_mask:0xf
	s_nop 1
	v_add_f32_dpp v180, v180, v180 row_bcast:31 row_mask:0xc bank_mask:0xf
	s_nop 0
	v_readlane_b32 s20, v180, 63
	s_nop 1
	v_mul_f32_e32 v184, s20, v2
	v_sub_f32_e32 v136, v136, v184
	v_sub_f32_e32 v137, v137, v184
	v_sub_f32_e32 v138, v138, v184
	v_sub_f32_e32 v139, v139, v184
	v_sub_f32_e32 v140, v140, v184
	v_sub_f32_e32 v141, v141, v184
	v_sub_f32_e32 v142, v142, v184
	v_sub_f32_e32 v143, v143, v184
	v_sub_f32_e32 v144, v144, v184
	v_sub_f32_e32 v145, v145, v184
	v_sub_f32_e32 v146, v146, v184
	v_sub_f32_e32 v147, v147, v184
	v_sub_f32_e32 v148, v148, v184
	v_sub_f32_e32 v149, v149, v184
	v_sub_f32_e32 v150, v150, v184
	v_sub_f32_e32 v151, v151, v184
	v_mul_f32_e32 v180, v136, v136
	v_mul_f32_e32 v181, v140, v140
	v_mul_f32_e32 v182, v144, v144
	v_mul_f32_e32 v183, v148, v148
	v_fmac_f32_e32 v180, v137, v137
	v_fmac_f32_e32 v181, v141, v141
	v_fmac_f32_e32 v182, v145, v145
	v_fmac_f32_e32 v183, v149, v149
	v_fmac_f32_e32 v180, v138, v138
	v_fmac_f32_e32 v181, v142, v142
	v_fmac_f32_e32 v182, v146, v146
	v_fmac_f32_e32 v183, v150, v150
	v_fmac_f32_e32 v180, v139, v139
	v_fmac_f32_e32 v181, v143, v143
	v_fmac_f32_e32 v182, v147, v147
	v_fmac_f32_e32 v183, v151, v151
	v_add_f32_e32 v180, v180, v181
	v_add_f32_e32 v182, v182, v183
	v_add_f32_e32 v180, v180, v182
	s_nop 1
	v_add_f32_dpp v180, v180, v180 quad_perm:[1,0,3,2] row_mask:0xf bank_mask:0xf
	s_nop 1
	v_add_f32_dpp v180, v180, v180 quad_perm:[2,3,0,1] row_mask:0xf bank_mask:0xf
	s_nop 1
	v_add_f32_dpp v180, v180, v180 row_half_mirror row_mask:0xf bank_mask:0xf
	s_nop 1
	v_add_f32_dpp v180, v180, v180 row_mirror row_mask:0xf bank_mask:0xf
	s_nop 1
	v_add_f32_dpp v180, v180, v180 row_bcast:15 row_mask:0xa bank_mask:0xf
	s_nop 1
	v_add_f32_dpp v180, v180, v180 row_bcast:31 row_mask:0xc bank_mask:0xf
	s_nop 0
	v_readlane_b32 s20, v180, 63
	s_nop 1
	v_mov_b32_e32 v185, s20
	v_fma_f32 v185, v185, v2, v4
	v_rsq_f32_e32 v185, v185
	s_nop 0
	v_mul_f32_e32 v136, v136, v185
	v_mul_f32_e32 v137, v137, v185
	v_mul_f32_e32 v138, v138, v185
	v_mul_f32_e32 v139, v139, v185
	v_mul_f32_e32 v140, v140, v185
	v_mul_f32_e32 v141, v141, v185
	v_mul_f32_e32 v142, v142, v185
	v_mul_f32_e32 v143, v143, v185
	v_mul_f32_e32 v144, v144, v185
	v_mul_f32_e32 v145, v145, v185
	v_mul_f32_e32 v146, v146, v185
	v_mul_f32_e32 v147, v147, v185
	v_mul_f32_e32 v148, v148, v185
	v_mul_f32_e32 v149, v149, v185
	v_mul_f32_e32 v150, v150, v185
	v_mul_f32_e32 v151, v151, v185
	v_fma_f32 v136, v136, v8, v24
	v_fma_f32 v137, v137, v9, v25
	v_fma_f32 v138, v138, v10, v26
	v_fma_f32 v139, v139, v11, v27
	v_fma_f32 v140, v140, v12, v28
	v_fma_f32 v141, v141, v13, v29
	v_fma_f32 v142, v142, v14, v30
	v_fma_f32 v143, v143, v15, v31
	v_fma_f32 v144, v144, v16, v32
	v_fma_f32 v145, v145, v17, v33
	v_fma_f32 v146, v146, v18, v34
	v_fma_f32 v147, v147, v19, v35
	v_fma_f32 v148, v148, v20, v36
	v_fma_f32 v149, v149, v21, v37
	v_fma_f32 v150, v150, v22, v38
	v_fma_f32 v151, v151, v23, v39
	v_add_u32_e32 v171, 0x6000, v1
	global_store_dwordx4 v171, v[136:139], s[4:5]
	global_store_dwordx4 v171, v[140:143], s[4:5] offset:1024
	global_store_dwordx4 v171, v[144:147], s[4:5] offset:2048
	global_store_dwordx4 v171, v[148:151], s[4:5] offset:3072
	s_waitcnt vmcnt(28)
	v_add_f32_e32 v180, v152, v153
	v_add_f32_e32 v181, v156, v157
	v_add_f32_e32 v182, v160, v161
	v_add_f32_e32 v183, v164, v165
	v_add_f32_e32 v180, v180, v154
	v_add_f32_e32 v181, v181, v158
	v_add_f32_e32 v182, v182, v162
	v_add_f32_e32 v183, v183, v166
	v_add_f32_e32 v180, v180, v155
	v_add_f32_e32 v181, v181, v159
	v_add_f32_e32 v182, v182, v163
	v_add_f32_e32 v183, v183, v167
	v_add_f32_e32 v180, v180, v181
	v_add_f32_e32 v182, v182, v183
	v_add_f32_e32 v180, v180, v182
	s_nop 1
	v_add_f32_dpp v180, v180, v180 quad_perm:[1,0,3,2] row_mask:0xf bank_mask:0xf
	s_nop 1
	v_add_f32_dpp v180, v180, v180 quad_perm:[2,3,0,1] row_mask:0xf bank_mask:0xf
	s_nop 1
	v_add_f32_dpp v180, v180, v180 row_half_mirror row_mask:0xf bank_mask:0xf
	s_nop 1
	v_add_f32_dpp v180, v180, v180 row_mirror row_mask:0xf bank_mask:0xf
	s_nop 1
	v_add_f32_dpp v180, v180, v180 row_bcast:15 row_mask:0xa bank_mask:0xf
	s_nop 1
	v_add_f32_dpp v180, v180, v180 row_bcast:31 row_mask:0xc bank_mask:0xf
	s_nop 0
	v_readlane_b32 s20, v180, 63
	s_nop 1
	v_mul_f32_e32 v184, s20, v2
	v_sub_f32_e32 v152, v152, v184
	v_sub_f32_e32 v153, v153, v184
	v_sub_f32_e32 v154, v154, v184
	v_sub_f32_e32 v155, v155, v184
	v_sub_f32_e32 v156, v156, v184
	v_sub_f32_e32 v157, v157, v184
	v_sub_f32_e32 v158, v158, v184
	v_sub_f32_e32 v159, v159, v184
	v_sub_f32_e32 v160, v160, v184
	v_sub_f32_e32 v161, v161, v184
	v_sub_f32_e32 v162, v162, v184
	v_sub_f32_e32 v163, v163, v184
	v_sub_f32_e32 v164, v164, v184
	v_sub_f32_e32 v165, v165, v184
	v_sub_f32_e32 v166, v166, v184
	v_sub_f32_e32 v167, v167, v184
	v_mul_f32_e32 v180, v152, v152
	v_mul_f32_e32 v181, v156, v156
	v_mul_f32_e32 v182, v160, v160
	v_mul_f32_e32 v183, v164, v164
	v_fmac_f32_e32 v180, v153, v153
	v_fmac_f32_e32 v181, v157, v157
	v_fmac_f32_e32 v182, v161, v161
	v_fmac_f32_e32 v183, v165, v165
	v_fmac_f32_e32 v180, v154, v154
	v_fmac_f32_e32 v181, v158, v158
	v_fmac_f32_e32 v182, v162, v162
	v_fmac_f32_e32 v183, v166, v166
	v_fmac_f32_e32 v180, v155, v155
	v_fmac_f32_e32 v181, v159, v159
	v_fmac_f32_e32 v182, v163, v163
	v_fmac_f32_e32 v183, v167, v167
	v_add_f32_e32 v180, v180, v181
	v_add_f32_e32 v182, v182, v183
	v_add_f32_e32 v180, v180, v182
	s_nop 1
	v_add_f32_dpp v180, v180, v180 quad_perm:[1,0,3,2] row_mask:0xf bank_mask:0xf
	s_nop 1
	v_add_f32_dpp v180, v180, v180 quad_perm:[2,3,0,1] row_mask:0xf bank_mask:0xf
	s_nop 1
	v_add_f32_dpp v180, v180, v180 row_half_mirror row_mask:0xf bank_mask:0xf
	s_nop 1
	v_add_f32_dpp v180, v180, v180 row_mirror row_mask:0xf bank_mask:0xf
	s_nop 1
	v_add_f32_dpp v180, v180, v180 row_bcast:15 row_mask:0xa bank_mask:0xf
	s_nop 1
	v_add_f32_dpp v180, v180, v180 row_bcast:31 row_mask:0xc bank_mask:0xf
	s_nop 0
	v_readlane_b32 s20, v180, 63
	s_nop 1
	v_mov_b32_e32 v185, s20
	v_fma_f32 v185, v185, v2, v4
	v_rsq_f32_e32 v185, v185
	s_nop 0
	v_mul_f32_e32 v152, v152, v185
	v_mul_f32_e32 v153, v153, v185
	v_mul_f32_e32 v154, v154, v185
	v_mul_f32_e32 v155, v155, v185
	v_mul_f32_e32 v156, v156, v185
	v_mul_f32_e32 v157, v157, v185
	v_mul_f32_e32 v158, v158, v185
	v_mul_f32_e32 v159, v159, v185
	v_mul_f32_e32 v160, v160, v185
	v_mul_f32_e32 v161, v161, v185
	v_mul_f32_e32 v162, v162, v185
	v_mul_f32_e32 v163, v163, v185
	v_mul_f32_e32 v164, v164, v185
	v_mul_f32_e32 v165, v165, v185
	v_mul_f32_e32 v166, v166, v185
	v_mul_f32_e32 v167, v167, v185
	v_fma_f32 v152, v152, v8, v24
	v_fma_f32 v153, v153, v9, v25
	v_fma_f32 v154, v154, v10, v26
	v_fma_f32 v155, v155, v11, v27
	v_fma_f32 v156, v156, v12, v28
	v_fma_f32 v157, v157, v13, v29
	v_fma_f32 v158, v158, v14, v30
	v_fma_f32 v159, v159, v15, v31
	v_fma_f32 v160, v160, v16, v32
	v_fma_f32 v161, v161, v17, v33
	v_fma_f32 v162, v162, v18, v34
	v_fma_f32 v163, v163, v19, v35
	v_fma_f32 v164, v164, v20, v36
	v_fma_f32 v165, v165, v21, v37
	v_fma_f32 v166, v166, v22, v38
	v_fma_f32 v167, v167, v23, v39
	v_add_u32_e32 v171, 0x7000, v1
	global_store_dwordx4 v171, v[152:155], s[4:5]
	global_store_dwordx4 v171, v[156:159], s[4:5] offset:1024
	global_store_dwordx4 v171, v[160:163], s[4:5] offset:2048
	global_store_dwordx4 v171, v[164:167], s[4:5] offset:3072
	s_branch .Ltr_29
